# code placement: FFN-in K-loop head shifted by 8 dwords (probe: -30us on that phase); aligned MFMA groups; without the single-LDS-base-register step
# speedup vs baseline: 1.0067x; 1.0022x over previous
; #define PG8_STAGE(bufoff, gbase, voff) do { _Pragma("unroll") for (int _i = 0; _i < 2; ++_i) \
;         __builtin_amdgcn_global_load_lds((const unsigned*)((const char*)(gbase) + (voff)[_i]), (PG8_LAS unsigned*)(lds + (bufoff) + ldsw + _i * 8192), 16, 0, 0); } while (0)
; #define PG8_LDA(dst, b, h) do { _Pragma("unroll") for (int m = 0; m < 4; ++m) _Pragma("unroll") for (int k = 0; k < 2; ++k) dst[m][k] = *(const PG8_LAS bf16x8*)(lds + PG8_SA(b, h) + aoff + m * 2048 + k * 1024); } while (0)
; #define PG8_LDB(dst, b, h) do { _Pragma("unroll") for (int n = 0; n < 2; ++n) _Pragma("unroll") for (int k = 0; k < 2; ++k) dst[n][k] = *(const PG8_LAS bf16x8*)(lds + PG8_SB(b, h) + boff + n * 2048 + k * 1024); } while (0)
; #define PG8_WAIT_V(n) asm volatile("s_waitcnt vmcnt(" #n ")" ::: "memory")
; #define PG8_WAIT_L(n) asm volatile("s_waitcnt lgkmcnt(" #n ")" ::: "memory")
; #define PG8_BAR __builtin_amdgcn_s_barrier()
; #define PG8_SCHED __builtin_amdgcn_sched_barrier(0)
; template <class Epi, class Sched, bool ALIGN_EPI = false, bool SP2 = false>
; __device__ __forceinline__ void gemm_phase(PG8_LAS unsigned char* lds, const Gemm g, const Sched& S, const Epi& E, int wave_s) {
;     ...
;         const bool has_next = S.next(ui + 1, nxt);
;         const char* nA = has_next ? (const char*)g.A + (size_t)nxt.pm * tstepA : cA; const char* nB = has_next ? (const char*)g.Bt + (size_t)nxt.pn * tstepB : cB;
;         for (int t = 0; t < nt; t += 2) {
;             const bool last = (t == nt - 2);
;             const char* a1 = cA + (size_t)(t + 1) * kstep;
;             const char* a2 = last ? nA : cA + (size_t)(t + 2) * kstep; const char* b2 = last ? nB : cB + (size_t)(t + 2) * kstep;
;             const char* a3 = a2 + kstep; const char* b3 = b2 + kstep;
;             if (last && has_next) S.a_ready(nxt);
;             if constexpr (SP2) {
;             PG8_LDB(B0, 0, 0); PG8_LDB(B1, 0, 1); PG8_SCHED; PG8_LDA(At, 0, 0); PG8_STAGE(PG8_SA(1, 1), a1 + hstepA, voffA);
;             PG8_WAIT_V(8); PG8_WAIT_L(0); PG8_BAR; PG8_MMA(0, 0, At, B0); PG8_MMA(0, 1, At, B1); PG8_BAR; PG8_SCHED;
;     ...
;         for (int a = 0; a < 2; ++a)
; #pragma unroll
;             for (int b = 0; b < 2; ++b)
; #pragma unroll
;                 for (int m = 0; m < 4; ++m)
; #pragma unroll
;                     for (int n = 0; n < 2; ++n) acc[a][b][m][n] = (f32x4){0.f, 0.f, 0.f, 0.f};
.LBB0_191:
	s_ashr_i32 s23, s22, 31
	s_lshl_b64 s[24:25], s[22:23], 20
	s_add_u32 s24, s2, s24
	s_addc_u32 s25, s30, s25
	s_and_b64 s[36:37], s[34:35], exec
	s_cselect_b32 s23, s25, s27
	s_cselect_b32 s39, s24, s26
	s_ashr_i32 s21, s20, 31
	s_lshl_b64 s[36:37], s[20:21], 20
	s_add_u32 s40, s42, s36
	s_addc_u32 s41, s43, s37
	s_and_b64 s[36:37], s[34:35], exec
	s_cselect_b32 s21, s41, s19
	s_cselect_b32 s52, s40, s18
	s_add_u32 s53, s18, 0x100
	s_addc_u32 s54, s19, 0
	s_add_u32 s18, s26, 0x80080
	s_addc_u32 s19, s27, 0
	s_mov_b32 s55, -2
	s_waitcnt vmcnt(0) lgkmcnt(0)
	v_mov_b64_e32 v[4:5], 0
	v_mov_b64_e32 v[6:7], 0
	v_mov_b64_e32 v[8:9], 0
	v_mov_b64_e32 v[10:11], 0
	v_mov_b64_e32 v[12:13], 0
	v_mov_b64_e32 v[14:15], 0
	v_mov_b64_e32 v[16:17], 0
	v_mov_b64_e32 v[18:19], 0
	v_mov_b64_e32 v[20:21], 0
	v_mov_b64_e32 v[22:23], 0
	v_mov_b64_e32 v[24:25], 0
	v_mov_b64_e32 v[26:27], 0
	v_mov_b64_e32 v[28:29], 0
	v_mov_b64_e32 v[30:31], 0
	v_mov_b64_e32 v[32:33], 0
	v_mov_b64_e32 v[34:35], 0
	v_mov_b64_e32 v[36:37], 0
	v_mov_b64_e32 v[38:39], 0
	v_mov_b64_e32 v[40:41], 0
	v_mov_b64_e32 v[42:43], 0
	v_mov_b64_e32 v[44:45], 0
	v_mov_b64_e32 v[46:47], 0
	v_mov_b64_e32 v[48:49], 0
	v_mov_b64_e32 v[50:51], 0
	v_mov_b64_e32 v[52:53], 0
	v_mov_b64_e32 v[54:55], 0
	v_mov_b64_e32 v[56:57], 0
	v_mov_b64_e32 v[58:59], 0
	v_mov_b64_e32 v[60:61], 0
	v_mov_b64_e32 v[62:63], 0
	v_mov_b64_e32 v[64:65], 0
	v_mov_b64_e32 v[66:67], 0
	v_mov_b64_e32 v[68:69], 0
	v_mov_b64_e32 v[70:71], 0
	v_mov_b64_e32 v[72:73], 0
	v_mov_b64_e32 v[74:75], 0
	v_mov_b64_e32 v[76:77], 0
	v_mov_b64_e32 v[78:79], 0
	v_mov_b64_e32 v[80:81], 0
	v_mov_b64_e32 v[82:83], 0
	v_mov_b64_e32 v[84:85], 0
	v_mov_b64_e32 v[86:87], 0
	v_mov_b64_e32 v[88:89], 0
	v_mov_b64_e32 v[90:91], 0
	v_mov_b64_e32 v[92:93], 0
	v_mov_b64_e32 v[94:95], 0
	v_mov_b64_e32 v[96:97], 0
	v_mov_b64_e32 v[98:99], 0
	v_mov_b64_e32 v[100:101], 0
	v_mov_b64_e32 v[102:103], 0
	v_mov_b64_e32 v[104:105], 0
	v_mov_b64_e32 v[106:107], 0
	v_mov_b64_e32 v[108:109], 0
	v_mov_b64_e32 v[110:111], 0
	v_mov_b64_e32 v[112:113], 0
	v_mov_b64_e32 v[114:115], 0
	v_mov_b64_e32 v[116:117], 0
	v_mov_b64_e32 v[118:119], 0
	v_mov_b64_e32 v[120:121], 0
	v_mov_b64_e32 v[122:123], 0
	v_mov_b64_e32 v[124:125], 0
	v_mov_b64_e32 v[126:127], 0
	v_mov_b64_e32 v[128:129], 0
	v_mov_b64_e32 v[130:131], 0
.LBB0_192:
	s_add_u32 s26, s18, 0xfff80080
	s_addc_u32 s27, s19, -1
	s_add_i32 s56, 0, 0x10000
	s_cmp_eq_u32 s55, 28
	s_cselect_b32 s37, s23, s27
	s_cselect_b32 s36, s39, s26
	v_add_u32_e32 v146, s56, v149
	s_cselect_b32 s27, s21, s54
	s_cselect_b32 s26, s52, s53
	s_add_i32 s58, 0, 0x14000
	ds_read_b128 v[142:145], v146
	ds_read_b128 v[152:155], v146 offset:1024
	ds_read_b128 v[156:159], v146 offset:2048
	ds_read_b128 v[160:163], v146 offset:3072
	v_add_u32_e32 v146, s58, v149
	ds_read_b128 v[164:167], v146
	ds_read_b128 v[182:185], v146 offset:1024
	ds_read_b128 v[186:189], v146 offset:2048
	ds_read_b128 v[190:193], v146 offset:3072
	s_add_i32 m0, s45, 0xc000
	ds_read_b128 v[194:197], v151
	ds_read_b128 v[198:201], v151 offset:1024
	ds_read_b128 v[212:215], v151 offset:2048
	ds_read_b128 v[216:219], v151 offset:3072
	ds_read_b128 v[220:223], v151 offset:4096
	ds_read_b128 v[224:227], v151 offset:5120
	ds_read_b128 v[228:231], v151 offset:6144
	ds_read_b128 v[232:235], v151 offset:7168
	global_load_lds_dwordx4 v140, s[18:19]
	s_add_i32 m0, s45, 0xe000
	s_nop 0
	global_load_lds_dwordx4 v138, s[18:19]
	s_waitcnt vmcnt(8)
	s_waitcnt lgkmcnt(0)
	s_barrier
	s_setprio 1
	s_waitcnt lgkmcnt(0)
	v_mfma_f32_16x16x32_bf16 v[72:75], v[142:145], v[194:197], v[72:75]
	v_mfma_f32_16x16x32_bf16 v[68:71], v[156:159], v[194:197], v[68:71]
	v_mfma_f32_16x16x32_bf16 v[64:67], v[142:145], v[212:215], v[64:67]
	v_mfma_f32_16x16x32_bf16 v[60:63], v[156:159], v[212:215], v[60:63]
	v_mfma_f32_16x16x32_bf16 v[56:59], v[142:145], v[220:223], v[56:59]
	v_mfma_f32_16x16x32_bf16 v[52:55], v[156:159], v[220:223], v[52:55]
	v_mfma_f32_16x16x32_bf16 v[48:51], v[142:145], v[228:231], v[48:51]
	v_mfma_f32_16x16x32_bf16 v[44:47], v[156:159], v[228:231], v[44:47]
	v_mfma_f32_16x16x32_bf16 v[72:75], v[152:155], v[198:201], v[72:75]
	v_mfma_f32_16x16x32_bf16 v[68:71], v[160:163], v[198:201], v[68:71]
	v_mfma_f32_16x16x32_bf16 v[64:67], v[152:155], v[216:219], v[64:67]
	v_mfma_f32_16x16x32_bf16 v[60:63], v[160:163], v[216:219], v[60:63]
	v_mfma_f32_16x16x32_bf16 v[56:59], v[152:155], v[224:227], v[56:59]
	v_mfma_f32_16x16x32_bf16 v[52:55], v[160:163], v[224:227], v[52:55]
	v_mfma_f32_16x16x32_bf16 v[48:51], v[152:155], v[232:235], v[48:51]
	v_mfma_f32_16x16x32_bf16 v[44:47], v[160:163], v[232:235], v[44:47]
	s_setprio 0
	s_setprio 1
	v_mfma_f32_16x16x32_bf16 v[128:131], v[164:167], v[194:197], v[128:131]
	v_mfma_f32_16x16x32_bf16 v[124:127], v[186:189], v[194:197], v[124:127]
	v_mfma_f32_16x16x32_bf16 v[120:123], v[164:167], v[212:215], v[120:123]
	v_mfma_f32_16x16x32_bf16 v[116:119], v[186:189], v[212:215], v[116:119]
	v_mfma_f32_16x16x32_bf16 v[112:115], v[164:167], v[220:223], v[112:115]
	v_mfma_f32_16x16x32_bf16 v[108:111], v[186:189], v[220:223], v[108:111]
	v_mfma_f32_16x16x32_bf16 v[104:107], v[164:167], v[228:231], v[104:107]
	v_mfma_f32_16x16x32_bf16 v[100:103], v[186:189], v[228:231], v[100:103]
	v_mfma_f32_16x16x32_bf16 v[128:131], v[182:185], v[198:201], v[128:131]
	v_mfma_f32_16x16x32_bf16 v[124:127], v[190:193], v[198:201], v[124:127]
	v_mfma_f32_16x16x32_bf16 v[120:123], v[182:185], v[216:219], v[120:123]
	v_mfma_f32_16x16x32_bf16 v[116:119], v[190:193], v[216:219], v[116:119]
	v_mfma_f32_16x16x32_bf16 v[112:115], v[182:185], v[224:227], v[112:115]
	v_mfma_f32_16x16x32_bf16 v[108:111], v[190:193], v[224:227], v[108:111]
	v_mfma_f32_16x16x32_bf16 v[104:107], v[182:185], v[232:235], v[104:107]
	v_mfma_f32_16x16x32_bf16 v[100:103], v[190:193], v[232:235], v[100:103]
	s_setprio 0
	s_barrier
; #define PG8_STAGE(bufoff, gbase, voff) do { _Pragma("unroll") for (int _i = 0; _i < 2; ++_i) \
;         __builtin_amdgcn_global_load_lds((const unsigned*)((const char*)(gbase) + (voff)[_i]), (PG8_LAS unsigned*)(lds + (bufoff) + ldsw + _i * 8192), 16, 0, 0); } while (0)
; #define PG8_LDA(dst, b, h) do { _Pragma("unroll") for (int m = 0; m < 4; ++m) _Pragma("unroll") for (int k = 0; k < 2; ++k) dst[m][k] = *(const PG8_LAS bf16x8*)(lds + PG8_SA(b, h) + aoff + m * 2048 + k * 1024); } while (0)
; #define PG8_LDB(dst, b, h) do { _Pragma("unroll") for (int n = 0; n < 2; ++n) _Pragma("unroll") for (int k = 0; k < 2; ++k) dst[n][k] = *(const PG8_LAS bf16x8*)(lds + PG8_SB(b, h) + boff + n * 2048 + k * 1024); } while (0)
; #define PG8_MMA(ai, bj, At, Bt) do { __builtin_amdgcn_s_setprio(1); _Pragma("unroll") for (int m = 0; m < 4; ++m) _Pragma("unroll") for (int n = 0; n < 2; ++n) _Pragma("unroll") for (int k = 0; k < 2; ++k) \
;         acc[ai][bj][m][n] = __builtin_amdgcn_mfma_f32_16x16x32_bf16(Bt[n][k], At[m][k], acc[ai][bj][m][n], 0, 0, 0); __builtin_amdgcn_s_setprio(0); } while (0)
; #define PG8_WAIT_V(n) asm volatile("s_waitcnt vmcnt(" #n ")" ::: "memory")
; #define PG8_WAIT_L(n) asm volatile("s_waitcnt lgkmcnt(" #n ")" ::: "memory")
; #define PG8_BAR __builtin_amdgcn_s_barrier()
; #define PG8_SCHED __builtin_amdgcn_sched_barrier(0)
; template <class Epi, class Sched, bool ALIGN_EPI = false, bool SP2 = false>
; __device__ __forceinline__ void gemm_phase(PG8_LAS unsigned char* lds, const Gemm g, const Sched& S, const Epi& E, int wave_s) {
;     ...
;             PG8_LDA(At, 0, 1); PG8_STAGE(PG8_SB(0, 0), b2, voffB); PG8_STAGE(PG8_SB(0, 1), b2 + hstepB, voffB); PG8_STAGE(PG8_SA(0, 0), a2, voffA);
;             PG8_WAIT_V(8); PG8_WAIT_L(0); PG8_BAR; PG8_MMA(1, 0, At, B0); PG8_MMA(1, 1, At, B1); PG8_BAR; PG8_SCHED;
;             PG8_LDB(B0, 1, 0); PG8_LDB(B1, 1, 1); PG8_SCHED; PG8_LDA(At, 1, 0); PG8_STAGE(PG8_SA(0, 1), a2 + hstepA, voffA);
;             PG8_WAIT_V(8); PG8_WAIT_L(0); PG8_BAR; PG8_MMA(0, 0, At, B0); PG8_MMA(0, 1, At, B1); PG8_BAR; PG8_SCHED;
	s_add_i32 s56, s56, s44
	s_add_u32 s98, s26, s60
	s_addc_u32 s99, s27, s61
	s_mov_b32 m0, s56
	ds_read_b128 v[194:197], v151 offset:16384
	ds_read_b128 v[198:201], v151 offset:17408
	ds_read_b128 v[212:215], v151 offset:18432
	ds_read_b128 v[216:219], v151 offset:19456
	ds_read_b128 v[220:223], v151 offset:20480
	ds_read_b128 v[224:227], v151 offset:21504
	ds_read_b128 v[228:231], v151 offset:22528
	ds_read_b128 v[232:235], v151 offset:23552
	global_load_lds_dwordx4 v2, s[26:27]
	s_add_i32 m0, s56, 0x2000
	s_add_u32 s56, s26, 0x80000
	s_addc_u32 s57, s27, 0
	s_add_i32 s58, s58, s44
	global_load_lds_dwordx4 v0, s[26:27]
	s_mov_b32 m0, s58
	s_nop 0
	global_load_lds_dwordx4 v2, s[56:57]
	s_add_i32 m0, s58, 0x2000
	s_nop 0
	global_load_lds_dwordx4 v0, s[56:57]
	s_mov_b32 m0, s45
	s_nop 0
	global_load_lds_dwordx4 v134, s[36:37]
	s_mov_b32 m0, s46
	s_nop 0
	global_load_lds_dwordx4 v132, s[36:37]
	s_waitcnt vmcnt(8)
	s_waitcnt lgkmcnt(0)
	s_barrier
	s_setprio 1
	s_waitcnt lgkmcnt(0)
	v_mfma_f32_16x16x32_bf16 v[32:35], v[142:145], v[194:197], v[32:35]
	v_mfma_f32_16x16x32_bf16 v[28:31], v[156:159], v[194:197], v[28:31]
	v_mfma_f32_16x16x32_bf16 v[24:27], v[142:145], v[212:215], v[24:27]
	v_mfma_f32_16x16x32_bf16 v[20:23], v[156:159], v[212:215], v[20:23]
	v_mfma_f32_16x16x32_bf16 v[16:19], v[142:145], v[220:223], v[16:19]
	v_mfma_f32_16x16x32_bf16 v[12:15], v[156:159], v[220:223], v[12:15]
	v_mfma_f32_16x16x32_bf16 v[8:11], v[142:145], v[228:231], v[8:11]
	v_mfma_f32_16x16x32_bf16 v[4:7], v[156:159], v[228:231], v[4:7]
	v_mfma_f32_16x16x32_bf16 v[32:35], v[152:155], v[198:201], v[32:35]
	v_mfma_f32_16x16x32_bf16 v[28:31], v[160:163], v[198:201], v[28:31]
	v_mfma_f32_16x16x32_bf16 v[24:27], v[152:155], v[216:219], v[24:27]
	v_mfma_f32_16x16x32_bf16 v[20:23], v[160:163], v[216:219], v[20:23]
	v_mfma_f32_16x16x32_bf16 v[16:19], v[152:155], v[224:227], v[16:19]
	v_mfma_f32_16x16x32_bf16 v[12:15], v[160:163], v[224:227], v[12:15]
	v_mfma_f32_16x16x32_bf16 v[8:11], v[152:155], v[232:235], v[8:11]
	v_mfma_f32_16x16x32_bf16 v[4:7], v[160:163], v[232:235], v[4:7]
	s_setprio 0
	s_setprio 1
	v_mfma_f32_16x16x32_bf16 v[96:99], v[164:167], v[194:197], v[96:99]
	v_mfma_f32_16x16x32_bf16 v[92:95], v[186:189], v[194:197], v[92:95]
	v_mfma_f32_16x16x32_bf16 v[88:91], v[164:167], v[212:215], v[88:91]
	v_mfma_f32_16x16x32_bf16 v[84:87], v[186:189], v[212:215], v[84:87]
	v_mfma_f32_16x16x32_bf16 v[80:83], v[164:167], v[220:223], v[80:83]
	v_mfma_f32_16x16x32_bf16 v[76:79], v[186:189], v[220:223], v[76:79]
	v_mfma_f32_16x16x32_bf16 v[40:43], v[164:167], v[228:231], v[40:43]
	v_mfma_f32_16x16x32_bf16 v[36:39], v[186:189], v[228:231], v[36:39]
	v_mfma_f32_16x16x32_bf16 v[96:99], v[182:185], v[198:201], v[96:99]
	v_mfma_f32_16x16x32_bf16 v[92:95], v[190:193], v[198:201], v[92:95]
	v_mfma_f32_16x16x32_bf16 v[88:91], v[182:185], v[216:219], v[88:91]
	v_mfma_f32_16x16x32_bf16 v[84:87], v[190:193], v[216:219], v[84:87]
	v_mfma_f32_16x16x32_bf16 v[80:83], v[182:185], v[224:227], v[80:83]
	v_mfma_f32_16x16x32_bf16 v[76:79], v[190:193], v[224:227], v[76:79]
	v_mfma_f32_16x16x32_bf16 v[40:43], v[182:185], v[232:235], v[40:43]
	v_mfma_f32_16x16x32_bf16 v[36:39], v[190:193], v[232:235], v[36:39]
	s_setprio 0
	s_barrier
	s_nop 0
	s_add_i32 s56, 0, 0x18000
	s_add_i32 s57, 0, 0x1c000
	v_add_u32_e32 v160, s56, v149
	v_add_u32_e32 v173, s57, v149
	ds_read_b128 v[142:145], v160
	ds_read_b128 v[152:155], v160 offset:1024
	ds_read_b128 v[156:159], v160 offset:2048
	ds_read_b128 v[160:163], v160 offset:3072
	ds_read_b128 v[164:167], v173
	ds_read_b128 v[182:185], v173 offset:1024
	ds_read_b128 v[186:189], v173 offset:2048
	ds_read_b128 v[190:193], v173 offset:3072
	s_add_u32 s100, s36, s60
	s_addc_u32 s101, s37, s61
	s_add_u32 s36, s36, 0x80000
	s_addc_u32 s37, s37, 0
	s_mov_b32 m0, s47
	ds_read_b128 v[194:197], v151 offset:32768
	ds_read_b128 v[198:201], v151 offset:33792
	ds_read_b128 v[212:215], v151 offset:34816
	ds_read_b128 v[216:219], v151 offset:35840
	ds_read_b128 v[220:223], v151 offset:36864
	ds_read_b128 v[224:227], v151 offset:37888
	ds_read_b128 v[228:231], v151 offset:38912
	ds_read_b128 v[232:235], v151 offset:39936
	global_load_lds_dwordx4 v134, s[36:37]
	s_mov_b32 m0, s48
	s_nop 0
	global_load_lds_dwordx4 v132, s[36:37]
	s_waitcnt vmcnt(8)
	s_waitcnt lgkmcnt(0)
	s_barrier
; #define PG8_STAGE(bufoff, gbase, voff) do { _Pragma("unroll") for (int _i = 0; _i < 2; ++_i) \
;         __builtin_amdgcn_global_load_lds((const unsigned*)((const char*)(gbase) + (voff)[_i]), (PG8_LAS unsigned*)(lds + (bufoff) + ldsw + _i * 8192), 16, 0, 0); } while (0)
; #define PG8_LDA(dst, b, h) do { _Pragma("unroll") for (int m = 0; m < 4; ++m) _Pragma("unroll") for (int k = 0; k < 2; ++k) dst[m][k] = *(const PG8_LAS bf16x8*)(lds + PG8_SA(b, h) + aoff + m * 2048 + k * 1024); } while (0)
; #define PG8_MMA(ai, bj, At, Bt) do { __builtin_amdgcn_s_setprio(1); _Pragma("unroll") for (int m = 0; m < 4; ++m) _Pragma("unroll") for (int n = 0; n < 2; ++n) _Pragma("unroll") for (int k = 0; k < 2; ++k) \
;         acc[ai][bj][m][n] = __builtin_amdgcn_mfma_f32_16x16x32_bf16(Bt[n][k], At[m][k], acc[ai][bj][m][n], 0, 0, 0); __builtin_amdgcn_s_setprio(0); } while (0)
; #define PG8_WAIT_V(n) asm volatile("s_waitcnt vmcnt(" #n ")" ::: "memory")
; #define PG8_WAIT_L(n) asm volatile("s_waitcnt lgkmcnt(" #n ")" ::: "memory")
; #define PG8_BAR __builtin_amdgcn_s_barrier()
; #define PG8_SCHED __builtin_amdgcn_sched_barrier(0)
;     __device__ __forceinline__ void operator()(const f32x4 (&acc)[2][2][4][2], const Unit& u, int wr, int wc, int fr, int fq) const {
;         const int row0 = u.pm * BM + wr * 64 + fr;
;         if (u.pn == 74) {
; template <class Epi, class Sched, bool ALIGN_EPI = false, bool SP2 = false>
; __device__ __forceinline__ void gemm_phase(PG8_LAS unsigned char* lds, const Gemm g, const Sched& S, const Epi& E, int wave_s) {
;     ...
;             PG8_WAIT_V(8); PG8_WAIT_L(0); PG8_BAR; PG8_MMA(0, 0, At, B0); PG8_MMA(0, 1, At, B1); PG8_BAR; PG8_SCHED;
;             PG8_LDA(At, 1, 1); PG8_STAGE(PG8_SB(1, 0), b3, voffB); PG8_STAGE(PG8_SB(1, 1), b3 + hstepB, voffB); PG8_STAGE(PG8_SA(1, 0), a3, voffA);
;             PG8_WAIT_V(8); PG8_WAIT_L(0); PG8_BAR; PG8_MMA(1, 0, At, B0); PG8_MMA(1, 1, At, B1); PG8_BAR; PG8_SCHED;
	s_setprio 1
	s_waitcnt lgkmcnt(0)
	v_mfma_f32_16x16x32_bf16 v[72:75], v[142:145], v[194:197], v[72:75]
	v_mfma_f32_16x16x32_bf16 v[68:71], v[156:159], v[194:197], v[68:71]
	v_mfma_f32_16x16x32_bf16 v[64:67], v[142:145], v[212:215], v[64:67]
	v_mfma_f32_16x16x32_bf16 v[60:63], v[156:159], v[212:215], v[60:63]
	v_mfma_f32_16x16x32_bf16 v[56:59], v[142:145], v[220:223], v[56:59]
	v_mfma_f32_16x16x32_bf16 v[52:55], v[156:159], v[220:223], v[52:55]
	v_mfma_f32_16x16x32_bf16 v[48:51], v[142:145], v[228:231], v[48:51]
	v_mfma_f32_16x16x32_bf16 v[44:47], v[156:159], v[228:231], v[44:47]
	v_mfma_f32_16x16x32_bf16 v[72:75], v[152:155], v[198:201], v[72:75]
	v_mfma_f32_16x16x32_bf16 v[68:71], v[160:163], v[198:201], v[68:71]
	v_mfma_f32_16x16x32_bf16 v[64:67], v[152:155], v[216:219], v[64:67]
	v_mfma_f32_16x16x32_bf16 v[60:63], v[160:163], v[216:219], v[60:63]
	v_mfma_f32_16x16x32_bf16 v[56:59], v[152:155], v[224:227], v[56:59]
	v_mfma_f32_16x16x32_bf16 v[52:55], v[160:163], v[224:227], v[52:55]
	v_mfma_f32_16x16x32_bf16 v[48:51], v[152:155], v[232:235], v[48:51]
	v_mfma_f32_16x16x32_bf16 v[44:47], v[160:163], v[232:235], v[44:47]
	s_setprio 0
	s_setprio 1
	v_mfma_f32_16x16x32_bf16 v[128:131], v[164:167], v[194:197], v[128:131]
	v_mfma_f32_16x16x32_bf16 v[124:127], v[186:189], v[194:197], v[124:127]
	v_mfma_f32_16x16x32_bf16 v[120:123], v[164:167], v[212:215], v[120:123]
	v_mfma_f32_16x16x32_bf16 v[116:119], v[186:189], v[212:215], v[116:119]
	v_mfma_f32_16x16x32_bf16 v[112:115], v[164:167], v[220:223], v[112:115]
	v_mfma_f32_16x16x32_bf16 v[108:111], v[186:189], v[220:223], v[108:111]
	v_mfma_f32_16x16x32_bf16 v[104:107], v[164:167], v[228:231], v[104:107]
	v_mfma_f32_16x16x32_bf16 v[100:103], v[186:189], v[228:231], v[100:103]
	v_mfma_f32_16x16x32_bf16 v[128:131], v[182:185], v[198:201], v[128:131]
	v_mfma_f32_16x16x32_bf16 v[124:127], v[190:193], v[198:201], v[124:127]
	v_mfma_f32_16x16x32_bf16 v[120:123], v[182:185], v[216:219], v[120:123]
	v_mfma_f32_16x16x32_bf16 v[116:119], v[190:193], v[216:219], v[116:119]
	v_mfma_f32_16x16x32_bf16 v[112:115], v[182:185], v[224:227], v[112:115]
	v_mfma_f32_16x16x32_bf16 v[108:111], v[190:193], v[224:227], v[108:111]
	v_mfma_f32_16x16x32_bf16 v[104:107], v[182:185], v[232:235], v[104:107]
	v_mfma_f32_16x16x32_bf16 v[100:103], v[190:193], v[232:235], v[100:103]
	s_setprio 0
	s_barrier
	s_add_i32 s36, s56, s44
	s_mov_b32 m0, s36
	ds_read_b128 v[194:197], v151 offset:49152
	ds_read_b128 v[198:201], v151 offset:50176
	ds_read_b128 v[212:215], v151 offset:51200
	ds_read_b128 v[216:219], v151 offset:52224
	ds_read_b128 v[220:223], v151 offset:53248
	ds_read_b128 v[224:227], v151 offset:54272
	ds_read_b128 v[228:231], v151 offset:55296
	ds_read_b128 v[232:235], v151 offset:56320
	global_load_lds_dwordx4 v2, s[98:99]
	s_add_i32 m0, s36, 0x2000
	s_add_u32 s26, s26, 0x80080
	s_addc_u32 s27, s27, 0
	s_add_i32 s36, s57, s44
	global_load_lds_dwordx4 v0, s[98:99]
	s_mov_b32 m0, s36
	s_nop 0
	global_load_lds_dwordx4 v2, s[26:27]
	s_add_i32 m0, s36, 0x2000
	s_nop 0
	global_load_lds_dwordx4 v0, s[26:27]
	s_mov_b32 m0, s49
	s_nop 0
	global_load_lds_dwordx4 v134, s[100:101]
	s_mov_b32 m0, s50
	s_nop 0
	global_load_lds_dwordx4 v132, s[100:101]
	s_waitcnt vmcnt(8)
	s_waitcnt lgkmcnt(0)
	s_barrier
	s_setprio 1
	s_waitcnt lgkmcnt(0)
	v_mfma_f32_16x16x32_bf16 v[32:35], v[142:145], v[194:197], v[32:35]
	v_mfma_f32_16x16x32_bf16 v[28:31], v[156:159], v[194:197], v[28:31]
	v_mfma_f32_16x16x32_bf16 v[24:27], v[142:145], v[212:215], v[24:27]
	v_mfma_f32_16x16x32_bf16 v[20:23], v[156:159], v[212:215], v[20:23]
	v_mfma_f32_16x16x32_bf16 v[16:19], v[142:145], v[220:223], v[16:19]
	v_mfma_f32_16x16x32_bf16 v[12:15], v[156:159], v[220:223], v[12:15]
	v_mfma_f32_16x16x32_bf16 v[8:11], v[142:145], v[228:231], v[8:11]
	v_mfma_f32_16x16x32_bf16 v[4:7], v[156:159], v[228:231], v[4:7]
	v_mfma_f32_16x16x32_bf16 v[32:35], v[152:155], v[198:201], v[32:35]
	v_mfma_f32_16x16x32_bf16 v[28:31], v[160:163], v[198:201], v[28:31]
	v_mfma_f32_16x16x32_bf16 v[24:27], v[152:155], v[216:219], v[24:27]
	v_mfma_f32_16x16x32_bf16 v[20:23], v[160:163], v[216:219], v[20:23]
	v_mfma_f32_16x16x32_bf16 v[16:19], v[152:155], v[224:227], v[16:19]
	v_mfma_f32_16x16x32_bf16 v[12:15], v[160:163], v[224:227], v[12:15]
	v_mfma_f32_16x16x32_bf16 v[8:11], v[152:155], v[232:235], v[8:11]
	v_mfma_f32_16x16x32_bf16 v[4:7], v[160:163], v[232:235], v[4:7]
	s_setprio 0
	s_setprio 1
	v_mfma_f32_16x16x32_bf16 v[96:99], v[164:167], v[194:197], v[96:99]
	v_mfma_f32_16x16x32_bf16 v[92:95], v[186:189], v[194:197], v[92:95]
	v_mfma_f32_16x16x32_bf16 v[88:91], v[164:167], v[212:215], v[88:91]
	v_mfma_f32_16x16x32_bf16 v[84:87], v[186:189], v[212:215], v[84:87]
	v_mfma_f32_16x16x32_bf16 v[80:83], v[164:167], v[220:223], v[80:83]
	v_mfma_f32_16x16x32_bf16 v[76:79], v[186:189], v[220:223], v[76:79]
	v_mfma_f32_16x16x32_bf16 v[40:43], v[164:167], v[228:231], v[40:43]
	v_mfma_f32_16x16x32_bf16 v[36:39], v[186:189], v[228:231], v[36:39]
	v_mfma_f32_16x16x32_bf16 v[96:99], v[182:185], v[198:201], v[96:99]
	v_mfma_f32_16x16x32_bf16 v[92:95], v[190:193], v[198:201], v[92:95]
	v_mfma_f32_16x16x32_bf16 v[88:91], v[182:185], v[216:219], v[88:91]
	v_mfma_f32_16x16x32_bf16 v[84:87], v[190:193], v[216:219], v[84:87]
	v_mfma_f32_16x16x32_bf16 v[80:83], v[182:185], v[224:227], v[80:83]
	v_mfma_f32_16x16x32_bf16 v[76:79], v[190:193], v[224:227], v[76:79]
	v_mfma_f32_16x16x32_bf16 v[40:43], v[182:185], v[232:235], v[40:43]
	v_mfma_f32_16x16x32_bf16 v[36:39], v[190:193], v[232:235], v[36:39]
	s_setprio 0
	s_barrier
	s_add_i32 s55, s55, 2
	s_add_u32 s53, s53, 0x100
	s_addc_u32 s54, s54, 0
	s_add_u32 s18, s18, 0x100
	s_addc_u32 s19, s19, 0
	s_cmp_gt_u32 s55, 29
	s_cbranch_scc0 .LBB0_192
	s_and_b64 vcc, exec, s[6:7]
	s_cbranch_vccnz .LBB0_196
	v_lshl_add_u32 v142, s38, 8, v148
	s_cmpk_lg_i32 s33, 0x4a
	s_mov_b64 s[18:19], -1
	s_cbranch_scc1 .LBB0_197

; #define PG8_STAGE(bufoff, gbase, voff) do { _Pragma("unroll") for (int _i = 0; _i < 2; ++_i) \
;         __builtin_amdgcn_global_load_lds((const unsigned*)((const char*)(gbase) + (voff)[_i]), (PG8_LAS unsigned*)(lds + (bufoff) + ldsw + _i * 8192), 16, 0, 0); } while (0)
; #define PG8_LDA(dst, b, h) do { _Pragma("unroll") for (int m = 0; m < 4; ++m) _Pragma("unroll") for (int k = 0; k < 2; ++k) dst[m][k] = *(const PG8_LAS bf16x8*)(lds + PG8_SA(b, h) + aoff + m * 2048 + k * 1024); } while (0)
; #define PG8_LDB(dst, b, h) do { _Pragma("unroll") for (int n = 0; n < 2; ++n) _Pragma("unroll") for (int k = 0; k < 2; ++k) dst[n][k] = *(const PG8_LAS bf16x8*)(lds + PG8_SB(b, h) + boff + n * 2048 + k * 1024); } while (0)
; #define PG8_WAIT_V(n) asm volatile("s_waitcnt vmcnt(" #n ")" ::: "memory")
; #define PG8_WAIT_L(n) asm volatile("s_waitcnt lgkmcnt(" #n ")" ::: "memory")
; #define PG8_BAR __builtin_amdgcn_s_barrier()
; #define PG8_SCHED __builtin_amdgcn_sched_barrier(0)
; template <class Epi, class Sched, bool ALIGN_EPI = false, bool SP2 = false>
; __device__ __forceinline__ void gemm_phase(PG8_LAS unsigned char* lds, const Gemm g, const Sched& S, const Epi& E, int wave_s) {
;     ...
;         const bool has_next = S.next(ui + 1, nxt);
;         const char* nA = has_next ? (const char*)g.A + (size_t)nxt.pm * tstepA : cA; const char* nB = has_next ? (const char*)g.Bt + (size_t)nxt.pn * tstepB : cB;
;         for (int t = 0; t < nt; t += 2) {
;             const bool last = (t == nt - 2);
;             const char* a1 = cA + (size_t)(t + 1) * kstep;
;             const char* a2 = last ? nA : cA + (size_t)(t + 2) * kstep; const char* b2 = last ? nB : cB + (size_t)(t + 2) * kstep;
;             const char* a3 = a2 + kstep; const char* b3 = b2 + kstep;
;             if (last && has_next) S.a_ready(nxt);
;             if constexpr (SP2) {
;             PG8_LDB(B0, 0, 0); PG8_LDB(B1, 0, 1); PG8_SCHED; PG8_LDA(At, 0, 0); PG8_STAGE(PG8_SA(1, 1), a1 + hstepA, voffA);
;             PG8_WAIT_V(8); PG8_WAIT_L(0); PG8_BAR; PG8_MMA(0, 0, At, B0); PG8_MMA(0, 1, At, B1); PG8_BAR; PG8_SCHED;
;     ...
;         for (int a = 0; a < 2; ++a)
; #pragma unroll
;             for (int b = 0; b < 2; ++b)
; #pragma unroll
;                 for (int m = 0; m < 4; ++m)
; #pragma unroll
;                     for (int n = 0; n < 2; ++n) acc[a][b][m][n] = (f32x4){0.f, 0.f, 0.f, 0.f};
.LBB0_567:
	s_ashr_i32 s19, s18, 31
	s_lshl_b64 s[22:23], s[18:19], 18
	s_add_u32 s22, s46, s22
	s_addc_u32 s23, s47, s23
	s_and_b64 s[38:39], s[38:39], exec
	s_cselect_b32 s19, s23, s27
	s_cselect_b32 s58, s22, s26
	s_add_u32 s59, s26, 0x100
	s_addc_u32 s66, s27, 0
	s_mov_b32 s67, -2
	s_waitcnt vmcnt(0) lgkmcnt(0)
	v_mov_b64_e32 v[4:5], 0
	v_mov_b64_e32 v[6:7], 0
	v_mov_b64_e32 v[8:9], 0
	v_mov_b64_e32 v[10:11], 0
	v_mov_b64_e32 v[12:13], 0
	v_mov_b64_e32 v[14:15], 0
	v_mov_b64_e32 v[16:17], 0
	v_mov_b64_e32 v[18:19], 0
	v_mov_b64_e32 v[20:21], 0
	v_mov_b64_e32 v[22:23], 0
	v_mov_b64_e32 v[24:25], 0
	v_mov_b64_e32 v[26:27], 0
	v_mov_b64_e32 v[28:29], 0
	v_mov_b64_e32 v[30:31], 0
	v_mov_b64_e32 v[32:33], 0
	v_mov_b64_e32 v[34:35], 0
	v_mov_b64_e32 v[36:37], 0
	v_mov_b64_e32 v[38:39], 0
	v_mov_b64_e32 v[40:41], 0
	v_mov_b64_e32 v[42:43], 0
	v_mov_b64_e32 v[44:45], 0
	v_mov_b64_e32 v[46:47], 0
	v_mov_b64_e32 v[48:49], 0
	v_mov_b64_e32 v[50:51], 0
	v_mov_b64_e32 v[52:53], 0
	v_mov_b64_e32 v[54:55], 0
	v_mov_b64_e32 v[56:57], 0
	v_mov_b64_e32 v[58:59], 0
	v_mov_b64_e32 v[60:61], 0
	v_mov_b64_e32 v[62:63], 0
	v_mov_b64_e32 v[64:65], 0
	v_mov_b64_e32 v[66:67], 0
	v_mov_b64_e32 v[68:69], 0
	v_mov_b64_e32 v[70:71], 0
	v_mov_b64_e32 v[72:73], 0
	v_mov_b64_e32 v[74:75], 0
	v_mov_b64_e32 v[76:77], 0
	v_mov_b64_e32 v[78:79], 0
	v_mov_b64_e32 v[80:81], 0
	v_mov_b64_e32 v[82:83], 0
	v_mov_b64_e32 v[84:85], 0
	v_mov_b64_e32 v[86:87], 0
	v_mov_b64_e32 v[88:89], 0
	v_mov_b64_e32 v[90:91], 0
	v_mov_b64_e32 v[92:93], 0
	v_mov_b64_e32 v[94:95], 0
	v_mov_b64_e32 v[96:97], 0
	v_mov_b64_e32 v[98:99], 0
	v_mov_b64_e32 v[100:101], 0
	v_mov_b64_e32 v[102:103], 0
	v_mov_b64_e32 v[104:105], 0
	v_mov_b64_e32 v[106:107], 0
	v_mov_b64_e32 v[108:109], 0
	v_mov_b64_e32 v[110:111], 0
	v_mov_b64_e32 v[112:113], 0
	v_mov_b64_e32 v[114:115], 0
	v_mov_b64_e32 v[116:117], 0
	v_mov_b64_e32 v[118:119], 0
	v_mov_b64_e32 v[120:121], 0
	v_mov_b64_e32 v[122:123], 0
	v_mov_b64_e32 v[124:125], 0
	v_mov_b64_e32 v[126:127], 0
	v_mov_b64_e32 v[128:129], 0
	v_mov_b64_e32 v[130:131], 0
.LBB0_568:
	s_nop 0
	s_add_u32 s26, s24, 0x100
	s_addc_u32 s27, s25, 0
	s_add_i32 s74, 0, 0x10000
	s_cmp_eq_u32 s67, 4
	s_cselect_b32 s43, s21, s27
	s_cselect_b32 s42, s20, s26
	s_cselect_b32 s39, s19, s66
	s_cselect_b32 s38, s58, s59
	s_add_i32 s75, 0, 0x14000
	v_add_u32_e32 v144, s74, v186
	v_add_u32_e32 v182, s75, v186
	ds_read_b128 v[132:135], v144
	ds_read_b128 v[136:139], v144 offset:1024
	ds_read_b128 v[140:143], v144 offset:2048
	ds_read_b128 v[144:147], v144 offset:3072
	ds_read_b128 v[148:151], v182
	ds_read_b128 v[160:163], v182 offset:1024
	ds_read_b128 v[164:167], v182 offset:2048
	ds_read_b128 v[182:185], v182 offset:3072
	v_lshl_add_u64 v[232:233], s[24:25], 0, v[158:159]
	s_add_i32 m0, s49, 0xc000
	ds_read_b128 v[190:193], v188
	ds_read_b128 v[194:197], v188 offset:1024
	ds_read_b128 v[198:201], v188 offset:2048
	ds_read_b128 v[212:215], v188 offset:3072
	ds_read_b128 v[216:219], v188 offset:4096
	ds_read_b128 v[220:223], v188 offset:5120
	ds_read_b128 v[224:227], v188 offset:6144
	ds_read_b128 v[228:231], v188 offset:7168
	global_load_lds_dwordx4 v[232:233], off
	v_lshl_add_u64 v[232:233], s[24:25], 0, v[156:157]
	s_add_i32 m0, s49, 0xe000
	s_nop 0
	global_load_lds_dwordx4 v[232:233], off
	s_waitcnt vmcnt(8)
	s_waitcnt lgkmcnt(0)
	s_barrier
	s_setprio 1
	s_waitcnt lgkmcnt(0)
	v_mfma_f32_16x16x32_bf16 v[128:131], v[132:135], v[190:193], v[128:131]
	v_mfma_f32_16x16x32_bf16 v[124:127], v[140:143], v[190:193], v[124:127]
	v_mfma_f32_16x16x32_bf16 v[120:123], v[132:135], v[198:201], v[120:123]
	v_mfma_f32_16x16x32_bf16 v[112:115], v[140:143], v[198:201], v[112:115]
	v_mfma_f32_16x16x32_bf16 v[100:103], v[132:135], v[216:219], v[100:103]
	v_mfma_f32_16x16x32_bf16 v[92:95], v[140:143], v[216:219], v[92:95]
	v_mfma_f32_16x16x32_bf16 v[84:87], v[132:135], v[224:227], v[84:87]
	v_mfma_f32_16x16x32_bf16 v[76:79], v[140:143], v[224:227], v[76:79]
	v_mfma_f32_16x16x32_bf16 v[128:131], v[136:139], v[194:197], v[128:131]
	v_mfma_f32_16x16x32_bf16 v[124:127], v[144:147], v[194:197], v[124:127]
	v_mfma_f32_16x16x32_bf16 v[120:123], v[136:139], v[212:215], v[120:123]
	v_mfma_f32_16x16x32_bf16 v[112:115], v[144:147], v[212:215], v[112:115]
	v_mfma_f32_16x16x32_bf16 v[100:103], v[136:139], v[220:223], v[100:103]
	v_mfma_f32_16x16x32_bf16 v[92:95], v[144:147], v[220:223], v[92:95]
	v_mfma_f32_16x16x32_bf16 v[84:87], v[136:139], v[228:231], v[84:87]
	v_mfma_f32_16x16x32_bf16 v[76:79], v[144:147], v[228:231], v[76:79]
	s_setprio 0
	s_setprio 1
	v_mfma_f32_16x16x32_bf16 v[116:119], v[148:151], v[190:193], v[116:119]
	v_mfma_f32_16x16x32_bf16 v[108:111], v[164:167], v[190:193], v[108:111]
	v_mfma_f32_16x16x32_bf16 v[104:107], v[148:151], v[198:201], v[104:107]
	v_mfma_f32_16x16x32_bf16 v[96:99], v[164:167], v[198:201], v[96:99]
	v_mfma_f32_16x16x32_bf16 v[88:91], v[148:151], v[216:219], v[88:91]
	v_mfma_f32_16x16x32_bf16 v[80:83], v[164:167], v[216:219], v[80:83]
	v_mfma_f32_16x16x32_bf16 v[72:75], v[148:151], v[224:227], v[72:75]
	v_mfma_f32_16x16x32_bf16 v[68:71], v[164:167], v[224:227], v[68:71]
	v_mfma_f32_16x16x32_bf16 v[116:119], v[160:163], v[194:197], v[116:119]
	v_mfma_f32_16x16x32_bf16 v[108:111], v[182:185], v[194:197], v[108:111]
	v_mfma_f32_16x16x32_bf16 v[104:107], v[160:163], v[212:215], v[104:107]
	v_mfma_f32_16x16x32_bf16 v[96:99], v[182:185], v[212:215], v[96:99]
	v_mfma_f32_16x16x32_bf16 v[88:91], v[160:163], v[220:223], v[88:91]
	v_mfma_f32_16x16x32_bf16 v[80:83], v[182:185], v[220:223], v[80:83]
	v_mfma_f32_16x16x32_bf16 v[72:75], v[160:163], v[228:231], v[72:75]
	v_mfma_f32_16x16x32_bf16 v[68:71], v[182:185], v[228:231], v[68:71]
	s_setprio 0
	s_barrier
; #define PG8_STAGE(bufoff, gbase, voff) do { _Pragma("unroll") for (int _i = 0; _i < 2; ++_i) \
;         __builtin_amdgcn_global_load_lds((const unsigned*)((const char*)(gbase) + (voff)[_i]), (PG8_LAS unsigned*)(lds + (bufoff) + ldsw + _i * 8192), 16, 0, 0); } while (0)
; #define PG8_LDA(dst, b, h) do { _Pragma("unroll") for (int m = 0; m < 4; ++m) _Pragma("unroll") for (int k = 0; k < 2; ++k) dst[m][k] = *(const PG8_LAS bf16x8*)(lds + PG8_SA(b, h) + aoff + m * 2048 + k * 1024); } while (0)
; #define PG8_LDB(dst, b, h) do { _Pragma("unroll") for (int n = 0; n < 2; ++n) _Pragma("unroll") for (int k = 0; k < 2; ++k) dst[n][k] = *(const PG8_LAS bf16x8*)(lds + PG8_SB(b, h) + boff + n * 2048 + k * 1024); } while (0)
; #define PG8_MMA(ai, bj, At, Bt) do { __builtin_amdgcn_s_setprio(1); _Pragma("unroll") for (int m = 0; m < 4; ++m) _Pragma("unroll") for (int n = 0; n < 2; ++n) _Pragma("unroll") for (int k = 0; k < 2; ++k) \
;         acc[ai][bj][m][n] = __builtin_amdgcn_mfma_f32_16x16x32_bf16(Bt[n][k], At[m][k], acc[ai][bj][m][n], 0, 0, 0); __builtin_amdgcn_s_setprio(0); } while (0)
; #define PG8_WAIT_V(n) asm volatile("s_waitcnt vmcnt(" #n ")" ::: "memory")
; #define PG8_WAIT_L(n) asm volatile("s_waitcnt lgkmcnt(" #n ")" ::: "memory")
; #define PG8_BAR __builtin_amdgcn_s_barrier()
; #define PG8_SCHED __builtin_amdgcn_sched_barrier(0)
; template <class Epi, class Sched, bool ALIGN_EPI = false, bool SP2 = false>
; __device__ __forceinline__ void gemm_phase(PG8_LAS unsigned char* lds, const Gemm g, const Sched& S, const Epi& E, int wave_s) {
;     ...
;             PG8_LDA(At, 0, 1); PG8_STAGE(PG8_SB(0, 0), b2, voffB); PG8_STAGE(PG8_SB(0, 1), b2 + hstepB, voffB); PG8_STAGE(PG8_SA(0, 0), a2, voffA);
;             PG8_WAIT_V(8); PG8_WAIT_L(0); PG8_BAR; PG8_MMA(1, 0, At, B0); PG8_MMA(1, 1, At, B1); PG8_BAR; PG8_SCHED;
;             PG8_LDB(B0, 1, 0); PG8_LDB(B1, 1, 1); PG8_SCHED; PG8_LDA(At, 1, 0); PG8_STAGE(PG8_SA(0, 1), a2 + hstepA, voffA);
;             PG8_WAIT_V(8); PG8_WAIT_L(0); PG8_BAR; PG8_MMA(0, 0, At, B0); PG8_MMA(0, 1, At, B1); PG8_BAR; PG8_SCHED;
	s_add_i32 s24, s74, s48
	s_add_u32 s98, s38, s60
	s_addc_u32 s99, s39, s61
	s_mov_b32 m0, s24
	ds_read_b128 v[190:193], v188 offset:16384
	ds_read_b128 v[194:197], v188 offset:17408
	ds_read_b128 v[198:201], v188 offset:18432
	ds_read_b128 v[212:215], v188 offset:19456
	ds_read_b128 v[216:219], v188 offset:20480
	ds_read_b128 v[220:223], v188 offset:21504
	ds_read_b128 v[224:227], v188 offset:22528
	ds_read_b128 v[228:231], v188 offset:23552
	global_load_lds_dwordx4 v2, s[38:39]
	s_add_i32 m0, s24, 0x2000
	s_add_u32 s24, s38, 0x20000
	s_addc_u32 s25, s39, 0
	s_add_i32 s74, s75, s48
	global_load_lds_dwordx4 v0, s[38:39]
	s_mov_b32 m0, s74
	s_add_u32 s100, s42, s60
	s_addc_u32 s101, s43, s61
	s_nop 0
	global_load_lds_dwordx4 v2, s[24:25]
	s_add_i32 m0, s74, 0x2000
	s_nop 0
	global_load_lds_dwordx4 v0, s[24:25]
	s_mov_b32 m0, s49
	s_nop 0
	global_load_lds_dwordx4 v154, s[42:43]
	s_mov_b32 m0, s50
	s_nop 0
	global_load_lds_dwordx4 v152, s[42:43]
	s_waitcnt vmcnt(8)
	s_waitcnt lgkmcnt(0)
	s_barrier
	s_setprio 1
	s_waitcnt lgkmcnt(0)
	v_mfma_f32_16x16x32_bf16 v[64:67], v[132:135], v[190:193], v[64:67]
	v_mfma_f32_16x16x32_bf16 v[60:63], v[140:143], v[190:193], v[60:63]
	v_mfma_f32_16x16x32_bf16 v[52:55], v[132:135], v[198:201], v[52:55]
	v_mfma_f32_16x16x32_bf16 v[44:47], v[140:143], v[198:201], v[44:47]
	v_mfma_f32_16x16x32_bf16 v[36:39], v[132:135], v[216:219], v[36:39]
	v_mfma_f32_16x16x32_bf16 v[28:31], v[140:143], v[216:219], v[28:31]
	v_mfma_f32_16x16x32_bf16 v[20:23], v[132:135], v[224:227], v[20:23]
	v_mfma_f32_16x16x32_bf16 v[12:15], v[140:143], v[224:227], v[12:15]
	v_mfma_f32_16x16x32_bf16 v[64:67], v[136:139], v[194:197], v[64:67]
	v_mfma_f32_16x16x32_bf16 v[60:63], v[144:147], v[194:197], v[60:63]
	v_mfma_f32_16x16x32_bf16 v[52:55], v[136:139], v[212:215], v[52:55]
	v_mfma_f32_16x16x32_bf16 v[44:47], v[144:147], v[212:215], v[44:47]
	v_mfma_f32_16x16x32_bf16 v[36:39], v[136:139], v[220:223], v[36:39]
	v_mfma_f32_16x16x32_bf16 v[28:31], v[144:147], v[220:223], v[28:31]
	v_mfma_f32_16x16x32_bf16 v[20:23], v[136:139], v[228:231], v[20:23]
	v_mfma_f32_16x16x32_bf16 v[12:15], v[144:147], v[228:231], v[12:15]
	s_setprio 0
	s_setprio 1
	v_mfma_f32_16x16x32_bf16 v[56:59], v[148:151], v[190:193], v[56:59]
	v_mfma_f32_16x16x32_bf16 v[48:51], v[164:167], v[190:193], v[48:51]
	v_mfma_f32_16x16x32_bf16 v[40:43], v[148:151], v[198:201], v[40:43]
	v_mfma_f32_16x16x32_bf16 v[32:35], v[164:167], v[198:201], v[32:35]
	v_mfma_f32_16x16x32_bf16 v[24:27], v[148:151], v[216:219], v[24:27]
	v_mfma_f32_16x16x32_bf16 v[16:19], v[164:167], v[216:219], v[16:19]
	v_mfma_f32_16x16x32_bf16 v[8:11], v[148:151], v[224:227], v[8:11]
	v_mfma_f32_16x16x32_bf16 v[4:7], v[164:167], v[224:227], v[4:7]
	v_mfma_f32_16x16x32_bf16 v[56:59], v[160:163], v[194:197], v[56:59]
	v_mfma_f32_16x16x32_bf16 v[48:51], v[182:185], v[194:197], v[48:51]
	v_mfma_f32_16x16x32_bf16 v[40:43], v[160:163], v[212:215], v[40:43]
	v_mfma_f32_16x16x32_bf16 v[32:35], v[182:185], v[212:215], v[32:35]
	v_mfma_f32_16x16x32_bf16 v[24:27], v[160:163], v[220:223], v[24:27]
	v_mfma_f32_16x16x32_bf16 v[16:19], v[182:185], v[220:223], v[16:19]
	v_mfma_f32_16x16x32_bf16 v[8:11], v[160:163], v[228:231], v[8:11]
	v_mfma_f32_16x16x32_bf16 v[4:7], v[182:185], v[228:231], v[4:7]
	s_setprio 0
	s_barrier
	s_nop 0
	s_add_i32 s74, 0, 0x18000
	s_add_i32 s75, 0, 0x1c000
	v_add_u32_e32 v144, s74, v186
	v_add_u32_e32 v182, s75, v186
	ds_read_b128 v[132:135], v144
	ds_read_b128 v[136:139], v144 offset:1024
	ds_read_b128 v[140:143], v144 offset:2048
	ds_read_b128 v[144:147], v144 offset:3072
	ds_read_b128 v[148:151], v182
	ds_read_b128 v[160:163], v182 offset:1024
	ds_read_b128 v[164:167], v182 offset:2048
	ds_read_b128 v[182:185], v182 offset:3072
	s_add_u32 s24, s42, 0x4b0000
	s_addc_u32 s25, s43, 0
	s_mov_b32 m0, s51
	ds_read_b128 v[190:193], v188 offset:32768
	ds_read_b128 v[194:197], v188 offset:33792
	ds_read_b128 v[198:201], v188 offset:34816
	ds_read_b128 v[212:215], v188 offset:35840
	ds_read_b128 v[216:219], v188 offset:36864
	ds_read_b128 v[220:223], v188 offset:37888
	ds_read_b128 v[224:227], v188 offset:38912
	ds_read_b128 v[228:231], v188 offset:39936
	global_load_lds_dwordx4 v154, s[24:25]
	s_mov_b32 m0, s52
	s_nop 0
	global_load_lds_dwordx4 v152, s[24:25]
	s_waitcnt vmcnt(8)
	s_waitcnt lgkmcnt(0)
	s_barrier
; #define PG8_STAGE(bufoff, gbase, voff) do { _Pragma("unroll") for (int _i = 0; _i < 2; ++_i) \
;         __builtin_amdgcn_global_load_lds((const unsigned*)((const char*)(gbase) + (voff)[_i]), (PG8_LAS unsigned*)(lds + (bufoff) + ldsw + _i * 8192), 16, 0, 0); } while (0)
; #define PG8_LDA(dst, b, h) do { _Pragma("unroll") for (int m = 0; m < 4; ++m) _Pragma("unroll") for (int k = 0; k < 2; ++k) dst[m][k] = *(const PG8_LAS bf16x8*)(lds + PG8_SA(b, h) + aoff + m * 2048 + k * 1024); } while (0)
; #define PG8_WAIT_V(n) asm volatile("s_waitcnt vmcnt(" #n ")" ::: "memory")
; #define PG8_WAIT_L(n) asm volatile("s_waitcnt lgkmcnt(" #n ")" ::: "memory")
; #define PG8_BAR __builtin_amdgcn_s_barrier()
; template <class Epi, class Sched, bool ALIGN_EPI = false, bool SP2 = false>
; __device__ __forceinline__ void gemm_phase(PG8_LAS unsigned char* lds, const Gemm g, const Sched& S, const Epi& E, int wave_s) {
;     ...
;         for (int t = 0; t < nt; t += 2) {
;             const bool last = (t == nt - 2);
;             const char* a1 = cA + (size_t)(t + 1) * kstep;
;             const char* a2 = last ? nA : cA + (size_t)(t + 2) * kstep; const char* b2 = last ? nB : cB + (size_t)(t + 2) * kstep;
;             const char* a3 = a2 + kstep; const char* b3 = b2 + kstep;
;             if (last && has_next) S.a_ready(nxt);
;             if constexpr (SP2) {
;             PG8_LDB(B0, 0, 0); PG8_LDB(B1, 0, 1); PG8_SCHED; PG8_LDA(At, 0, 0); PG8_STAGE(PG8_SA(1, 1), a1 + hstepA, voffA);
;             PG8_WAIT_V(8); PG8_WAIT_L(0); PG8_BAR; PG8_MMA(0, 0, At, B0); PG8_MMA(0, 1, At, B1); PG8_BAR; PG8_SCHED;
;             PG8_LDA(At, 0, 1); PG8_STAGE(PG8_SB(0, 0), b2, voffB); PG8_STAGE(PG8_SB(0, 1), b2 + hstepB, voffB); PG8_STAGE(PG8_SA(0, 0), a2, voffA);
;             PG8_WAIT_V(8); PG8_WAIT_L(0); PG8_BAR; PG8_MMA(1, 0, At, B0); PG8_MMA(1, 1, At, B1); PG8_BAR; PG8_SCHED;
;             PG8_LDB(B0, 1, 0); PG8_LDB(B1, 1, 1); PG8_SCHED; PG8_LDA(At, 1, 0); PG8_STAGE(PG8_SA(0, 1), a2 + hstepA, voffA);
;             PG8_WAIT_V(8); PG8_WAIT_L(0); PG8_BAR; PG8_MMA(0, 0, At, B0); PG8_MMA(0, 1, At, B1); PG8_BAR; PG8_SCHED;
;             PG8_LDA(At, 1, 1); PG8_STAGE(PG8_SB(1, 0), b3, voffB); PG8_STAGE(PG8_SB(1, 1), b3 + hstepB, voffB); PG8_STAGE(PG8_SA(1, 0), a3, voffA);
;             PG8_WAIT_V(8); PG8_WAIT_L(0); PG8_BAR; PG8_MMA(1, 0, At, B0); PG8_MMA(1, 1, At, B1); PG8_BAR; PG8_SCHED;
	s_setprio 1
	s_waitcnt lgkmcnt(0)
	v_mfma_f32_16x16x32_bf16 v[128:131], v[132:135], v[190:193], v[128:131]
	v_mfma_f32_16x16x32_bf16 v[124:127], v[140:143], v[190:193], v[124:127]
	v_mfma_f32_16x16x32_bf16 v[120:123], v[132:135], v[198:201], v[120:123]
	v_mfma_f32_16x16x32_bf16 v[112:115], v[140:143], v[198:201], v[112:115]
	v_mfma_f32_16x16x32_bf16 v[100:103], v[132:135], v[216:219], v[100:103]
	v_mfma_f32_16x16x32_bf16 v[92:95], v[140:143], v[216:219], v[92:95]
	v_mfma_f32_16x16x32_bf16 v[84:87], v[132:135], v[224:227], v[84:87]
	v_mfma_f32_16x16x32_bf16 v[76:79], v[140:143], v[224:227], v[76:79]
	v_mfma_f32_16x16x32_bf16 v[128:131], v[136:139], v[194:197], v[128:131]
	v_mfma_f32_16x16x32_bf16 v[124:127], v[144:147], v[194:197], v[124:127]
	v_mfma_f32_16x16x32_bf16 v[120:123], v[136:139], v[212:215], v[120:123]
	v_mfma_f32_16x16x32_bf16 v[112:115], v[144:147], v[212:215], v[112:115]
	v_mfma_f32_16x16x32_bf16 v[100:103], v[136:139], v[220:223], v[100:103]
	v_mfma_f32_16x16x32_bf16 v[92:95], v[144:147], v[220:223], v[92:95]
	v_mfma_f32_16x16x32_bf16 v[84:87], v[136:139], v[228:231], v[84:87]
	v_mfma_f32_16x16x32_bf16 v[76:79], v[144:147], v[228:231], v[76:79]
	s_setprio 0
	s_setprio 1
	v_mfma_f32_16x16x32_bf16 v[116:119], v[148:151], v[190:193], v[116:119]
	v_mfma_f32_16x16x32_bf16 v[108:111], v[164:167], v[190:193], v[108:111]
	v_mfma_f32_16x16x32_bf16 v[104:107], v[148:151], v[198:201], v[104:107]
	v_mfma_f32_16x16x32_bf16 v[96:99], v[164:167], v[198:201], v[96:99]
	v_mfma_f32_16x16x32_bf16 v[88:91], v[148:151], v[216:219], v[88:91]
	v_mfma_f32_16x16x32_bf16 v[80:83], v[164:167], v[216:219], v[80:83]
	v_mfma_f32_16x16x32_bf16 v[72:75], v[148:151], v[224:227], v[72:75]
	v_mfma_f32_16x16x32_bf16 v[68:71], v[164:167], v[224:227], v[68:71]
	v_mfma_f32_16x16x32_bf16 v[116:119], v[160:163], v[194:197], v[116:119]
	v_mfma_f32_16x16x32_bf16 v[108:111], v[182:185], v[194:197], v[108:111]
	v_mfma_f32_16x16x32_bf16 v[104:107], v[160:163], v[212:215], v[104:107]
	v_mfma_f32_16x16x32_bf16 v[96:99], v[182:185], v[212:215], v[96:99]
	v_mfma_f32_16x16x32_bf16 v[88:91], v[160:163], v[220:223], v[88:91]
	v_mfma_f32_16x16x32_bf16 v[80:83], v[182:185], v[220:223], v[80:83]
	v_mfma_f32_16x16x32_bf16 v[72:75], v[160:163], v[228:231], v[72:75]
	v_mfma_f32_16x16x32_bf16 v[68:71], v[182:185], v[228:231], v[68:71]
	s_setprio 0
	s_barrier
	s_add_i32 s24, s74, s48
	s_mov_b32 m0, s24
	ds_read_b128 v[190:193], v188 offset:49152
	ds_read_b128 v[194:197], v188 offset:50176
	ds_read_b128 v[198:201], v188 offset:51200
	ds_read_b128 v[212:215], v188 offset:52224
	ds_read_b128 v[216:219], v188 offset:53248
	ds_read_b128 v[220:223], v188 offset:54272
	ds_read_b128 v[224:227], v188 offset:55296
	ds_read_b128 v[228:231], v188 offset:56320
	global_load_lds_dwordx4 v2, s[98:99]
	s_add_i32 m0, s24, 0x2000
	s_add_u32 s24, s38, 0x20080
	s_addc_u32 s25, s39, 0
	s_add_i32 s38, s75, s48
	global_load_lds_dwordx4 v0, s[98:99]
	s_mov_b32 m0, s38
	s_nop 0
	global_load_lds_dwordx4 v2, s[24:25]
	s_add_i32 m0, s38, 0x2000
	s_nop 0
	global_load_lds_dwordx4 v0, s[24:25]
	s_mov_b32 m0, s53
	s_nop 0
	global_load_lds_dwordx4 v154, s[100:101]
	s_mov_b32 m0, s54
	s_nop 0
	global_load_lds_dwordx4 v152, s[100:101]
	s_waitcnt vmcnt(8)
	s_waitcnt lgkmcnt(0)
	s_barrier
	s_setprio 1
	s_waitcnt lgkmcnt(0)
	v_mfma_f32_16x16x32_bf16 v[64:67], v[132:135], v[190:193], v[64:67]
	v_mfma_f32_16x16x32_bf16 v[60:63], v[140:143], v[190:193], v[60:63]
	v_mfma_f32_16x16x32_bf16 v[52:55], v[132:135], v[198:201], v[52:55]
	v_mfma_f32_16x16x32_bf16 v[44:47], v[140:143], v[198:201], v[44:47]
	v_mfma_f32_16x16x32_bf16 v[36:39], v[132:135], v[216:219], v[36:39]
	v_mfma_f32_16x16x32_bf16 v[28:31], v[140:143], v[216:219], v[28:31]
	v_mfma_f32_16x16x32_bf16 v[20:23], v[132:135], v[224:227], v[20:23]
	v_mfma_f32_16x16x32_bf16 v[12:15], v[140:143], v[224:227], v[12:15]
	v_mfma_f32_16x16x32_bf16 v[64:67], v[136:139], v[194:197], v[64:67]
	v_mfma_f32_16x16x32_bf16 v[60:63], v[144:147], v[194:197], v[60:63]
	v_mfma_f32_16x16x32_bf16 v[52:55], v[136:139], v[212:215], v[52:55]
	v_mfma_f32_16x16x32_bf16 v[44:47], v[144:147], v[212:215], v[44:47]
	v_mfma_f32_16x16x32_bf16 v[36:39], v[136:139], v[220:223], v[36:39]
	v_mfma_f32_16x16x32_bf16 v[28:31], v[144:147], v[220:223], v[28:31]
	v_mfma_f32_16x16x32_bf16 v[20:23], v[136:139], v[228:231], v[20:23]
	v_mfma_f32_16x16x32_bf16 v[12:15], v[144:147], v[228:231], v[12:15]
	s_setprio 0
	s_setprio 1
	v_mfma_f32_16x16x32_bf16 v[56:59], v[148:151], v[190:193], v[56:59]
	v_mfma_f32_16x16x32_bf16 v[48:51], v[164:167], v[190:193], v[48:51]
	v_mfma_f32_16x16x32_bf16 v[40:43], v[148:151], v[198:201], v[40:43]
	v_mfma_f32_16x16x32_bf16 v[32:35], v[164:167], v[198:201], v[32:35]
	v_mfma_f32_16x16x32_bf16 v[24:27], v[148:151], v[216:219], v[24:27]
	v_mfma_f32_16x16x32_bf16 v[16:19], v[164:167], v[216:219], v[16:19]
	v_mfma_f32_16x16x32_bf16 v[8:11], v[148:151], v[224:227], v[8:11]
	v_mfma_f32_16x16x32_bf16 v[4:7], v[164:167], v[224:227], v[4:7]
	v_mfma_f32_16x16x32_bf16 v[56:59], v[160:163], v[194:197], v[56:59]
	v_mfma_f32_16x16x32_bf16 v[48:51], v[182:185], v[194:197], v[48:51]
	v_mfma_f32_16x16x32_bf16 v[40:43], v[160:163], v[212:215], v[40:43]
	v_mfma_f32_16x16x32_bf16 v[32:35], v[182:185], v[212:215], v[32:35]
	v_mfma_f32_16x16x32_bf16 v[24:27], v[160:163], v[220:223], v[24:27]
	v_mfma_f32_16x16x32_bf16 v[16:19], v[182:185], v[220:223], v[16:19]
	v_mfma_f32_16x16x32_bf16 v[8:11], v[160:163], v[228:231], v[8:11]
	v_mfma_f32_16x16x32_bf16 v[4:7], v[182:185], v[228:231], v[4:7]
	s_setprio 0
	s_barrier
	s_add_i32 s67, s67, 2
	s_add_u32 s59, s59, 0x100
	s_addc_u32 s66, s66, 0
	s_cmp_gt_u32 s67, 5
	s_mov_b64 s[24:25], s[26:27]
	s_cbranch_scc0 .LBB0_568
	s_and_b64 vcc, exec, s[16:17]
	s_cbranch_vccz .LBB0_571
	s_barrier

; #define PG8_STAGE(bufoff, gbase, voff) do { _Pragma("unroll") for (int _i = 0; _i < 2; ++_i) \
;         __builtin_amdgcn_global_load_lds((const unsigned*)((const char*)(gbase) + (voff)[_i]), (PG8_LAS unsigned*)(lds + (bufoff) + ldsw + _i * 8192), 16, 0, 0); } while (0)
; #define PG8_LDA(dst, b, h) do { _Pragma("unroll") for (int m = 0; m < 4; ++m) _Pragma("unroll") for (int k = 0; k < 2; ++k) dst[m][k] = *(const PG8_LAS bf16x8*)(lds + PG8_SA(b, h) + aoff + m * 2048 + k * 1024); } while (0)
; #define PG8_LDB(dst, b, h) do { _Pragma("unroll") for (int n = 0; n < 2; ++n) _Pragma("unroll") for (int k = 0; k < 2; ++k) dst[n][k] = *(const PG8_LAS bf16x8*)(lds + PG8_SB(b, h) + boff + n * 2048 + k * 1024); } while (0)
; #define PG8_WAIT_V(n) asm volatile("s_waitcnt vmcnt(" #n ")" ::: "memory")
; #define PG8_WAIT_L(n) asm volatile("s_waitcnt lgkmcnt(" #n ")" ::: "memory")
; #define PG8_BAR __builtin_amdgcn_s_barrier()
; #define PG8_SCHED __builtin_amdgcn_sched_barrier(0)
; template <class Epi, class Sched, bool ALIGN_EPI = false, bool SP2 = false>
; __device__ __forceinline__ void gemm_phase(PG8_LAS unsigned char* lds, const Gemm g, const Sched& S, const Epi& E, int wave_s) {
;     ...
;         const bool has_next = S.next(ui + 1, nxt);
;         const char* nA = has_next ? (const char*)g.A + (size_t)nxt.pm * tstepA : cA; const char* nB = has_next ? (const char*)g.Bt + (size_t)nxt.pn * tstepB : cB;
;         for (int t = 0; t < nt; t += 2) {
;             const bool last = (t == nt - 2);
;             const char* a1 = cA + (size_t)(t + 1) * kstep;
;             const char* a2 = last ? nA : cA + (size_t)(t + 2) * kstep; const char* b2 = last ? nB : cB + (size_t)(t + 2) * kstep;
;             const char* a3 = a2 + kstep; const char* b3 = b2 + kstep;
;             if (last && has_next) S.a_ready(nxt);
;             if constexpr (SP2) {
;             PG8_LDB(B0, 0, 0); PG8_LDB(B1, 0, 1); PG8_SCHED; PG8_LDA(At, 0, 0); PG8_STAGE(PG8_SA(1, 1), a1 + hstepA, voffA);
;             PG8_WAIT_V(8); PG8_WAIT_L(0); PG8_BAR; PG8_MMA(0, 0, At, B0); PG8_MMA(0, 1, At, B1); PG8_BAR; PG8_SCHED;
;     ...
;         for (int a = 0; a < 2; ++a)
; #pragma unroll
;             for (int b = 0; b < 2; ++b)
; #pragma unroll
;                 for (int m = 0; m < 4; ++m)
; #pragma unroll
;                     for (int n = 0; n < 2; ++n) acc[a][b][m][n] = (f32x4){0.f, 0.f, 0.f, 0.f};
.LBB0_589:
	s_ashr_i32 s47, s46, 31
	s_lshl_b64 s[0:1], s[46:47], 21
	s_add_u32 s50, s22, s0
	s_addc_u32 s51, s23, s1
	s_and_b64 s[0:1], s[38:39], exec
	s_cselect_b32 s38, s51, s7
	s_cselect_b32 s39, s50, s6
	s_add_u32 s47, s6, 0x100
	s_addc_u32 s56, s7, 0
	s_mov_b32 s57, -2
	s_waitcnt vmcnt(0) lgkmcnt(0)
	v_mov_b64_e32 v[4:5], 0
	v_mov_b64_e32 v[6:7], 0
	v_mov_b64_e32 v[8:9], 0
	v_mov_b64_e32 v[10:11], 0
	v_mov_b64_e32 v[12:13], 0
	v_mov_b64_e32 v[14:15], 0
	v_mov_b64_e32 v[16:17], 0
	v_mov_b64_e32 v[18:19], 0
	v_mov_b64_e32 v[20:21], 0
	v_mov_b64_e32 v[22:23], 0
	v_mov_b64_e32 v[24:25], 0
	v_mov_b64_e32 v[26:27], 0
	v_mov_b64_e32 v[28:29], 0
	v_mov_b64_e32 v[30:31], 0
	v_mov_b64_e32 v[32:33], 0
	v_mov_b64_e32 v[34:35], 0
	v_mov_b64_e32 v[36:37], 0
	v_mov_b64_e32 v[38:39], 0
	v_mov_b64_e32 v[40:41], 0
	v_mov_b64_e32 v[42:43], 0
	v_mov_b64_e32 v[44:45], 0
	v_mov_b64_e32 v[46:47], 0
	v_mov_b64_e32 v[48:49], 0
	v_mov_b64_e32 v[50:51], 0
	v_mov_b64_e32 v[52:53], 0
	v_mov_b64_e32 v[54:55], 0
	v_mov_b64_e32 v[56:57], 0
	v_mov_b64_e32 v[58:59], 0
	v_mov_b64_e32 v[60:61], 0
	v_mov_b64_e32 v[62:63], 0
	v_mov_b64_e32 v[64:65], 0
	v_mov_b64_e32 v[66:67], 0
	v_mov_b64_e32 v[68:69], 0
	v_mov_b64_e32 v[70:71], 0
	v_mov_b64_e32 v[72:73], 0
	v_mov_b64_e32 v[74:75], 0
	v_mov_b64_e32 v[76:77], 0
	v_mov_b64_e32 v[78:79], 0
	v_mov_b64_e32 v[80:81], 0
	v_mov_b64_e32 v[82:83], 0
	v_mov_b64_e32 v[84:85], 0
	v_mov_b64_e32 v[86:87], 0
	v_mov_b64_e32 v[88:89], 0
	v_mov_b64_e32 v[90:91], 0
	v_mov_b64_e32 v[92:93], 0
	v_mov_b64_e32 v[94:95], 0
	v_mov_b64_e32 v[96:97], 0
	v_mov_b64_e32 v[98:99], 0
	v_mov_b64_e32 v[104:105], 0
	v_mov_b64_e32 v[106:107], 0
	v_mov_b64_e32 v[108:109], 0
	v_mov_b64_e32 v[110:111], 0
	v_mov_b64_e32 v[112:113], 0
	v_mov_b64_e32 v[114:115], 0
	v_mov_b64_e32 v[116:117], 0
	v_mov_b64_e32 v[118:119], 0
	v_mov_b64_e32 v[128:129], 0
	v_mov_b64_e32 v[130:131], 0
	v_mov_b64_e32 v[132:133], 0
	v_mov_b64_e32 v[134:135], 0
	v_mov_b64_e32 v[136:137], 0
	v_mov_b64_e32 v[138:139], 0
	v_mov_b64_e32 v[140:141], 0
	v_mov_b64_e32 v[142:143], 0
.LBB0_590:
	s_add_u32 s0, s4, 0x100
	s_addc_u32 s1, s5, 0
	s_add_i32 s58, 0, 0x10000
	s_cmp_eq_u32 s57, 60
	s_cselect_b32 s17, s49, s1
	s_cselect_b32 s16, s48, s0
	s_cselect_b32 s7, s38, s56
	s_cselect_b32 s6, s39, s47
	s_add_i32 s59, 0, 0x14000
	v_add_u32_e32 v144, s58, v194
	v_add_u32_e32 v182, s59, v194
	ds_read_b128 v[100:103], v144
	ds_read_b128 v[120:123], v144 offset:1024
	ds_read_b128 v[124:127], v144 offset:2048
	ds_read_b128 v[144:147], v144 offset:3072
	ds_read_b128 v[148:151], v182
	ds_read_b128 v[152:155], v182 offset:1024
	ds_read_b128 v[156:159], v182 offset:2048
	ds_read_b128 v[182:185], v182 offset:3072
	v_lshl_add_u64 v[232:233], s[4:5], 0, v[166:167]
	s_add_i32 m0, s25, 0xc000
	ds_read_b128 v[186:189], v196
	ds_read_b128 v[190:193], v196 offset:1024
	ds_read_b128 v[198:201], v196 offset:2048
	ds_read_b128 v[212:215], v196 offset:3072
	ds_read_b128 v[216:219], v196 offset:4096
	ds_read_b128 v[220:223], v196 offset:5120
	ds_read_b128 v[224:227], v196 offset:6144
	ds_read_b128 v[228:231], v196 offset:7168
	global_load_lds_dwordx4 v[232:233], off
	v_lshl_add_u64 v[232:233], s[4:5], 0, v[164:165]
	s_add_i32 m0, s25, 0xe000
	s_nop 0
	global_load_lds_dwordx4 v[232:233], off
	s_waitcnt vmcnt(8)
	s_waitcnt lgkmcnt(0)
	s_barrier
	s_setprio 1
	s_waitcnt lgkmcnt(0)
	v_mfma_f32_16x16x32_bf16 v[140:143], v[100:103], v[186:189], v[140:143]
	v_mfma_f32_16x16x32_bf16 v[136:139], v[124:127], v[186:189], v[136:139]
	v_mfma_f32_16x16x32_bf16 v[116:119], v[100:103], v[198:201], v[116:119]
	v_mfma_f32_16x16x32_bf16 v[112:115], v[124:127], v[198:201], v[112:115]
	v_mfma_f32_16x16x32_bf16 v[96:99], v[100:103], v[216:219], v[96:99]
	v_mfma_f32_16x16x32_bf16 v[92:95], v[124:127], v[216:219], v[92:95]
	v_mfma_f32_16x16x32_bf16 v[80:83], v[100:103], v[224:227], v[80:83]
	v_mfma_f32_16x16x32_bf16 v[76:79], v[124:127], v[224:227], v[76:79]
	v_mfma_f32_16x16x32_bf16 v[140:143], v[120:123], v[190:193], v[140:143]
	v_mfma_f32_16x16x32_bf16 v[136:139], v[144:147], v[190:193], v[136:139]
	v_mfma_f32_16x16x32_bf16 v[116:119], v[120:123], v[212:215], v[116:119]
	v_mfma_f32_16x16x32_bf16 v[112:115], v[144:147], v[212:215], v[112:115]
	v_mfma_f32_16x16x32_bf16 v[96:99], v[120:123], v[220:223], v[96:99]
	v_mfma_f32_16x16x32_bf16 v[92:95], v[144:147], v[220:223], v[92:95]
	v_mfma_f32_16x16x32_bf16 v[80:83], v[120:123], v[228:231], v[80:83]
	v_mfma_f32_16x16x32_bf16 v[76:79], v[144:147], v[228:231], v[76:79]
	s_setprio 0
	s_setprio 1
	v_mfma_f32_16x16x32_bf16 v[132:135], v[148:151], v[186:189], v[132:135]
	v_mfma_f32_16x16x32_bf16 v[128:131], v[156:159], v[186:189], v[128:131]
	v_mfma_f32_16x16x32_bf16 v[108:111], v[148:151], v[198:201], v[108:111]
	v_mfma_f32_16x16x32_bf16 v[104:107], v[156:159], v[198:201], v[104:107]
	v_mfma_f32_16x16x32_bf16 v[88:91], v[148:151], v[216:219], v[88:91]
	v_mfma_f32_16x16x32_bf16 v[84:87], v[156:159], v[216:219], v[84:87]
	v_mfma_f32_16x16x32_bf16 v[72:75], v[148:151], v[224:227], v[72:75]
	v_mfma_f32_16x16x32_bf16 v[68:71], v[156:159], v[224:227], v[68:71]
	v_mfma_f32_16x16x32_bf16 v[132:135], v[152:155], v[190:193], v[132:135]
	v_mfma_f32_16x16x32_bf16 v[128:131], v[182:185], v[190:193], v[128:131]
	v_mfma_f32_16x16x32_bf16 v[108:111], v[152:155], v[212:215], v[108:111]
	v_mfma_f32_16x16x32_bf16 v[104:107], v[182:185], v[212:215], v[104:107]
	v_mfma_f32_16x16x32_bf16 v[88:91], v[152:155], v[220:223], v[88:91]
	v_mfma_f32_16x16x32_bf16 v[84:87], v[182:185], v[220:223], v[84:87]
	v_mfma_f32_16x16x32_bf16 v[72:75], v[152:155], v[228:231], v[72:75]
	v_mfma_f32_16x16x32_bf16 v[68:71], v[182:185], v[228:231], v[68:71]
	s_setprio 0
	s_barrier
; #define PG8_STAGE(bufoff, gbase, voff) do { _Pragma("unroll") for (int _i = 0; _i < 2; ++_i) \
;         __builtin_amdgcn_global_load_lds((const unsigned*)((const char*)(gbase) + (voff)[_i]), (PG8_LAS unsigned*)(lds + (bufoff) + ldsw + _i * 8192), 16, 0, 0); } while (0)
; #define PG8_LDA(dst, b, h) do { _Pragma("unroll") for (int m = 0; m < 4; ++m) _Pragma("unroll") for (int k = 0; k < 2; ++k) dst[m][k] = *(const PG8_LAS bf16x8*)(lds + PG8_SA(b, h) + aoff + m * 2048 + k * 1024); } while (0)
; #define PG8_LDB(dst, b, h) do { _Pragma("unroll") for (int n = 0; n < 2; ++n) _Pragma("unroll") for (int k = 0; k < 2; ++k) dst[n][k] = *(const PG8_LAS bf16x8*)(lds + PG8_SB(b, h) + boff + n * 2048 + k * 1024); } while (0)
; #define PG8_MMA(ai, bj, At, Bt) do { __builtin_amdgcn_s_setprio(1); _Pragma("unroll") for (int m = 0; m < 4; ++m) _Pragma("unroll") for (int n = 0; n < 2; ++n) _Pragma("unroll") for (int k = 0; k < 2; ++k) \
;         acc[ai][bj][m][n] = __builtin_amdgcn_mfma_f32_16x16x32_bf16(Bt[n][k], At[m][k], acc[ai][bj][m][n], 0, 0, 0); __builtin_amdgcn_s_setprio(0); } while (0)
; #define PG8_WAIT_V(n) asm volatile("s_waitcnt vmcnt(" #n ")" ::: "memory")
; #define PG8_WAIT_L(n) asm volatile("s_waitcnt lgkmcnt(" #n ")" ::: "memory")
; #define PG8_BAR __builtin_amdgcn_s_barrier()
; #define PG8_SCHED __builtin_amdgcn_sched_barrier(0)
; template <class Epi, class Sched, bool ALIGN_EPI = false, bool SP2 = false>
; __device__ __forceinline__ void gemm_phase(PG8_LAS unsigned char* lds, const Gemm g, const Sched& S, const Epi& E, int wave_s) {
;     ...
;             PG8_LDA(At, 0, 1); PG8_STAGE(PG8_SB(0, 0), b2, voffB); PG8_STAGE(PG8_SB(0, 1), b2 + hstepB, voffB); PG8_STAGE(PG8_SA(0, 0), a2, voffA);
;             PG8_WAIT_V(8); PG8_WAIT_L(0); PG8_BAR; PG8_MMA(1, 0, At, B0); PG8_MMA(1, 1, At, B1); PG8_BAR; PG8_SCHED;
;             PG8_LDB(B0, 1, 0); PG8_LDB(B1, 1, 1); PG8_SCHED; PG8_LDA(At, 1, 0); PG8_STAGE(PG8_SA(0, 1), a2 + hstepA, voffA);
;             PG8_WAIT_V(8); PG8_WAIT_L(0); PG8_BAR; PG8_MMA(0, 0, At, B0); PG8_MMA(0, 1, At, B1); PG8_BAR; PG8_SCHED;
	s_add_i32 s4, s58, s24
	s_add_u32 s98, s6, s60
	s_addc_u32 s99, s7, s61
	s_mov_b32 m0, s4
	ds_read_b128 v[186:189], v196 offset:16384
	ds_read_b128 v[190:193], v196 offset:17408
	ds_read_b128 v[198:201], v196 offset:18432
	ds_read_b128 v[212:215], v196 offset:19456
	ds_read_b128 v[216:219], v196 offset:20480
	ds_read_b128 v[220:223], v196 offset:21504
	ds_read_b128 v[224:227], v196 offset:22528
	ds_read_b128 v[228:231], v196 offset:23552
	global_load_lds_dwordx4 v2, s[6:7]
	s_add_i32 m0, s4, 0x2000
	s_add_u32 s4, s6, 0x100000
	s_addc_u32 s5, s7, 0
	s_add_i32 s58, s59, s24
	global_load_lds_dwordx4 v0, s[6:7]
	s_mov_b32 m0, s58
	s_add_u32 s100, s16, s60
	s_addc_u32 s101, s17, s61
	s_nop 0
	global_load_lds_dwordx4 v2, s[4:5]
	s_add_i32 m0, s58, 0x2000
	s_nop 0
	global_load_lds_dwordx4 v0, s[4:5]
	s_mov_b32 m0, s25
	s_nop 0
	global_load_lds_dwordx4 v162, s[16:17]
	s_mov_b32 m0, s26
	s_nop 0
	global_load_lds_dwordx4 v160, s[16:17]
	s_waitcnt vmcnt(8)
	s_waitcnt lgkmcnt(0)
	s_barrier
	s_setprio 1
	s_waitcnt lgkmcnt(0)
	v_mfma_f32_16x16x32_bf16 v[64:67], v[100:103], v[186:189], v[64:67]
	v_mfma_f32_16x16x32_bf16 v[60:63], v[124:127], v[186:189], v[60:63]
	v_mfma_f32_16x16x32_bf16 v[48:51], v[100:103], v[198:201], v[48:51]
	v_mfma_f32_16x16x32_bf16 v[44:47], v[124:127], v[198:201], v[44:47]
	v_mfma_f32_16x16x32_bf16 v[32:35], v[100:103], v[216:219], v[32:35]
	v_mfma_f32_16x16x32_bf16 v[28:31], v[124:127], v[216:219], v[28:31]
	v_mfma_f32_16x16x32_bf16 v[16:19], v[100:103], v[224:227], v[16:19]
	v_mfma_f32_16x16x32_bf16 v[12:15], v[124:127], v[224:227], v[12:15]
	v_mfma_f32_16x16x32_bf16 v[64:67], v[120:123], v[190:193], v[64:67]
	v_mfma_f32_16x16x32_bf16 v[60:63], v[144:147], v[190:193], v[60:63]
	v_mfma_f32_16x16x32_bf16 v[48:51], v[120:123], v[212:215], v[48:51]
	v_mfma_f32_16x16x32_bf16 v[44:47], v[144:147], v[212:215], v[44:47]
	v_mfma_f32_16x16x32_bf16 v[32:35], v[120:123], v[220:223], v[32:35]
	v_mfma_f32_16x16x32_bf16 v[28:31], v[144:147], v[220:223], v[28:31]
	v_mfma_f32_16x16x32_bf16 v[16:19], v[120:123], v[228:231], v[16:19]
	v_mfma_f32_16x16x32_bf16 v[12:15], v[144:147], v[228:231], v[12:15]
	s_setprio 0
	s_setprio 1
	v_mfma_f32_16x16x32_bf16 v[56:59], v[148:151], v[186:189], v[56:59]
	v_mfma_f32_16x16x32_bf16 v[52:55], v[156:159], v[186:189], v[52:55]
	v_mfma_f32_16x16x32_bf16 v[40:43], v[148:151], v[198:201], v[40:43]
	v_mfma_f32_16x16x32_bf16 v[36:39], v[156:159], v[198:201], v[36:39]
	v_mfma_f32_16x16x32_bf16 v[24:27], v[148:151], v[216:219], v[24:27]
	v_mfma_f32_16x16x32_bf16 v[20:23], v[156:159], v[216:219], v[20:23]
	v_mfma_f32_16x16x32_bf16 v[8:11], v[148:151], v[224:227], v[8:11]
	v_mfma_f32_16x16x32_bf16 v[4:7], v[156:159], v[224:227], v[4:7]
	v_mfma_f32_16x16x32_bf16 v[56:59], v[152:155], v[190:193], v[56:59]
	v_mfma_f32_16x16x32_bf16 v[52:55], v[182:185], v[190:193], v[52:55]
	v_mfma_f32_16x16x32_bf16 v[40:43], v[152:155], v[212:215], v[40:43]
	v_mfma_f32_16x16x32_bf16 v[36:39], v[182:185], v[212:215], v[36:39]
	v_mfma_f32_16x16x32_bf16 v[24:27], v[152:155], v[220:223], v[24:27]
	v_mfma_f32_16x16x32_bf16 v[20:23], v[182:185], v[220:223], v[20:23]
	v_mfma_f32_16x16x32_bf16 v[8:11], v[152:155], v[228:231], v[8:11]
	v_mfma_f32_16x16x32_bf16 v[4:7], v[182:185], v[228:231], v[4:7]
	s_setprio 0
	s_barrier
	s_nop 0
	s_add_i32 s58, 0, 0x18000
	s_add_i32 s59, 0, 0x1c000
	v_add_u32_e32 v144, s58, v194
	v_add_u32_e32 v182, s59, v194
	ds_read_b128 v[100:103], v144
	ds_read_b128 v[120:123], v144 offset:1024
	ds_read_b128 v[124:127], v144 offset:2048
	ds_read_b128 v[144:147], v144 offset:3072
	ds_read_b128 v[148:151], v182
	ds_read_b128 v[152:155], v182 offset:1024
	ds_read_b128 v[156:159], v182 offset:2048
	ds_read_b128 v[182:185], v182 offset:3072
	s_add_u32 s4, s16, 0x4b0000
	s_addc_u32 s5, s17, 0
	s_mov_b32 m0, s27
	ds_read_b128 v[186:189], v196 offset:32768
	ds_read_b128 v[190:193], v196 offset:33792
	ds_read_b128 v[198:201], v196 offset:34816
	ds_read_b128 v[212:215], v196 offset:35840
	ds_read_b128 v[216:219], v196 offset:36864
	ds_read_b128 v[220:223], v196 offset:37888
	ds_read_b128 v[224:227], v196 offset:38912
	ds_read_b128 v[228:231], v196 offset:39936
	global_load_lds_dwordx4 v162, s[4:5]
	s_mov_b32 m0, s30
	s_nop 0
	global_load_lds_dwordx4 v160, s[4:5]
	s_waitcnt vmcnt(8)
	s_waitcnt lgkmcnt(0)
	s_barrier
; #define PG8_STAGE(bufoff, gbase, voff) do { _Pragma("unroll") for (int _i = 0; _i < 2; ++_i) \
;         __builtin_amdgcn_global_load_lds((const unsigned*)((const char*)(gbase) + (voff)[_i]), (PG8_LAS unsigned*)(lds + (bufoff) + ldsw + _i * 8192), 16, 0, 0); } while (0)
; #define PG8_LDA(dst, b, h) do { _Pragma("unroll") for (int m = 0; m < 4; ++m) _Pragma("unroll") for (int k = 0; k < 2; ++k) dst[m][k] = *(const PG8_LAS bf16x8*)(lds + PG8_SA(b, h) + aoff + m * 2048 + k * 1024); } while (0)
; #define PG8_WAIT_V(n) asm volatile("s_waitcnt vmcnt(" #n ")" ::: "memory")
; #define PG8_WAIT_L(n) asm volatile("s_waitcnt lgkmcnt(" #n ")" ::: "memory")
; #define PG8_BAR __builtin_amdgcn_s_barrier()
; template <class Epi, class Sched, bool ALIGN_EPI = false, bool SP2 = false>
; __device__ __forceinline__ void gemm_phase(PG8_LAS unsigned char* lds, const Gemm g, const Sched& S, const Epi& E, int wave_s) {
;     ...
;         for (int t = 0; t < nt; t += 2) {
;             const bool last = (t == nt - 2);
;             const char* a1 = cA + (size_t)(t + 1) * kstep;
;             const char* a2 = last ? nA : cA + (size_t)(t + 2) * kstep; const char* b2 = last ? nB : cB + (size_t)(t + 2) * kstep;
;             const char* a3 = a2 + kstep; const char* b3 = b2 + kstep;
;             if (last && has_next) S.a_ready(nxt);
;             if constexpr (SP2) {
;             PG8_LDB(B0, 0, 0); PG8_LDB(B1, 0, 1); PG8_SCHED; PG8_LDA(At, 0, 0); PG8_STAGE(PG8_SA(1, 1), a1 + hstepA, voffA);
;             PG8_WAIT_V(8); PG8_WAIT_L(0); PG8_BAR; PG8_MMA(0, 0, At, B0); PG8_MMA(0, 1, At, B1); PG8_BAR; PG8_SCHED;
;             PG8_LDA(At, 0, 1); PG8_STAGE(PG8_SB(0, 0), b2, voffB); PG8_STAGE(PG8_SB(0, 1), b2 + hstepB, voffB); PG8_STAGE(PG8_SA(0, 0), a2, voffA);
;             PG8_WAIT_V(8); PG8_WAIT_L(0); PG8_BAR; PG8_MMA(1, 0, At, B0); PG8_MMA(1, 1, At, B1); PG8_BAR; PG8_SCHED;
;             PG8_LDB(B0, 1, 0); PG8_LDB(B1, 1, 1); PG8_SCHED; PG8_LDA(At, 1, 0); PG8_STAGE(PG8_SA(0, 1), a2 + hstepA, voffA);
;             PG8_WAIT_V(8); PG8_WAIT_L(0); PG8_BAR; PG8_MMA(0, 0, At, B0); PG8_MMA(0, 1, At, B1); PG8_BAR; PG8_SCHED;
;             PG8_LDA(At, 1, 1); PG8_STAGE(PG8_SB(1, 0), b3, voffB); PG8_STAGE(PG8_SB(1, 1), b3 + hstepB, voffB); PG8_STAGE(PG8_SA(1, 0), a3, voffA);
;             PG8_WAIT_V(8); PG8_WAIT_L(0); PG8_BAR; PG8_MMA(1, 0, At, B0); PG8_MMA(1, 1, At, B1); PG8_BAR; PG8_SCHED;
	s_setprio 1
	s_waitcnt lgkmcnt(0)
	v_mfma_f32_16x16x32_bf16 v[140:143], v[100:103], v[186:189], v[140:143]
	v_mfma_f32_16x16x32_bf16 v[136:139], v[124:127], v[186:189], v[136:139]
	v_mfma_f32_16x16x32_bf16 v[116:119], v[100:103], v[198:201], v[116:119]
	v_mfma_f32_16x16x32_bf16 v[112:115], v[124:127], v[198:201], v[112:115]
	v_mfma_f32_16x16x32_bf16 v[96:99], v[100:103], v[216:219], v[96:99]
	v_mfma_f32_16x16x32_bf16 v[92:95], v[124:127], v[216:219], v[92:95]
	v_mfma_f32_16x16x32_bf16 v[80:83], v[100:103], v[224:227], v[80:83]
	v_mfma_f32_16x16x32_bf16 v[76:79], v[124:127], v[224:227], v[76:79]
	v_mfma_f32_16x16x32_bf16 v[140:143], v[120:123], v[190:193], v[140:143]
	v_mfma_f32_16x16x32_bf16 v[136:139], v[144:147], v[190:193], v[136:139]
	v_mfma_f32_16x16x32_bf16 v[116:119], v[120:123], v[212:215], v[116:119]
	v_mfma_f32_16x16x32_bf16 v[112:115], v[144:147], v[212:215], v[112:115]
	v_mfma_f32_16x16x32_bf16 v[96:99], v[120:123], v[220:223], v[96:99]
	v_mfma_f32_16x16x32_bf16 v[92:95], v[144:147], v[220:223], v[92:95]
	v_mfma_f32_16x16x32_bf16 v[80:83], v[120:123], v[228:231], v[80:83]
	v_mfma_f32_16x16x32_bf16 v[76:79], v[144:147], v[228:231], v[76:79]
	s_setprio 0
	s_setprio 1
	v_mfma_f32_16x16x32_bf16 v[132:135], v[148:151], v[186:189], v[132:135]
	v_mfma_f32_16x16x32_bf16 v[128:131], v[156:159], v[186:189], v[128:131]
	v_mfma_f32_16x16x32_bf16 v[108:111], v[148:151], v[198:201], v[108:111]
	v_mfma_f32_16x16x32_bf16 v[104:107], v[156:159], v[198:201], v[104:107]
	v_mfma_f32_16x16x32_bf16 v[88:91], v[148:151], v[216:219], v[88:91]
	v_mfma_f32_16x16x32_bf16 v[84:87], v[156:159], v[216:219], v[84:87]
	v_mfma_f32_16x16x32_bf16 v[72:75], v[148:151], v[224:227], v[72:75]
	v_mfma_f32_16x16x32_bf16 v[68:71], v[156:159], v[224:227], v[68:71]
	v_mfma_f32_16x16x32_bf16 v[132:135], v[152:155], v[190:193], v[132:135]
	v_mfma_f32_16x16x32_bf16 v[128:131], v[182:185], v[190:193], v[128:131]
	v_mfma_f32_16x16x32_bf16 v[108:111], v[152:155], v[212:215], v[108:111]
	v_mfma_f32_16x16x32_bf16 v[104:107], v[182:185], v[212:215], v[104:107]
	v_mfma_f32_16x16x32_bf16 v[88:91], v[152:155], v[220:223], v[88:91]
	v_mfma_f32_16x16x32_bf16 v[84:87], v[182:185], v[220:223], v[84:87]
	v_mfma_f32_16x16x32_bf16 v[72:75], v[152:155], v[228:231], v[72:75]
	v_mfma_f32_16x16x32_bf16 v[68:71], v[182:185], v[228:231], v[68:71]
	s_setprio 0
	s_barrier
	s_add_i32 s4, s58, s24
	s_mov_b32 m0, s4
	ds_read_b128 v[186:189], v196 offset:49152
	ds_read_b128 v[190:193], v196 offset:50176
	ds_read_b128 v[198:201], v196 offset:51200
	ds_read_b128 v[212:215], v196 offset:52224
	ds_read_b128 v[216:219], v196 offset:53248
	ds_read_b128 v[220:223], v196 offset:54272
	ds_read_b128 v[224:227], v196 offset:55296
	ds_read_b128 v[228:231], v196 offset:56320
	global_load_lds_dwordx4 v2, s[98:99]
	s_add_i32 m0, s4, 0x2000
	s_add_u32 s4, s6, 0x100080
	s_addc_u32 s5, s7, 0
	s_add_i32 s6, s59, s24
	global_load_lds_dwordx4 v0, s[98:99]
	s_mov_b32 m0, s6
	s_nop 0
	global_load_lds_dwordx4 v2, s[4:5]
	s_add_i32 m0, s6, 0x2000
	s_nop 0
	global_load_lds_dwordx4 v0, s[4:5]
	s_mov_b32 m0, s52
	s_nop 0
	global_load_lds_dwordx4 v162, s[100:101]
	s_mov_b32 m0, s53
	s_nop 0
	global_load_lds_dwordx4 v160, s[100:101]
	s_waitcnt vmcnt(8)
	s_waitcnt lgkmcnt(0)
	s_barrier
	s_setprio 1
	s_waitcnt lgkmcnt(0)
	v_mfma_f32_16x16x32_bf16 v[64:67], v[100:103], v[186:189], v[64:67]
	v_mfma_f32_16x16x32_bf16 v[60:63], v[124:127], v[186:189], v[60:63]
	v_mfma_f32_16x16x32_bf16 v[48:51], v[100:103], v[198:201], v[48:51]
	v_mfma_f32_16x16x32_bf16 v[44:47], v[124:127], v[198:201], v[44:47]
	v_mfma_f32_16x16x32_bf16 v[32:35], v[100:103], v[216:219], v[32:35]
	v_mfma_f32_16x16x32_bf16 v[28:31], v[124:127], v[216:219], v[28:31]
	v_mfma_f32_16x16x32_bf16 v[16:19], v[100:103], v[224:227], v[16:19]
	v_mfma_f32_16x16x32_bf16 v[12:15], v[124:127], v[224:227], v[12:15]
	v_mfma_f32_16x16x32_bf16 v[64:67], v[120:123], v[190:193], v[64:67]
	v_mfma_f32_16x16x32_bf16 v[60:63], v[144:147], v[190:193], v[60:63]
	v_mfma_f32_16x16x32_bf16 v[48:51], v[120:123], v[212:215], v[48:51]
	v_mfma_f32_16x16x32_bf16 v[44:47], v[144:147], v[212:215], v[44:47]
	v_mfma_f32_16x16x32_bf16 v[32:35], v[120:123], v[220:223], v[32:35]
	v_mfma_f32_16x16x32_bf16 v[28:31], v[144:147], v[220:223], v[28:31]
	v_mfma_f32_16x16x32_bf16 v[16:19], v[120:123], v[228:231], v[16:19]
	v_mfma_f32_16x16x32_bf16 v[12:15], v[144:147], v[228:231], v[12:15]
	s_setprio 0
	s_setprio 1
	v_mfma_f32_16x16x32_bf16 v[56:59], v[148:151], v[186:189], v[56:59]
	v_mfma_f32_16x16x32_bf16 v[52:55], v[156:159], v[186:189], v[52:55]
	v_mfma_f32_16x16x32_bf16 v[40:43], v[148:151], v[198:201], v[40:43]
	v_mfma_f32_16x16x32_bf16 v[36:39], v[156:159], v[198:201], v[36:39]
	v_mfma_f32_16x16x32_bf16 v[24:27], v[148:151], v[216:219], v[24:27]
	v_mfma_f32_16x16x32_bf16 v[20:23], v[156:159], v[216:219], v[20:23]
	v_mfma_f32_16x16x32_bf16 v[8:11], v[148:151], v[224:227], v[8:11]
	v_mfma_f32_16x16x32_bf16 v[4:7], v[156:159], v[224:227], v[4:7]
	v_mfma_f32_16x16x32_bf16 v[56:59], v[152:155], v[190:193], v[56:59]
	v_mfma_f32_16x16x32_bf16 v[52:55], v[182:185], v[190:193], v[52:55]
	v_mfma_f32_16x16x32_bf16 v[40:43], v[152:155], v[212:215], v[40:43]
	v_mfma_f32_16x16x32_bf16 v[36:39], v[182:185], v[212:215], v[36:39]
	v_mfma_f32_16x16x32_bf16 v[24:27], v[152:155], v[220:223], v[24:27]
	v_mfma_f32_16x16x32_bf16 v[20:23], v[182:185], v[220:223], v[20:23]
	v_mfma_f32_16x16x32_bf16 v[8:11], v[152:155], v[228:231], v[8:11]
	v_mfma_f32_16x16x32_bf16 v[4:7], v[182:185], v[228:231], v[4:7]
	s_setprio 0
	s_barrier
	s_add_i32 s57, s57, 2
	s_add_u32 s47, s47, 0x100
	s_addc_u32 s56, s56, 0
	s_cmp_gt_u32 s57, 61
	s_mov_b64 s[4:5], s[0:1]
	s_cbranch_scc0 .LBB0_590
	s_and_b64 vcc, exec, s[20:21]
	s_cbranch_vccz .LBB0_593
	s_barrier

; #define PG8_STAGE(bufoff, gbase, voff) do { _Pragma("unroll") for (int _i = 0; _i < 2; ++_i) \
;         __builtin_amdgcn_global_load_lds((const unsigned*)((const char*)(gbase) + (voff)[_i]), (PG8_LAS unsigned*)(lds + (bufoff) + ldsw + _i * 8192), 16, 0, 0); } while (0)
; #define PG8_LDA(dst, b, h) do { _Pragma("unroll") for (int m = 0; m < 4; ++m) _Pragma("unroll") for (int k = 0; k < 2; ++k) dst[m][k] = *(const PG8_LAS bf16x8*)(lds + PG8_SA(b, h) + aoff + m * 2048 + k * 1024); } while (0)
; #define PG8_LDB(dst, b, h) do { _Pragma("unroll") for (int n = 0; n < 2; ++n) _Pragma("unroll") for (int k = 0; k < 2; ++k) dst[n][k] = *(const PG8_LAS bf16x8*)(lds + PG8_SB(b, h) + boff + n * 2048 + k * 1024); } while (0)
; #define PG8_WAIT_V(n) asm volatile("s_waitcnt vmcnt(" #n ")" ::: "memory")
; #define PG8_WAIT_L(n) asm volatile("s_waitcnt lgkmcnt(" #n ")" ::: "memory")
; #define PG8_BAR __builtin_amdgcn_s_barrier()
; #define PG8_SCHED __builtin_amdgcn_sched_barrier(0)
; template <class Epi, class Sched, bool ALIGN_EPI = false, bool SP2 = false>
; __device__ __forceinline__ void gemm_phase(PG8_LAS unsigned char* lds, const Gemm g, const Sched& S, const Epi& E, int wave_s) {
;     ...
;         const bool has_next = S.next(ui + 1, nxt);
;         const char* nA = has_next ? (const char*)g.A + (size_t)nxt.pm * tstepA : cA; const char* nB = has_next ? (const char*)g.Bt + (size_t)nxt.pn * tstepB : cB;
;         for (int t = 0; t < nt; t += 2) {
;             const bool last = (t == nt - 2);
;             const char* a1 = cA + (size_t)(t + 1) * kstep;
;             const char* a2 = last ? nA : cA + (size_t)(t + 2) * kstep; const char* b2 = last ? nB : cB + (size_t)(t + 2) * kstep;
;             const char* a3 = a2 + kstep; const char* b3 = b2 + kstep;
;             if (last && has_next) S.a_ready(nxt);
;             if constexpr (SP2) {
;             PG8_LDB(B0, 0, 0); PG8_LDB(B1, 0, 1); PG8_SCHED; PG8_LDA(At, 0, 0); PG8_STAGE(PG8_SA(1, 1), a1 + hstepA, voffA);
;             PG8_WAIT_V(8); PG8_WAIT_L(0); PG8_BAR; PG8_MMA(0, 0, At, B0); PG8_MMA(0, 1, At, B1); PG8_BAR; PG8_SCHED;
;     ...
;         for (int a = 0; a < 2; ++a)
; #pragma unroll
;             for (int b = 0; b < 2; ++b)
; #pragma unroll
;                 for (int m = 0; m < 4; ++m)
; #pragma unroll
;                     for (int n = 0; n < 2; ++n) acc[a][b][m][n] = (f32x4){0.f, 0.f, 0.f, 0.f};
.LBB0_660:
	s_ashr_i32 s7, s6, 31
	s_lshl_b64 s[16:17], s[6:7], 20
	s_add_u32 s22, s2, s16
	s_addc_u32 s23, s30, s17
	s_and_b64 s[16:17], s[36:37], exec
	s_cselect_b32 s7, s23, s27
	s_cselect_b32 s57, s22, s26
	s_ashr_i32 s5, s4, 31
	s_lshl_b64 s[16:17], s[4:5], 20
	s_add_u32 s16, s44, s16
	s_addc_u32 s17, s45, s17
	s_and_b64 s[42:43], s[36:37], exec
	s_cselect_b32 s5, s17, s19
	s_cselect_b32 s58, s16, s18
	s_add_u32 s59, s18, 0x100
	s_addc_u32 s66, s19, 0
	s_add_u32 s18, s26, 0x80080
	s_addc_u32 s19, s27, 0
	s_mov_b32 s67, -2
	v_mov_b64_e32 v[4:5], 0
	v_mov_b64_e32 v[6:7], 0
	v_mov_b64_e32 v[8:9], 0
	v_mov_b64_e32 v[10:11], 0
	v_mov_b64_e32 v[12:13], 0
	v_mov_b64_e32 v[14:15], 0
	v_mov_b64_e32 v[16:17], 0
	v_mov_b64_e32 v[18:19], 0
	v_mov_b64_e32 v[20:21], 0
	v_mov_b64_e32 v[22:23], 0
	v_mov_b64_e32 v[24:25], 0
	v_mov_b64_e32 v[26:27], 0
	v_mov_b64_e32 v[28:29], 0
	v_mov_b64_e32 v[30:31], 0
	v_mov_b64_e32 v[32:33], 0
	v_mov_b64_e32 v[34:35], 0
	v_mov_b64_e32 v[36:37], 0
	v_mov_b64_e32 v[38:39], 0
	v_mov_b64_e32 v[40:41], 0
	v_mov_b64_e32 v[42:43], 0
	v_mov_b64_e32 v[44:45], 0
	v_mov_b64_e32 v[46:47], 0
	v_mov_b64_e32 v[48:49], 0
	v_mov_b64_e32 v[50:51], 0
	v_mov_b64_e32 v[52:53], 0
	v_mov_b64_e32 v[54:55], 0
	v_mov_b64_e32 v[56:57], 0
	v_mov_b64_e32 v[58:59], 0
	v_mov_b64_e32 v[60:61], 0
	v_mov_b64_e32 v[62:63], 0
	v_mov_b64_e32 v[64:65], 0
	v_mov_b64_e32 v[66:67], 0
	v_mov_b64_e32 v[68:69], 0
	v_mov_b64_e32 v[70:71], 0
	v_mov_b64_e32 v[72:73], 0
	v_mov_b64_e32 v[74:75], 0
	v_mov_b64_e32 v[76:77], 0
	v_mov_b64_e32 v[78:79], 0
	v_mov_b64_e32 v[80:81], 0
	v_mov_b64_e32 v[82:83], 0
	v_mov_b64_e32 v[84:85], 0
	v_mov_b64_e32 v[86:87], 0
	v_mov_b64_e32 v[88:89], 0
	v_mov_b64_e32 v[90:91], 0
	v_mov_b64_e32 v[92:93], 0
	v_mov_b64_e32 v[94:95], 0
	v_mov_b64_e32 v[96:97], 0
	v_mov_b64_e32 v[98:99], 0
	v_mov_b64_e32 v[100:101], 0
	v_mov_b64_e32 v[102:103], 0
	v_mov_b64_e32 v[104:105], 0
	v_mov_b64_e32 v[106:107], 0
	v_mov_b64_e32 v[124:125], 0
	v_mov_b64_e32 v[126:127], 0
	v_mov_b64_e32 v[128:129], 0
	v_mov_b64_e32 v[130:131], 0
	v_mov_b64_e32 v[132:133], 0
	v_mov_b64_e32 v[134:135], 0
	v_mov_b64_e32 v[136:137], 0
	v_mov_b64_e32 v[138:139], 0
	v_mov_b64_e32 v[140:141], 0
	v_mov_b64_e32 v[142:143], 0
	v_mov_b64_e32 v[144:145], 0
	v_mov_b64_e32 v[146:147], 0
.LBB0_661:
	s_nop 0
	s_add_u32 s26, s18, 0xfff80080
	s_addc_u32 s27, s19, -1
	s_add_i32 s74, 0, 0x10000
	s_cmp_eq_u32 s67, 28
	s_cselect_b32 s43, s7, s27
	s_cselect_b32 s42, s57, s26
	s_cselect_b32 s27, s5, s66
	s_cselect_b32 s26, s58, s59
	s_add_i32 s76, 0, 0x14000
	s_waitcnt vmcnt(0) lgkmcnt(0)
	v_add_u32_e32 v120, s74, v211
	v_add_u32_e32 v160, s76, v211
	ds_read_b128 v[108:111], v120
	ds_read_b128 v[112:115], v120 offset:1024
	ds_read_b128 v[116:119], v120 offset:2048
	ds_read_b128 v[120:123], v120 offset:3072
	ds_read_b128 v[148:151], v160
	ds_read_b128 v[152:155], v160 offset:1024
	ds_read_b128 v[156:159], v160 offset:2048
	ds_read_b128 v[160:163], v160 offset:3072
	s_add_i32 m0, s47, 0xc000
	ds_read_b128 v[164:167], v213
	ds_read_b128 v[190:193], v213 offset:1024
	ds_read_b128 v[194:197], v213 offset:2048
	ds_read_b128 v[198:201], v213 offset:3072
	ds_read_b128 v[214:217], v213 offset:4096
	ds_read_b128 v[218:221], v213 offset:5120
	ds_read_b128 v[222:225], v213 offset:6144
	ds_read_b128 v[226:229], v213 offset:7168
	global_load_lds_dwordx4 v188, s[18:19]
	s_add_i32 m0, s47, 0xe000
	s_nop 0
	global_load_lds_dwordx4 v186, s[18:19]
	s_waitcnt vmcnt(8)
	s_waitcnt lgkmcnt(0)
	s_barrier
	s_setprio 1
	s_waitcnt lgkmcnt(0)
	v_mfma_f32_16x16x32_bf16 v[144:147], v[108:111], v[164:167], v[144:147]
	v_mfma_f32_16x16x32_bf16 v[140:143], v[116:119], v[164:167], v[140:143]
	v_mfma_f32_16x16x32_bf16 v[136:139], v[108:111], v[194:197], v[136:139]
	v_mfma_f32_16x16x32_bf16 v[132:135], v[116:119], v[194:197], v[132:135]
	v_mfma_f32_16x16x32_bf16 v[96:99], v[108:111], v[214:217], v[96:99]
	v_mfma_f32_16x16x32_bf16 v[92:95], v[116:119], v[214:217], v[92:95]
	v_mfma_f32_16x16x32_bf16 v[80:83], v[108:111], v[222:225], v[80:83]
	v_mfma_f32_16x16x32_bf16 v[76:79], v[116:119], v[222:225], v[76:79]
	v_mfma_f32_16x16x32_bf16 v[144:147], v[112:115], v[190:193], v[144:147]
	v_mfma_f32_16x16x32_bf16 v[140:143], v[120:123], v[190:193], v[140:143]
	v_mfma_f32_16x16x32_bf16 v[136:139], v[112:115], v[198:201], v[136:139]
	v_mfma_f32_16x16x32_bf16 v[132:135], v[120:123], v[198:201], v[132:135]
	v_mfma_f32_16x16x32_bf16 v[96:99], v[112:115], v[218:221], v[96:99]
	v_mfma_f32_16x16x32_bf16 v[92:95], v[120:123], v[218:221], v[92:95]
	v_mfma_f32_16x16x32_bf16 v[80:83], v[112:115], v[226:229], v[80:83]
	v_mfma_f32_16x16x32_bf16 v[76:79], v[120:123], v[226:229], v[76:79]
	s_setprio 0
	s_setprio 1
	v_mfma_f32_16x16x32_bf16 v[128:131], v[148:151], v[164:167], v[128:131]
	v_mfma_f32_16x16x32_bf16 v[124:127], v[156:159], v[164:167], v[124:127]
	v_mfma_f32_16x16x32_bf16 v[104:107], v[148:151], v[194:197], v[104:107]
	v_mfma_f32_16x16x32_bf16 v[100:103], v[156:159], v[194:197], v[100:103]
	v_mfma_f32_16x16x32_bf16 v[88:91], v[148:151], v[214:217], v[88:91]
	v_mfma_f32_16x16x32_bf16 v[84:87], v[156:159], v[214:217], v[84:87]
	v_mfma_f32_16x16x32_bf16 v[72:75], v[148:151], v[222:225], v[72:75]
	v_mfma_f32_16x16x32_bf16 v[68:71], v[156:159], v[222:225], v[68:71]
	v_mfma_f32_16x16x32_bf16 v[128:131], v[152:155], v[190:193], v[128:131]
	v_mfma_f32_16x16x32_bf16 v[124:127], v[160:163], v[190:193], v[124:127]
	v_mfma_f32_16x16x32_bf16 v[104:107], v[152:155], v[198:201], v[104:107]
	v_mfma_f32_16x16x32_bf16 v[100:103], v[160:163], v[198:201], v[100:103]
	v_mfma_f32_16x16x32_bf16 v[88:91], v[152:155], v[218:221], v[88:91]
	v_mfma_f32_16x16x32_bf16 v[84:87], v[160:163], v[218:221], v[84:87]
	v_mfma_f32_16x16x32_bf16 v[72:75], v[152:155], v[226:229], v[72:75]
	v_mfma_f32_16x16x32_bf16 v[68:71], v[160:163], v[226:229], v[68:71]
	s_setprio 0
	s_barrier
; #define PG8_STAGE(bufoff, gbase, voff) do { _Pragma("unroll") for (int _i = 0; _i < 2; ++_i) \
;         __builtin_amdgcn_global_load_lds((const unsigned*)((const char*)(gbase) + (voff)[_i]), (PG8_LAS unsigned*)(lds + (bufoff) + ldsw + _i * 8192), 16, 0, 0); } while (0)
; #define PG8_LDA(dst, b, h) do { _Pragma("unroll") for (int m = 0; m < 4; ++m) _Pragma("unroll") for (int k = 0; k < 2; ++k) dst[m][k] = *(const PG8_LAS bf16x8*)(lds + PG8_SA(b, h) + aoff + m * 2048 + k * 1024); } while (0)
; #define PG8_LDB(dst, b, h) do { _Pragma("unroll") for (int n = 0; n < 2; ++n) _Pragma("unroll") for (int k = 0; k < 2; ++k) dst[n][k] = *(const PG8_LAS bf16x8*)(lds + PG8_SB(b, h) + boff + n * 2048 + k * 1024); } while (0)
; #define PG8_MMA(ai, bj, At, Bt) do { __builtin_amdgcn_s_setprio(1); _Pragma("unroll") for (int m = 0; m < 4; ++m) _Pragma("unroll") for (int n = 0; n < 2; ++n) _Pragma("unroll") for (int k = 0; k < 2; ++k) \
;         acc[ai][bj][m][n] = __builtin_amdgcn_mfma_f32_16x16x32_bf16(Bt[n][k], At[m][k], acc[ai][bj][m][n], 0, 0, 0); __builtin_amdgcn_s_setprio(0); } while (0)
; #define PG8_WAIT_V(n) asm volatile("s_waitcnt vmcnt(" #n ")" ::: "memory")
; #define PG8_WAIT_L(n) asm volatile("s_waitcnt lgkmcnt(" #n ")" ::: "memory")
; #define PG8_BAR __builtin_amdgcn_s_barrier()
; #define PG8_SCHED __builtin_amdgcn_sched_barrier(0)
; template <class Epi, class Sched, bool ALIGN_EPI = false, bool SP2 = false>
; __device__ __forceinline__ void gemm_phase(PG8_LAS unsigned char* lds, const Gemm g, const Sched& S, const Epi& E, int wave_s) {
;     ...
;             PG8_LDA(At, 0, 1); PG8_STAGE(PG8_SB(0, 0), b2, voffB); PG8_STAGE(PG8_SB(0, 1), b2 + hstepB, voffB); PG8_STAGE(PG8_SA(0, 0), a2, voffA);
;             PG8_WAIT_V(8); PG8_WAIT_L(0); PG8_BAR; PG8_MMA(1, 0, At, B0); PG8_MMA(1, 1, At, B1); PG8_BAR; PG8_SCHED;
;             PG8_LDB(B0, 1, 0); PG8_LDB(B1, 1, 1); PG8_SCHED; PG8_LDA(At, 1, 0); PG8_STAGE(PG8_SA(0, 1), a2 + hstepA, voffA);
;             PG8_WAIT_V(8); PG8_WAIT_L(0); PG8_BAR; PG8_MMA(0, 0, At, B0); PG8_MMA(0, 1, At, B1); PG8_BAR; PG8_SCHED;
	s_add_i32 s74, s74, s46
	s_add_u32 s98, s26, s60
	s_addc_u32 s99, s27, s61
	s_mov_b32 m0, s74
	ds_read_b128 v[164:167], v213 offset:16384
	ds_read_b128 v[190:193], v213 offset:17408
	ds_read_b128 v[194:197], v213 offset:18432
	ds_read_b128 v[198:201], v213 offset:19456
	ds_read_b128 v[214:217], v213 offset:20480
	ds_read_b128 v[218:221], v213 offset:21504
	ds_read_b128 v[222:225], v213 offset:22528
	ds_read_b128 v[226:229], v213 offset:23552
	global_load_lds_dwordx4 v2, s[26:27]
	s_add_i32 m0, s74, 0x2000
	s_add_u32 s74, s26, 0x80000
	s_addc_u32 s75, s27, 0
	s_add_i32 s76, s76, s46
	global_load_lds_dwordx4 v0, s[26:27]
	s_mov_b32 m0, s76
	s_add_u32 s100, s42, s60
	s_addc_u32 s101, s43, s61
	s_nop 0
	global_load_lds_dwordx4 v2, s[74:75]
	s_add_i32 m0, s76, 0x2000
	s_nop 0
	global_load_lds_dwordx4 v0, s[74:75]
	s_mov_b32 m0, s47
	s_nop 0
	global_load_lds_dwordx4 v184, s[42:43]
	s_mov_b32 m0, s48
	s_nop 0
	global_load_lds_dwordx4 v182, s[42:43]
	s_waitcnt vmcnt(8)
	s_waitcnt lgkmcnt(0)
	s_barrier
	s_setprio 1
	s_waitcnt lgkmcnt(0)
	v_mfma_f32_16x16x32_bf16 v[64:67], v[108:111], v[164:167], v[64:67]
	v_mfma_f32_16x16x32_bf16 v[60:63], v[116:119], v[164:167], v[60:63]
	v_mfma_f32_16x16x32_bf16 v[48:51], v[108:111], v[194:197], v[48:51]
	v_mfma_f32_16x16x32_bf16 v[44:47], v[116:119], v[194:197], v[44:47]
	v_mfma_f32_16x16x32_bf16 v[32:35], v[108:111], v[214:217], v[32:35]
	v_mfma_f32_16x16x32_bf16 v[28:31], v[116:119], v[214:217], v[28:31]
	v_mfma_f32_16x16x32_bf16 v[16:19], v[108:111], v[222:225], v[16:19]
	v_mfma_f32_16x16x32_bf16 v[12:15], v[116:119], v[222:225], v[12:15]
	v_mfma_f32_16x16x32_bf16 v[64:67], v[112:115], v[190:193], v[64:67]
	v_mfma_f32_16x16x32_bf16 v[60:63], v[120:123], v[190:193], v[60:63]
	v_mfma_f32_16x16x32_bf16 v[48:51], v[112:115], v[198:201], v[48:51]
	v_mfma_f32_16x16x32_bf16 v[44:47], v[120:123], v[198:201], v[44:47]
	v_mfma_f32_16x16x32_bf16 v[32:35], v[112:115], v[218:221], v[32:35]
	v_mfma_f32_16x16x32_bf16 v[28:31], v[120:123], v[218:221], v[28:31]
	v_mfma_f32_16x16x32_bf16 v[16:19], v[112:115], v[226:229], v[16:19]
	v_mfma_f32_16x16x32_bf16 v[12:15], v[120:123], v[226:229], v[12:15]
	s_setprio 0
	s_setprio 1
	v_mfma_f32_16x16x32_bf16 v[56:59], v[148:151], v[164:167], v[56:59]
	v_mfma_f32_16x16x32_bf16 v[52:55], v[156:159], v[164:167], v[52:55]
	v_mfma_f32_16x16x32_bf16 v[40:43], v[148:151], v[194:197], v[40:43]
	v_mfma_f32_16x16x32_bf16 v[36:39], v[156:159], v[194:197], v[36:39]
	v_mfma_f32_16x16x32_bf16 v[24:27], v[148:151], v[214:217], v[24:27]
	v_mfma_f32_16x16x32_bf16 v[20:23], v[156:159], v[214:217], v[20:23]
	v_mfma_f32_16x16x32_bf16 v[8:11], v[148:151], v[222:225], v[8:11]
	v_mfma_f32_16x16x32_bf16 v[4:7], v[156:159], v[222:225], v[4:7]
	v_mfma_f32_16x16x32_bf16 v[56:59], v[152:155], v[190:193], v[56:59]
	v_mfma_f32_16x16x32_bf16 v[52:55], v[160:163], v[190:193], v[52:55]
	v_mfma_f32_16x16x32_bf16 v[40:43], v[152:155], v[198:201], v[40:43]
	v_mfma_f32_16x16x32_bf16 v[36:39], v[160:163], v[198:201], v[36:39]
	v_mfma_f32_16x16x32_bf16 v[24:27], v[152:155], v[218:221], v[24:27]
	v_mfma_f32_16x16x32_bf16 v[20:23], v[160:163], v[218:221], v[20:23]
	v_mfma_f32_16x16x32_bf16 v[8:11], v[152:155], v[226:229], v[8:11]
	v_mfma_f32_16x16x32_bf16 v[4:7], v[160:163], v[226:229], v[4:7]
	s_setprio 0
	s_barrier
	s_nop 0
	s_add_i32 s74, 0, 0x18000
	s_add_i32 s75, 0, 0x1c000
	v_add_u32_e32 v120, s74, v211
	v_add_u32_e32 v160, s75, v211
	ds_read_b128 v[108:111], v120
	ds_read_b128 v[112:115], v120 offset:1024
	ds_read_b128 v[116:119], v120 offset:2048
	ds_read_b128 v[120:123], v120 offset:3072
	ds_read_b128 v[148:151], v160
	ds_read_b128 v[152:155], v160 offset:1024
	ds_read_b128 v[156:159], v160 offset:2048
	ds_read_b128 v[160:163], v160 offset:3072
	s_add_u32 s42, s42, 0x80000
	s_addc_u32 s43, s43, 0
	s_mov_b32 m0, s49
	ds_read_b128 v[164:167], v213 offset:32768
	ds_read_b128 v[190:193], v213 offset:33792
	ds_read_b128 v[194:197], v213 offset:34816
	ds_read_b128 v[198:201], v213 offset:35840
	ds_read_b128 v[214:217], v213 offset:36864
	ds_read_b128 v[218:221], v213 offset:37888
	ds_read_b128 v[222:225], v213 offset:38912
	ds_read_b128 v[226:229], v213 offset:39936
	global_load_lds_dwordx4 v184, s[42:43]
	s_mov_b32 m0, s50
	s_nop 0
	global_load_lds_dwordx4 v182, s[42:43]
	s_waitcnt vmcnt(8)
	s_waitcnt lgkmcnt(0)
	s_barrier
; #define PG8_STAGE(bufoff, gbase, voff) do { _Pragma("unroll") for (int _i = 0; _i < 2; ++_i) \
;         __builtin_amdgcn_global_load_lds((const unsigned*)((const char*)(gbase) + (voff)[_i]), (PG8_LAS unsigned*)(lds + (bufoff) + ldsw + _i * 8192), 16, 0, 0); } while (0)
; #define PG8_LDA(dst, b, h) do { _Pragma("unroll") for (int m = 0; m < 4; ++m) _Pragma("unroll") for (int k = 0; k < 2; ++k) dst[m][k] = *(const PG8_LAS bf16x8*)(lds + PG8_SA(b, h) + aoff + m * 2048 + k * 1024); } while (0)
; #define PG8_WAIT_V(n) asm volatile("s_waitcnt vmcnt(" #n ")" ::: "memory")
; #define PG8_WAIT_L(n) asm volatile("s_waitcnt lgkmcnt(" #n ")" ::: "memory")
; #define PG8_BAR __builtin_amdgcn_s_barrier()
; template <class Epi, class Sched, bool ALIGN_EPI = false, bool SP2 = false>
; __device__ __forceinline__ void gemm_phase(PG8_LAS unsigned char* lds, const Gemm g, const Sched& S, const Epi& E, int wave_s) {
;     ...
;         for (int t = 0; t < nt; t += 2) {
;             const bool last = (t == nt - 2);
;             const char* a1 = cA + (size_t)(t + 1) * kstep;
;             const char* a2 = last ? nA : cA + (size_t)(t + 2) * kstep; const char* b2 = last ? nB : cB + (size_t)(t + 2) * kstep;
;             const char* a3 = a2 + kstep; const char* b3 = b2 + kstep;
;             if (last && has_next) S.a_ready(nxt);
;             if constexpr (SP2) {
;             PG8_LDB(B0, 0, 0); PG8_LDB(B1, 0, 1); PG8_SCHED; PG8_LDA(At, 0, 0); PG8_STAGE(PG8_SA(1, 1), a1 + hstepA, voffA);
;             PG8_WAIT_V(8); PG8_WAIT_L(0); PG8_BAR; PG8_MMA(0, 0, At, B0); PG8_MMA(0, 1, At, B1); PG8_BAR; PG8_SCHED;
;             PG8_LDA(At, 0, 1); PG8_STAGE(PG8_SB(0, 0), b2, voffB); PG8_STAGE(PG8_SB(0, 1), b2 + hstepB, voffB); PG8_STAGE(PG8_SA(0, 0), a2, voffA);
;             PG8_WAIT_V(8); PG8_WAIT_L(0); PG8_BAR; PG8_MMA(1, 0, At, B0); PG8_MMA(1, 1, At, B1); PG8_BAR; PG8_SCHED;
;             PG8_LDB(B0, 1, 0); PG8_LDB(B1, 1, 1); PG8_SCHED; PG8_LDA(At, 1, 0); PG8_STAGE(PG8_SA(0, 1), a2 + hstepA, voffA);
;             PG8_WAIT_V(8); PG8_WAIT_L(0); PG8_BAR; PG8_MMA(0, 0, At, B0); PG8_MMA(0, 1, At, B1); PG8_BAR; PG8_SCHED;
;             PG8_LDA(At, 1, 1); PG8_STAGE(PG8_SB(1, 0), b3, voffB); PG8_STAGE(PG8_SB(1, 1), b3 + hstepB, voffB); PG8_STAGE(PG8_SA(1, 0), a3, voffA);
;             PG8_WAIT_V(8); PG8_WAIT_L(0); PG8_BAR; PG8_MMA(1, 0, At, B0); PG8_MMA(1, 1, At, B1); PG8_BAR; PG8_SCHED;
	s_setprio 1
	s_waitcnt lgkmcnt(0)
	v_mfma_f32_16x16x32_bf16 v[144:147], v[108:111], v[164:167], v[144:147]
	v_mfma_f32_16x16x32_bf16 v[140:143], v[116:119], v[164:167], v[140:143]
	v_mfma_f32_16x16x32_bf16 v[136:139], v[108:111], v[194:197], v[136:139]
	v_mfma_f32_16x16x32_bf16 v[132:135], v[116:119], v[194:197], v[132:135]
	v_mfma_f32_16x16x32_bf16 v[96:99], v[108:111], v[214:217], v[96:99]
	v_mfma_f32_16x16x32_bf16 v[92:95], v[116:119], v[214:217], v[92:95]
	v_mfma_f32_16x16x32_bf16 v[80:83], v[108:111], v[222:225], v[80:83]
	v_mfma_f32_16x16x32_bf16 v[76:79], v[116:119], v[222:225], v[76:79]
	v_mfma_f32_16x16x32_bf16 v[144:147], v[112:115], v[190:193], v[144:147]
	v_mfma_f32_16x16x32_bf16 v[140:143], v[120:123], v[190:193], v[140:143]
	v_mfma_f32_16x16x32_bf16 v[136:139], v[112:115], v[198:201], v[136:139]
	v_mfma_f32_16x16x32_bf16 v[132:135], v[120:123], v[198:201], v[132:135]
	v_mfma_f32_16x16x32_bf16 v[96:99], v[112:115], v[218:221], v[96:99]
	v_mfma_f32_16x16x32_bf16 v[92:95], v[120:123], v[218:221], v[92:95]
	v_mfma_f32_16x16x32_bf16 v[80:83], v[112:115], v[226:229], v[80:83]
	v_mfma_f32_16x16x32_bf16 v[76:79], v[120:123], v[226:229], v[76:79]
	s_setprio 0
	s_setprio 1
	v_mfma_f32_16x16x32_bf16 v[128:131], v[148:151], v[164:167], v[128:131]
	v_mfma_f32_16x16x32_bf16 v[124:127], v[156:159], v[164:167], v[124:127]
	v_mfma_f32_16x16x32_bf16 v[104:107], v[148:151], v[194:197], v[104:107]
	v_mfma_f32_16x16x32_bf16 v[100:103], v[156:159], v[194:197], v[100:103]
	v_mfma_f32_16x16x32_bf16 v[88:91], v[148:151], v[214:217], v[88:91]
	v_mfma_f32_16x16x32_bf16 v[84:87], v[156:159], v[214:217], v[84:87]
	v_mfma_f32_16x16x32_bf16 v[72:75], v[148:151], v[222:225], v[72:75]
	v_mfma_f32_16x16x32_bf16 v[68:71], v[156:159], v[222:225], v[68:71]
	v_mfma_f32_16x16x32_bf16 v[128:131], v[152:155], v[190:193], v[128:131]
	v_mfma_f32_16x16x32_bf16 v[124:127], v[160:163], v[190:193], v[124:127]
	v_mfma_f32_16x16x32_bf16 v[104:107], v[152:155], v[198:201], v[104:107]
	v_mfma_f32_16x16x32_bf16 v[100:103], v[160:163], v[198:201], v[100:103]
	v_mfma_f32_16x16x32_bf16 v[88:91], v[152:155], v[218:221], v[88:91]
	v_mfma_f32_16x16x32_bf16 v[84:87], v[160:163], v[218:221], v[84:87]
	v_mfma_f32_16x16x32_bf16 v[72:75], v[152:155], v[226:229], v[72:75]
	v_mfma_f32_16x16x32_bf16 v[68:71], v[160:163], v[226:229], v[68:71]
	s_setprio 0
	s_barrier
	s_add_i32 s42, s74, s46
	s_mov_b32 m0, s42
	ds_read_b128 v[164:167], v213 offset:49152
	ds_read_b128 v[190:193], v213 offset:50176
	ds_read_b128 v[194:197], v213 offset:51200
	ds_read_b128 v[198:201], v213 offset:52224
	ds_read_b128 v[214:217], v213 offset:53248
	ds_read_b128 v[218:221], v213 offset:54272
	ds_read_b128 v[222:225], v213 offset:55296
	ds_read_b128 v[226:229], v213 offset:56320
	global_load_lds_dwordx4 v2, s[98:99]
	s_add_i32 m0, s42, 0x2000
	s_add_u32 s26, s26, 0x80080
	s_addc_u32 s27, s27, 0
	s_add_i32 s42, s75, s46
	global_load_lds_dwordx4 v0, s[98:99]
	s_mov_b32 m0, s42
	s_nop 0
	global_load_lds_dwordx4 v2, s[26:27]
	s_add_i32 m0, s42, 0x2000
	s_nop 0
	global_load_lds_dwordx4 v0, s[26:27]
	s_mov_b32 m0, s54
	s_nop 0
	global_load_lds_dwordx4 v184, s[100:101]
	s_mov_b32 m0, s55
	s_nop 0
	global_load_lds_dwordx4 v182, s[100:101]
	s_waitcnt vmcnt(8)
	s_waitcnt lgkmcnt(0)
	s_barrier
	s_setprio 1
	s_waitcnt lgkmcnt(0)
	v_mfma_f32_16x16x32_bf16 v[64:67], v[108:111], v[164:167], v[64:67]
	v_mfma_f32_16x16x32_bf16 v[60:63], v[116:119], v[164:167], v[60:63]
	v_mfma_f32_16x16x32_bf16 v[48:51], v[108:111], v[194:197], v[48:51]
	v_mfma_f32_16x16x32_bf16 v[44:47], v[116:119], v[194:197], v[44:47]
	v_mfma_f32_16x16x32_bf16 v[32:35], v[108:111], v[214:217], v[32:35]
	v_mfma_f32_16x16x32_bf16 v[28:31], v[116:119], v[214:217], v[28:31]
	v_mfma_f32_16x16x32_bf16 v[16:19], v[108:111], v[222:225], v[16:19]
	v_mfma_f32_16x16x32_bf16 v[12:15], v[116:119], v[222:225], v[12:15]
	v_mfma_f32_16x16x32_bf16 v[64:67], v[112:115], v[190:193], v[64:67]
	v_mfma_f32_16x16x32_bf16 v[60:63], v[120:123], v[190:193], v[60:63]
	v_mfma_f32_16x16x32_bf16 v[48:51], v[112:115], v[198:201], v[48:51]
	v_mfma_f32_16x16x32_bf16 v[44:47], v[120:123], v[198:201], v[44:47]
	v_mfma_f32_16x16x32_bf16 v[32:35], v[112:115], v[218:221], v[32:35]
	v_mfma_f32_16x16x32_bf16 v[28:31], v[120:123], v[218:221], v[28:31]
	v_mfma_f32_16x16x32_bf16 v[16:19], v[112:115], v[226:229], v[16:19]
	v_mfma_f32_16x16x32_bf16 v[12:15], v[120:123], v[226:229], v[12:15]
	s_setprio 0
	s_setprio 1
	v_mfma_f32_16x16x32_bf16 v[56:59], v[148:151], v[164:167], v[56:59]
	v_mfma_f32_16x16x32_bf16 v[52:55], v[156:159], v[164:167], v[52:55]
	v_mfma_f32_16x16x32_bf16 v[40:43], v[148:151], v[194:197], v[40:43]
	v_mfma_f32_16x16x32_bf16 v[36:39], v[156:159], v[194:197], v[36:39]
	v_mfma_f32_16x16x32_bf16 v[24:27], v[148:151], v[214:217], v[24:27]
	v_mfma_f32_16x16x32_bf16 v[20:23], v[156:159], v[214:217], v[20:23]
	v_mfma_f32_16x16x32_bf16 v[8:11], v[148:151], v[222:225], v[8:11]
	v_mfma_f32_16x16x32_bf16 v[4:7], v[156:159], v[222:225], v[4:7]
	v_mfma_f32_16x16x32_bf16 v[56:59], v[152:155], v[190:193], v[56:59]
	v_mfma_f32_16x16x32_bf16 v[52:55], v[160:163], v[190:193], v[52:55]
	v_mfma_f32_16x16x32_bf16 v[40:43], v[152:155], v[198:201], v[40:43]
	v_mfma_f32_16x16x32_bf16 v[36:39], v[160:163], v[198:201], v[36:39]
	v_mfma_f32_16x16x32_bf16 v[24:27], v[152:155], v[218:221], v[24:27]
	v_mfma_f32_16x16x32_bf16 v[20:23], v[160:163], v[218:221], v[20:23]
	v_mfma_f32_16x16x32_bf16 v[8:11], v[152:155], v[226:229], v[8:11]
	v_mfma_f32_16x16x32_bf16 v[4:7], v[160:163], v[226:229], v[4:7]
	s_setprio 0
	s_barrier
	s_add_i32 s67, s67, 2
	s_add_u32 s59, s59, 0x100
	s_addc_u32 s66, s66, 0
	s_add_u32 s18, s18, 0x100
	s_addc_u32 s19, s19, 0
	s_cmp_gt_u32 s67, 29
	s_cbranch_scc0 .LBB0_661
	s_and_b64 vcc, exec, s[38:39]
	s_cbranch_vccz .LBB0_664
	s_barrier

; #define PG8_STAGE(bufoff, gbase, voff) do { _Pragma("unroll") for (int _i = 0; _i < 2; ++_i) \
;         __builtin_amdgcn_global_load_lds((const unsigned*)((const char*)(gbase) + (voff)[_i]), (PG8_LAS unsigned*)(lds + (bufoff) + ldsw + _i * 8192), 16, 0, 0); } while (0)
; #define PG8_LDA(dst, b, h) do { _Pragma("unroll") for (int m = 0; m < 4; ++m) _Pragma("unroll") for (int k = 0; k < 2; ++k) dst[m][k] = *(const PG8_LAS bf16x8*)(lds + PG8_SA(b, h) + aoff + m * 2048 + k * 1024); } while (0)
; #define PG8_LDB(dst, b, h) do { _Pragma("unroll") for (int n = 0; n < 2; ++n) _Pragma("unroll") for (int k = 0; k < 2; ++k) dst[n][k] = *(const PG8_LAS bf16x8*)(lds + PG8_SB(b, h) + boff + n * 2048 + k * 1024); } while (0)
; #define PG8_WAIT_V(n) asm volatile("s_waitcnt vmcnt(" #n ")" ::: "memory")
; #define PG8_WAIT_L(n) asm volatile("s_waitcnt lgkmcnt(" #n ")" ::: "memory")
; #define PG8_BAR __builtin_amdgcn_s_barrier()
; #define PG8_SCHED __builtin_amdgcn_sched_barrier(0)
; template <class Epi, class Sched, bool ALIGN_EPI = false, bool SP2 = false>
; __device__ __forceinline__ void gemm_phase(PG8_LAS unsigned char* lds, const Gemm g, const Sched& S, const Epi& E, int wave_s) {
;     ...
;         const bool has_next = S.next(ui + 1, nxt);
;         const char* nA = has_next ? (const char*)g.A + (size_t)nxt.pm * tstepA : cA; const char* nB = has_next ? (const char*)g.Bt + (size_t)nxt.pn * tstepB : cB;
;         for (int t = 0; t < nt; t += 2) {
;             const bool last = (t == nt - 2);
;             const char* a1 = cA + (size_t)(t + 1) * kstep;
;             const char* a2 = last ? nA : cA + (size_t)(t + 2) * kstep; const char* b2 = last ? nB : cB + (size_t)(t + 2) * kstep;
;             const char* a3 = a2 + kstep; const char* b3 = b2 + kstep;
;             if (last && has_next) S.a_ready(nxt);
;             if constexpr (SP2) {
;             PG8_LDB(B0, 0, 0); PG8_LDB(B1, 0, 1); PG8_SCHED; PG8_LDA(At, 0, 0); PG8_STAGE(PG8_SA(1, 1), a1 + hstepA, voffA);
;             PG8_WAIT_V(8); PG8_WAIT_L(0); PG8_BAR; PG8_MMA(0, 0, At, B0); PG8_MMA(0, 1, At, B1); PG8_BAR; PG8_SCHED;
;     ...
;         for (int a = 0; a < 2; ++a)
; #pragma unroll
;             for (int b = 0; b < 2; ++b)
; #pragma unroll
;                 for (int m = 0; m < 4; ++m)
; #pragma unroll
;                     for (int n = 0; n < 2; ++n) acc[a][b][m][n] = (f32x4){0.f, 0.f, 0.f, 0.f};
.LBB0_789:
	s_ashr_i32 s21, s20, 31
	s_lshl_b64 s[22:23], s[20:21], 20
	s_add_u32 s22, s2, s22
	s_addc_u32 s23, s30, s23
	s_and_b64 s[24:25], s[36:37], exec
	s_cselect_b32 s21, s23, s27
	s_cselect_b32 s51, s22, s26
	s_ashr_i32 s17, s16, 31
	s_lshl_b64 s[24:25], s[16:17], 20
	s_add_u32 s24, s40, s24
	s_addc_u32 s25, s41, s25
	s_and_b64 s[38:39], s[36:37], exec
	s_cselect_b32 s17, s25, s19
	s_cselect_b32 s52, s24, s18
	s_add_u32 s53, s18, 0x100
	s_addc_u32 s54, s19, 0
	s_add_u32 s18, s26, 0x80080
	s_addc_u32 s19, s27, 0
	s_mov_b32 s55, -2
	s_waitcnt lgkmcnt(0)
	s_nop 0
	s_nop 0
	s_nop 0
	s_nop 0
	s_nop 0
	s_nop 0
	s_nop 0
	s_nop 0
	v_mov_b64_e32 v[4:5], 0
	v_mov_b64_e32 v[6:7], 0
	v_mov_b64_e32 v[8:9], 0
	v_mov_b64_e32 v[10:11], 0
	v_mov_b64_e32 v[12:13], 0
	v_mov_b64_e32 v[14:15], 0
	v_mov_b64_e32 v[16:17], 0
	v_mov_b64_e32 v[18:19], 0
	v_mov_b64_e32 v[20:21], 0
	v_mov_b64_e32 v[22:23], 0
	v_mov_b64_e32 v[24:25], 0
	v_mov_b64_e32 v[26:27], 0
	v_mov_b64_e32 v[28:29], 0
	v_mov_b64_e32 v[30:31], 0
	v_mov_b64_e32 v[32:33], 0
	v_mov_b64_e32 v[34:35], 0
	v_mov_b64_e32 v[36:37], 0
	v_mov_b64_e32 v[38:39], 0
	v_mov_b64_e32 v[40:41], 0
	v_mov_b64_e32 v[42:43], 0
	v_mov_b64_e32 v[44:45], 0
	v_mov_b64_e32 v[46:47], 0
	v_mov_b64_e32 v[48:49], 0
	v_mov_b64_e32 v[50:51], 0
	v_mov_b64_e32 v[52:53], 0
	v_mov_b64_e32 v[54:55], 0
	v_mov_b64_e32 v[56:57], 0
	v_mov_b64_e32 v[58:59], 0
	v_mov_b64_e32 v[60:61], 0
	v_mov_b64_e32 v[62:63], 0
	v_mov_b64_e32 v[64:65], 0
	v_mov_b64_e32 v[66:67], 0
	v_mov_b64_e32 v[68:69], 0
	v_mov_b64_e32 v[70:71], 0
	v_mov_b64_e32 v[72:73], 0
	v_mov_b64_e32 v[74:75], 0
	v_mov_b64_e32 v[76:77], 0
	v_mov_b64_e32 v[78:79], 0
	v_mov_b64_e32 v[80:81], 0
	v_mov_b64_e32 v[82:83], 0
	v_mov_b64_e32 v[84:85], 0
	v_mov_b64_e32 v[86:87], 0
	v_mov_b64_e32 v[88:89], 0
	v_mov_b64_e32 v[90:91], 0
	v_mov_b64_e32 v[92:93], 0
	v_mov_b64_e32 v[94:95], 0
	v_mov_b64_e32 v[96:97], 0
	v_mov_b64_e32 v[98:99], 0
	v_mov_b64_e32 v[100:101], 0
	v_mov_b64_e32 v[102:103], 0
	v_mov_b64_e32 v[104:105], 0
	v_mov_b64_e32 v[106:107], 0
	v_mov_b64_e32 v[108:109], 0
	v_mov_b64_e32 v[110:111], 0
	v_mov_b64_e32 v[112:113], 0
	v_mov_b64_e32 v[114:115], 0
	v_mov_b64_e32 v[116:117], 0
	v_mov_b64_e32 v[118:119], 0
	v_mov_b64_e32 v[120:121], 0
	v_mov_b64_e32 v[122:123], 0
	v_mov_b64_e32 v[124:125], 0
	v_mov_b64_e32 v[126:127], 0
	v_mov_b64_e32 v[128:129], 0
	v_mov_b64_e32 v[130:131], 0
.LBB0_790:
	s_add_u32 s26, s18, 0xfff80080
	s_addc_u32 s27, s19, -1
	s_add_i32 s56, 0, 0x10000
	s_cmp_eq_u32 s55, 28
	s_cselect_b32 s39, s21, s27
	s_cselect_b32 s38, s51, s26
	v_add_u32_e32 v140, s56, v143
	s_cselect_b32 s27, s17, s54
	s_cselect_b32 s26, s52, s53
	s_add_i32 s58, 0, 0x14000
	ds_read_b128 v[146:149], v140
	ds_read_b128 v[150:153], v140 offset:1024
	ds_read_b128 v[154:157], v140 offset:2048
	ds_read_b128 v[158:161], v140 offset:3072
	v_add_u32_e32 v140, s58, v143
	ds_read_b128 v[162:165], v140
	ds_read_b128 v[182:185], v140 offset:1024
	ds_read_b128 v[186:189], v140 offset:2048
	ds_read_b128 v[190:193], v140 offset:3072
	s_add_i32 m0, s43, 0xc000
	ds_read_b128 v[194:197], v145
	ds_read_b128 v[198:201], v145 offset:1024
	ds_read_b128 v[212:215], v145 offset:2048
	ds_read_b128 v[216:219], v145 offset:3072
	ds_read_b128 v[220:223], v145 offset:4096
	ds_read_b128 v[224:227], v145 offset:5120
	ds_read_b128 v[228:231], v145 offset:6144
	ds_read_b128 v[232:235], v145 offset:7168
	global_load_lds_dwordx4 v138, s[18:19]
	s_add_i32 m0, s43, 0xe000
	s_nop 0
	global_load_lds_dwordx4 v136, s[18:19]
	s_waitcnt vmcnt(8)
	s_waitcnt lgkmcnt(0)
	s_barrier
	s_setprio 1
	s_waitcnt lgkmcnt(0)
	v_mfma_f32_16x16x32_bf16 v[128:131], v[146:149], v[194:197], v[128:131]
	v_mfma_f32_16x16x32_bf16 v[120:123], v[154:157], v[194:197], v[120:123]
	v_mfma_f32_16x16x32_bf16 v[112:115], v[146:149], v[212:215], v[112:115]
	v_mfma_f32_16x16x32_bf16 v[104:107], v[154:157], v[212:215], v[104:107]
	v_mfma_f32_16x16x32_bf16 v[96:99], v[146:149], v[220:223], v[96:99]
	v_mfma_f32_16x16x32_bf16 v[88:91], v[154:157], v[220:223], v[88:91]
	v_mfma_f32_16x16x32_bf16 v[80:83], v[146:149], v[228:231], v[80:83]
	v_mfma_f32_16x16x32_bf16 v[72:75], v[154:157], v[228:231], v[72:75]
	v_mfma_f32_16x16x32_bf16 v[128:131], v[150:153], v[198:201], v[128:131]
	v_mfma_f32_16x16x32_bf16 v[120:123], v[158:161], v[198:201], v[120:123]
	v_mfma_f32_16x16x32_bf16 v[112:115], v[150:153], v[216:219], v[112:115]
	v_mfma_f32_16x16x32_bf16 v[104:107], v[158:161], v[216:219], v[104:107]
	v_mfma_f32_16x16x32_bf16 v[96:99], v[150:153], v[224:227], v[96:99]
	v_mfma_f32_16x16x32_bf16 v[88:91], v[158:161], v[224:227], v[88:91]
	v_mfma_f32_16x16x32_bf16 v[80:83], v[150:153], v[232:235], v[80:83]
	v_mfma_f32_16x16x32_bf16 v[72:75], v[158:161], v[232:235], v[72:75]
	s_setprio 0
	s_setprio 1
	v_mfma_f32_16x16x32_bf16 v[124:127], v[162:165], v[194:197], v[124:127]
	v_mfma_f32_16x16x32_bf16 v[116:119], v[186:189], v[194:197], v[116:119]
	v_mfma_f32_16x16x32_bf16 v[108:111], v[162:165], v[212:215], v[108:111]
	v_mfma_f32_16x16x32_bf16 v[100:103], v[186:189], v[212:215], v[100:103]
	v_mfma_f32_16x16x32_bf16 v[92:95], v[162:165], v[220:223], v[92:95]
	v_mfma_f32_16x16x32_bf16 v[84:87], v[186:189], v[220:223], v[84:87]
	v_mfma_f32_16x16x32_bf16 v[76:79], v[162:165], v[228:231], v[76:79]
	v_mfma_f32_16x16x32_bf16 v[68:71], v[186:189], v[228:231], v[68:71]
	v_mfma_f32_16x16x32_bf16 v[124:127], v[182:185], v[198:201], v[124:127]
	v_mfma_f32_16x16x32_bf16 v[116:119], v[190:193], v[198:201], v[116:119]
	v_mfma_f32_16x16x32_bf16 v[108:111], v[182:185], v[216:219], v[108:111]
	v_mfma_f32_16x16x32_bf16 v[100:103], v[190:193], v[216:219], v[100:103]
	v_mfma_f32_16x16x32_bf16 v[92:95], v[182:185], v[224:227], v[92:95]
	v_mfma_f32_16x16x32_bf16 v[84:87], v[190:193], v[224:227], v[84:87]
	v_mfma_f32_16x16x32_bf16 v[76:79], v[182:185], v[232:235], v[76:79]
	v_mfma_f32_16x16x32_bf16 v[68:71], v[190:193], v[232:235], v[68:71]
	s_setprio 0
	s_barrier
; #define PG8_STAGE(bufoff, gbase, voff) do { _Pragma("unroll") for (int _i = 0; _i < 2; ++_i) \
;         __builtin_amdgcn_global_load_lds((const unsigned*)((const char*)(gbase) + (voff)[_i]), (PG8_LAS unsigned*)(lds + (bufoff) + ldsw + _i * 8192), 16, 0, 0); } while (0)
; #define PG8_LDA(dst, b, h) do { _Pragma("unroll") for (int m = 0; m < 4; ++m) _Pragma("unroll") for (int k = 0; k < 2; ++k) dst[m][k] = *(const PG8_LAS bf16x8*)(lds + PG8_SA(b, h) + aoff + m * 2048 + k * 1024); } while (0)
; #define PG8_LDB(dst, b, h) do { _Pragma("unroll") for (int n = 0; n < 2; ++n) _Pragma("unroll") for (int k = 0; k < 2; ++k) dst[n][k] = *(const PG8_LAS bf16x8*)(lds + PG8_SB(b, h) + boff + n * 2048 + k * 1024); } while (0)
; #define PG8_MMA(ai, bj, At, Bt) do { __builtin_amdgcn_s_setprio(1); _Pragma("unroll") for (int m = 0; m < 4; ++m) _Pragma("unroll") for (int n = 0; n < 2; ++n) _Pragma("unroll") for (int k = 0; k < 2; ++k) \
;         acc[ai][bj][m][n] = __builtin_amdgcn_mfma_f32_16x16x32_bf16(Bt[n][k], At[m][k], acc[ai][bj][m][n], 0, 0, 0); __builtin_amdgcn_s_setprio(0); } while (0)
; #define PG8_WAIT_V(n) asm volatile("s_waitcnt vmcnt(" #n ")" ::: "memory")
; #define PG8_WAIT_L(n) asm volatile("s_waitcnt lgkmcnt(" #n ")" ::: "memory")
; #define PG8_BAR __builtin_amdgcn_s_barrier()
; #define PG8_SCHED __builtin_amdgcn_sched_barrier(0)
; template <class Epi, class Sched, bool ALIGN_EPI = false, bool SP2 = false>
; __device__ __forceinline__ void gemm_phase(PG8_LAS unsigned char* lds, const Gemm g, const Sched& S, const Epi& E, int wave_s) {
;     ...
;             PG8_LDA(At, 0, 1); PG8_STAGE(PG8_SB(0, 0), b2, voffB); PG8_STAGE(PG8_SB(0, 1), b2 + hstepB, voffB); PG8_STAGE(PG8_SA(0, 0), a2, voffA);
;             PG8_WAIT_V(8); PG8_WAIT_L(0); PG8_BAR; PG8_MMA(1, 0, At, B0); PG8_MMA(1, 1, At, B1); PG8_BAR; PG8_SCHED;
;             PG8_LDB(B0, 1, 0); PG8_LDB(B1, 1, 1); PG8_SCHED; PG8_LDA(At, 1, 0); PG8_STAGE(PG8_SA(0, 1), a2 + hstepA, voffA);
;             PG8_WAIT_V(8); PG8_WAIT_L(0); PG8_BAR; PG8_MMA(0, 0, At, B0); PG8_MMA(0, 1, At, B1); PG8_BAR; PG8_SCHED;
	s_add_i32 s56, s56, s42
	s_add_u32 s98, s26, s60
	s_addc_u32 s99, s27, s61
	s_mov_b32 m0, s56
	ds_read_b128 v[194:197], v145 offset:16384
	ds_read_b128 v[198:201], v145 offset:17408
	ds_read_b128 v[212:215], v145 offset:18432
	ds_read_b128 v[216:219], v145 offset:19456
	ds_read_b128 v[220:223], v145 offset:20480
	ds_read_b128 v[224:227], v145 offset:21504
	ds_read_b128 v[228:231], v145 offset:22528
	ds_read_b128 v[232:235], v145 offset:23552
	global_load_lds_dwordx4 v2, s[26:27]
	s_add_i32 m0, s56, 0x2000
	s_add_u32 s56, s26, 0x80000
	s_addc_u32 s57, s27, 0
	s_add_i32 s58, s58, s42
	global_load_lds_dwordx4 v0, s[26:27]
	s_mov_b32 m0, s58
	s_add_u32 s100, s38, s60
	s_addc_u32 s101, s39, s61
	s_nop 0
	global_load_lds_dwordx4 v2, s[56:57]
	s_add_i32 m0, s58, 0x2000
	s_nop 0
	global_load_lds_dwordx4 v0, s[56:57]
	s_mov_b32 m0, s43
	s_nop 0
	global_load_lds_dwordx4 v134, s[38:39]
	s_mov_b32 m0, s44
	s_nop 0
	global_load_lds_dwordx4 v132, s[38:39]
	s_waitcnt vmcnt(8)
	s_waitcnt lgkmcnt(0)
	s_barrier
	s_setprio 1
	s_waitcnt lgkmcnt(0)
	v_mfma_f32_16x16x32_bf16 v[64:67], v[146:149], v[194:197], v[64:67]
	v_mfma_f32_16x16x32_bf16 v[56:59], v[154:157], v[194:197], v[56:59]
	v_mfma_f32_16x16x32_bf16 v[48:51], v[146:149], v[212:215], v[48:51]
	v_mfma_f32_16x16x32_bf16 v[40:43], v[154:157], v[212:215], v[40:43]
	v_mfma_f32_16x16x32_bf16 v[32:35], v[146:149], v[220:223], v[32:35]
	v_mfma_f32_16x16x32_bf16 v[24:27], v[154:157], v[220:223], v[24:27]
	v_mfma_f32_16x16x32_bf16 v[16:19], v[146:149], v[228:231], v[16:19]
	v_mfma_f32_16x16x32_bf16 v[8:11], v[154:157], v[228:231], v[8:11]
	v_mfma_f32_16x16x32_bf16 v[64:67], v[150:153], v[198:201], v[64:67]
	v_mfma_f32_16x16x32_bf16 v[56:59], v[158:161], v[198:201], v[56:59]
	v_mfma_f32_16x16x32_bf16 v[48:51], v[150:153], v[216:219], v[48:51]
	v_mfma_f32_16x16x32_bf16 v[40:43], v[158:161], v[216:219], v[40:43]
	v_mfma_f32_16x16x32_bf16 v[32:35], v[150:153], v[224:227], v[32:35]
	v_mfma_f32_16x16x32_bf16 v[24:27], v[158:161], v[224:227], v[24:27]
	v_mfma_f32_16x16x32_bf16 v[16:19], v[150:153], v[232:235], v[16:19]
	v_mfma_f32_16x16x32_bf16 v[8:11], v[158:161], v[232:235], v[8:11]
	s_setprio 0
	s_setprio 1
	v_mfma_f32_16x16x32_bf16 v[60:63], v[162:165], v[194:197], v[60:63]
	v_mfma_f32_16x16x32_bf16 v[52:55], v[186:189], v[194:197], v[52:55]
	v_mfma_f32_16x16x32_bf16 v[44:47], v[162:165], v[212:215], v[44:47]
	v_mfma_f32_16x16x32_bf16 v[36:39], v[186:189], v[212:215], v[36:39]
	v_mfma_f32_16x16x32_bf16 v[28:31], v[162:165], v[220:223], v[28:31]
	v_mfma_f32_16x16x32_bf16 v[20:23], v[186:189], v[220:223], v[20:23]
	v_mfma_f32_16x16x32_bf16 v[12:15], v[162:165], v[228:231], v[12:15]
	v_mfma_f32_16x16x32_bf16 v[4:7], v[186:189], v[228:231], v[4:7]
	v_mfma_f32_16x16x32_bf16 v[60:63], v[182:185], v[198:201], v[60:63]
	v_mfma_f32_16x16x32_bf16 v[52:55], v[190:193], v[198:201], v[52:55]
	v_mfma_f32_16x16x32_bf16 v[44:47], v[182:185], v[216:219], v[44:47]
	v_mfma_f32_16x16x32_bf16 v[36:39], v[190:193], v[216:219], v[36:39]
	v_mfma_f32_16x16x32_bf16 v[28:31], v[182:185], v[224:227], v[28:31]
	v_mfma_f32_16x16x32_bf16 v[20:23], v[190:193], v[224:227], v[20:23]
	v_mfma_f32_16x16x32_bf16 v[12:15], v[182:185], v[232:235], v[12:15]
	v_mfma_f32_16x16x32_bf16 v[4:7], v[190:193], v[232:235], v[4:7]
	s_setprio 0
	s_barrier
	s_nop 0
	s_add_i32 s56, 0, 0x18000
	s_add_i32 s57, 0, 0x1c000
	v_add_u32_e32 v158, s56, v143
	v_add_u32_e32 v173, s57, v143
	ds_read_b128 v[146:149], v158
	ds_read_b128 v[150:153], v158 offset:1024
	ds_read_b128 v[154:157], v158 offset:2048
	ds_read_b128 v[158:161], v158 offset:3072
	ds_read_b128 v[162:165], v173
	ds_read_b128 v[182:185], v173 offset:1024
	ds_read_b128 v[186:189], v173 offset:2048
	ds_read_b128 v[190:193], v173 offset:3072
	s_add_u32 s38, s38, 0x80000
	s_addc_u32 s39, s39, 0
	s_mov_b32 m0, s45
	ds_read_b128 v[194:197], v145 offset:32768
	ds_read_b128 v[198:201], v145 offset:33792
	ds_read_b128 v[212:215], v145 offset:34816
	ds_read_b128 v[216:219], v145 offset:35840
	ds_read_b128 v[220:223], v145 offset:36864
	ds_read_b128 v[224:227], v145 offset:37888
	ds_read_b128 v[228:231], v145 offset:38912
	ds_read_b128 v[232:235], v145 offset:39936
	global_load_lds_dwordx4 v134, s[38:39]
	s_mov_b32 m0, s46
	s_nop 0
	global_load_lds_dwordx4 v132, s[38:39]
	s_waitcnt vmcnt(8)
	s_waitcnt lgkmcnt(0)
	s_barrier
; #define PG8_STAGE(bufoff, gbase, voff) do { _Pragma("unroll") for (int _i = 0; _i < 2; ++_i) \
;         __builtin_amdgcn_global_load_lds((const unsigned*)((const char*)(gbase) + (voff)[_i]), (PG8_LAS unsigned*)(lds + (bufoff) + ldsw + _i * 8192), 16, 0, 0); } while (0)
; #define PG8_LDA(dst, b, h) do { _Pragma("unroll") for (int m = 0; m < 4; ++m) _Pragma("unroll") for (int k = 0; k < 2; ++k) dst[m][k] = *(const PG8_LAS bf16x8*)(lds + PG8_SA(b, h) + aoff + m * 2048 + k * 1024); } while (0)
; #define PG8_WAIT_V(n) asm volatile("s_waitcnt vmcnt(" #n ")" ::: "memory")
; #define PG8_WAIT_L(n) asm volatile("s_waitcnt lgkmcnt(" #n ")" ::: "memory")
; #define PG8_BAR __builtin_amdgcn_s_barrier()
; template <class Epi, class Sched, bool ALIGN_EPI = false, bool SP2 = false>
; __device__ __forceinline__ void gemm_phase(PG8_LAS unsigned char* lds, const Gemm g, const Sched& S, const Epi& E, int wave_s) {
;     ...
;         for (int t = 0; t < nt; t += 2) {
;             const bool last = (t == nt - 2);
;             const char* a1 = cA + (size_t)(t + 1) * kstep;
;             const char* a2 = last ? nA : cA + (size_t)(t + 2) * kstep; const char* b2 = last ? nB : cB + (size_t)(t + 2) * kstep;
;             const char* a3 = a2 + kstep; const char* b3 = b2 + kstep;
;             if (last && has_next) S.a_ready(nxt);
;             if constexpr (SP2) {
;             PG8_LDB(B0, 0, 0); PG8_LDB(B1, 0, 1); PG8_SCHED; PG8_LDA(At, 0, 0); PG8_STAGE(PG8_SA(1, 1), a1 + hstepA, voffA);
;             PG8_WAIT_V(8); PG8_WAIT_L(0); PG8_BAR; PG8_MMA(0, 0, At, B0); PG8_MMA(0, 1, At, B1); PG8_BAR; PG8_SCHED;
;             PG8_LDA(At, 0, 1); PG8_STAGE(PG8_SB(0, 0), b2, voffB); PG8_STAGE(PG8_SB(0, 1), b2 + hstepB, voffB); PG8_STAGE(PG8_SA(0, 0), a2, voffA);
;             PG8_WAIT_V(8); PG8_WAIT_L(0); PG8_BAR; PG8_MMA(1, 0, At, B0); PG8_MMA(1, 1, At, B1); PG8_BAR; PG8_SCHED;
;             PG8_LDB(B0, 1, 0); PG8_LDB(B1, 1, 1); PG8_SCHED; PG8_LDA(At, 1, 0); PG8_STAGE(PG8_SA(0, 1), a2 + hstepA, voffA);
;             PG8_WAIT_V(8); PG8_WAIT_L(0); PG8_BAR; PG8_MMA(0, 0, At, B0); PG8_MMA(0, 1, At, B1); PG8_BAR; PG8_SCHED;
;             PG8_LDA(At, 1, 1); PG8_STAGE(PG8_SB(1, 0), b3, voffB); PG8_STAGE(PG8_SB(1, 1), b3 + hstepB, voffB); PG8_STAGE(PG8_SA(1, 0), a3, voffA);
;             PG8_WAIT_V(8); PG8_WAIT_L(0); PG8_BAR; PG8_MMA(1, 0, At, B0); PG8_MMA(1, 1, At, B1); PG8_BAR; PG8_SCHED;
	s_setprio 1
	s_waitcnt lgkmcnt(0)
	v_mfma_f32_16x16x32_bf16 v[128:131], v[146:149], v[194:197], v[128:131]
	v_mfma_f32_16x16x32_bf16 v[120:123], v[154:157], v[194:197], v[120:123]
	v_mfma_f32_16x16x32_bf16 v[112:115], v[146:149], v[212:215], v[112:115]
	v_mfma_f32_16x16x32_bf16 v[104:107], v[154:157], v[212:215], v[104:107]
	v_mfma_f32_16x16x32_bf16 v[96:99], v[146:149], v[220:223], v[96:99]
	v_mfma_f32_16x16x32_bf16 v[88:91], v[154:157], v[220:223], v[88:91]
	v_mfma_f32_16x16x32_bf16 v[80:83], v[146:149], v[228:231], v[80:83]
	v_mfma_f32_16x16x32_bf16 v[72:75], v[154:157], v[228:231], v[72:75]
	v_mfma_f32_16x16x32_bf16 v[128:131], v[150:153], v[198:201], v[128:131]
	v_mfma_f32_16x16x32_bf16 v[120:123], v[158:161], v[198:201], v[120:123]
	v_mfma_f32_16x16x32_bf16 v[112:115], v[150:153], v[216:219], v[112:115]
	v_mfma_f32_16x16x32_bf16 v[104:107], v[158:161], v[216:219], v[104:107]
	v_mfma_f32_16x16x32_bf16 v[96:99], v[150:153], v[224:227], v[96:99]
	v_mfma_f32_16x16x32_bf16 v[88:91], v[158:161], v[224:227], v[88:91]
	v_mfma_f32_16x16x32_bf16 v[80:83], v[150:153], v[232:235], v[80:83]
	v_mfma_f32_16x16x32_bf16 v[72:75], v[158:161], v[232:235], v[72:75]
	s_setprio 0
	s_setprio 1
	v_mfma_f32_16x16x32_bf16 v[124:127], v[162:165], v[194:197], v[124:127]
	v_mfma_f32_16x16x32_bf16 v[116:119], v[186:189], v[194:197], v[116:119]
	v_mfma_f32_16x16x32_bf16 v[108:111], v[162:165], v[212:215], v[108:111]
	v_mfma_f32_16x16x32_bf16 v[100:103], v[186:189], v[212:215], v[100:103]
	v_mfma_f32_16x16x32_bf16 v[92:95], v[162:165], v[220:223], v[92:95]
	v_mfma_f32_16x16x32_bf16 v[84:87], v[186:189], v[220:223], v[84:87]
	v_mfma_f32_16x16x32_bf16 v[76:79], v[162:165], v[228:231], v[76:79]
	v_mfma_f32_16x16x32_bf16 v[68:71], v[186:189], v[228:231], v[68:71]
	v_mfma_f32_16x16x32_bf16 v[124:127], v[182:185], v[198:201], v[124:127]
	v_mfma_f32_16x16x32_bf16 v[116:119], v[190:193], v[198:201], v[116:119]
	v_mfma_f32_16x16x32_bf16 v[108:111], v[182:185], v[216:219], v[108:111]
	v_mfma_f32_16x16x32_bf16 v[100:103], v[190:193], v[216:219], v[100:103]
	v_mfma_f32_16x16x32_bf16 v[92:95], v[182:185], v[224:227], v[92:95]
	v_mfma_f32_16x16x32_bf16 v[84:87], v[190:193], v[224:227], v[84:87]
	v_mfma_f32_16x16x32_bf16 v[76:79], v[182:185], v[232:235], v[76:79]
	v_mfma_f32_16x16x32_bf16 v[68:71], v[190:193], v[232:235], v[68:71]
	s_setprio 0
	s_barrier
	s_add_i32 s38, s56, s42
	s_mov_b32 m0, s38
	ds_read_b128 v[194:197], v145 offset:49152
	ds_read_b128 v[198:201], v145 offset:50176
	ds_read_b128 v[212:215], v145 offset:51200
	ds_read_b128 v[216:219], v145 offset:52224
	ds_read_b128 v[220:223], v145 offset:53248
	ds_read_b128 v[224:227], v145 offset:54272
	ds_read_b128 v[228:231], v145 offset:55296
	ds_read_b128 v[232:235], v145 offset:56320
	global_load_lds_dwordx4 v2, s[98:99]
	s_add_i32 m0, s38, 0x2000
	s_add_u32 s26, s26, 0x80080
	s_addc_u32 s27, s27, 0
	s_add_i32 s38, s57, s42
	global_load_lds_dwordx4 v0, s[98:99]
	s_mov_b32 m0, s38
	s_nop 0
	global_load_lds_dwordx4 v2, s[26:27]
	s_add_i32 m0, s38, 0x2000
	s_nop 0
	global_load_lds_dwordx4 v0, s[26:27]
	s_mov_b32 m0, s47
	s_nop 0
	global_load_lds_dwordx4 v134, s[100:101]
	s_mov_b32 m0, s48
	s_nop 0
	global_load_lds_dwordx4 v132, s[100:101]
	s_waitcnt vmcnt(8)
	s_waitcnt lgkmcnt(0)
	s_barrier
	s_setprio 1
	s_waitcnt lgkmcnt(0)
	v_mfma_f32_16x16x32_bf16 v[64:67], v[146:149], v[194:197], v[64:67]
	v_mfma_f32_16x16x32_bf16 v[56:59], v[154:157], v[194:197], v[56:59]
	v_mfma_f32_16x16x32_bf16 v[48:51], v[146:149], v[212:215], v[48:51]
	v_mfma_f32_16x16x32_bf16 v[40:43], v[154:157], v[212:215], v[40:43]
	v_mfma_f32_16x16x32_bf16 v[32:35], v[146:149], v[220:223], v[32:35]
	v_mfma_f32_16x16x32_bf16 v[24:27], v[154:157], v[220:223], v[24:27]
	v_mfma_f32_16x16x32_bf16 v[16:19], v[146:149], v[228:231], v[16:19]
	v_mfma_f32_16x16x32_bf16 v[8:11], v[154:157], v[228:231], v[8:11]
	v_mfma_f32_16x16x32_bf16 v[64:67], v[150:153], v[198:201], v[64:67]
	v_mfma_f32_16x16x32_bf16 v[56:59], v[158:161], v[198:201], v[56:59]
	v_mfma_f32_16x16x32_bf16 v[48:51], v[150:153], v[216:219], v[48:51]
	v_mfma_f32_16x16x32_bf16 v[40:43], v[158:161], v[216:219], v[40:43]
	v_mfma_f32_16x16x32_bf16 v[32:35], v[150:153], v[224:227], v[32:35]
	v_mfma_f32_16x16x32_bf16 v[24:27], v[158:161], v[224:227], v[24:27]
	v_mfma_f32_16x16x32_bf16 v[16:19], v[150:153], v[232:235], v[16:19]
	v_mfma_f32_16x16x32_bf16 v[8:11], v[158:161], v[232:235], v[8:11]
	s_setprio 0
	s_setprio 1
	v_mfma_f32_16x16x32_bf16 v[60:63], v[162:165], v[194:197], v[60:63]
	v_mfma_f32_16x16x32_bf16 v[52:55], v[186:189], v[194:197], v[52:55]
	v_mfma_f32_16x16x32_bf16 v[44:47], v[162:165], v[212:215], v[44:47]
	v_mfma_f32_16x16x32_bf16 v[36:39], v[186:189], v[212:215], v[36:39]
	v_mfma_f32_16x16x32_bf16 v[28:31], v[162:165], v[220:223], v[28:31]
	v_mfma_f32_16x16x32_bf16 v[20:23], v[186:189], v[220:223], v[20:23]
	v_mfma_f32_16x16x32_bf16 v[12:15], v[162:165], v[228:231], v[12:15]
	v_mfma_f32_16x16x32_bf16 v[4:7], v[186:189], v[228:231], v[4:7]
	v_mfma_f32_16x16x32_bf16 v[60:63], v[182:185], v[198:201], v[60:63]
	v_mfma_f32_16x16x32_bf16 v[52:55], v[190:193], v[198:201], v[52:55]
	v_mfma_f32_16x16x32_bf16 v[44:47], v[182:185], v[216:219], v[44:47]
	v_mfma_f32_16x16x32_bf16 v[36:39], v[190:193], v[216:219], v[36:39]
	v_mfma_f32_16x16x32_bf16 v[28:31], v[182:185], v[224:227], v[28:31]
	v_mfma_f32_16x16x32_bf16 v[20:23], v[190:193], v[224:227], v[20:23]
	v_mfma_f32_16x16x32_bf16 v[12:15], v[182:185], v[232:235], v[12:15]
	v_mfma_f32_16x16x32_bf16 v[4:7], v[190:193], v[232:235], v[4:7]
	s_setprio 0
	s_barrier
	s_add_i32 s55, s55, 2
	s_add_u32 s53, s53, 0x100
	s_addc_u32 s54, s54, 0
	s_add_u32 s18, s18, 0x100
	s_addc_u32 s19, s19, 0
	s_cmp_gt_u32 s55, 29
	s_cbranch_scc0 .LBB0_790
	s_and_b64 vcc, exec, s[6:7]
	s_cbranch_vccz .LBB0_793
	s_barrier

; #define PG8_STAGE(bufoff, gbase, voff) do { _Pragma("unroll") for (int _i = 0; _i < 2; ++_i) \
;         __builtin_amdgcn_global_load_lds((const unsigned*)((const char*)(gbase) + (voff)[_i]), (PG8_LAS unsigned*)(lds + (bufoff) + ldsw + _i * 8192), 16, 0, 0); } while (0)
; #define PG8_LDA(dst, b, h) do { _Pragma("unroll") for (int m = 0; m < 4; ++m) _Pragma("unroll") for (int k = 0; k < 2; ++k) dst[m][k] = *(const PG8_LAS bf16x8*)(lds + PG8_SA(b, h) + aoff + m * 2048 + k * 1024); } while (0)
; #define PG8_LDB(dst, b, h) do { _Pragma("unroll") for (int n = 0; n < 2; ++n) _Pragma("unroll") for (int k = 0; k < 2; ++k) dst[n][k] = *(const PG8_LAS bf16x8*)(lds + PG8_SB(b, h) + boff + n * 2048 + k * 1024); } while (0)
; #define PG8_WAIT_V(n) asm volatile("s_waitcnt vmcnt(" #n ")" ::: "memory")
; #define PG8_WAIT_L(n) asm volatile("s_waitcnt lgkmcnt(" #n ")" ::: "memory")
; #define PG8_BAR __builtin_amdgcn_s_barrier()
; #define PG8_SCHED __builtin_amdgcn_sched_barrier(0)
; template <class Epi, class Sched, bool ALIGN_EPI = false, bool SP2 = false>
; __device__ __forceinline__ void gemm_phase(PG8_LAS unsigned char* lds, const Gemm g, const Sched& S, const Epi& E, int wave_s) {
;     ...
;         const bool has_next = S.next(ui + 1, nxt);
;         const char* nA = has_next ? (const char*)g.A + (size_t)nxt.pm * tstepA : cA; const char* nB = has_next ? (const char*)g.Bt + (size_t)nxt.pn * tstepB : cB;
;         for (int t = 0; t < nt; t += 2) {
;             const bool last = (t == nt - 2);
;             const char* a1 = cA + (size_t)(t + 1) * kstep;
;             const char* a2 = last ? nA : cA + (size_t)(t + 2) * kstep; const char* b2 = last ? nB : cB + (size_t)(t + 2) * kstep;
;             const char* a3 = a2 + kstep; const char* b3 = b2 + kstep;
;             if (last && has_next) S.a_ready(nxt);
;             if constexpr (SP2) {
;             PG8_LDB(B0, 0, 0); PG8_LDB(B1, 0, 1); PG8_SCHED; PG8_LDA(At, 0, 0); PG8_STAGE(PG8_SA(1, 1), a1 + hstepA, voffA);
;             PG8_WAIT_V(8); PG8_WAIT_L(0); PG8_BAR; PG8_MMA(0, 0, At, B0); PG8_MMA(0, 1, At, B1); PG8_BAR; PG8_SCHED;
;     ...
;         for (int a = 0; a < 2; ++a)
; #pragma unroll
;             for (int b = 0; b < 2; ++b)
; #pragma unroll
;                 for (int m = 0; m < 4; ++m)
; #pragma unroll
;                     for (int n = 0; n < 2; ++n) acc[a][b][m][n] = (f32x4){0.f, 0.f, 0.f, 0.f};
.LBB0_862:
	s_add_u32 s36, s22, 0x100
	s_addc_u32 s37, s23, 0
	s_mov_b32 s53, -2
	s_waitcnt vmcnt(0) lgkmcnt(0)
	v_mov_b64_e32 v[4:5], 0
	v_mov_b64_e32 v[6:7], 0
	v_mov_b64_e32 v[8:9], 0
	v_mov_b64_e32 v[10:11], 0
	v_mov_b64_e32 v[12:13], 0
	v_mov_b64_e32 v[14:15], 0
	v_mov_b64_e32 v[16:17], 0
	v_mov_b64_e32 v[18:19], 0
	v_mov_b64_e32 v[20:21], 0
	v_mov_b64_e32 v[22:23], 0
	v_mov_b64_e32 v[24:25], 0
	v_mov_b64_e32 v[26:27], 0
	v_mov_b64_e32 v[28:29], 0
	v_mov_b64_e32 v[30:31], 0
	v_mov_b64_e32 v[32:33], 0
	v_mov_b64_e32 v[34:35], 0
	v_mov_b64_e32 v[36:37], 0
	v_mov_b64_e32 v[38:39], 0
	v_mov_b64_e32 v[40:41], 0
	v_mov_b64_e32 v[42:43], 0
	v_mov_b64_e32 v[44:45], 0
	v_mov_b64_e32 v[46:47], 0
	v_mov_b64_e32 v[48:49], 0
	v_mov_b64_e32 v[50:51], 0
	v_mov_b64_e32 v[52:53], 0
	v_mov_b64_e32 v[54:55], 0
	v_mov_b64_e32 v[56:57], 0
	v_mov_b64_e32 v[58:59], 0
	v_mov_b64_e32 v[60:61], 0
	v_mov_b64_e32 v[62:63], 0
	v_mov_b64_e32 v[64:65], 0
	v_mov_b64_e32 v[66:67], 0
	v_mov_b64_e32 v[68:69], 0
	v_mov_b64_e32 v[70:71], 0
	v_mov_b64_e32 v[72:73], 0
	v_mov_b64_e32 v[74:75], 0
	v_mov_b64_e32 v[76:77], 0
	v_mov_b64_e32 v[78:79], 0
	v_mov_b64_e32 v[80:81], 0
	v_mov_b64_e32 v[82:83], 0
	v_mov_b64_e32 v[84:85], 0
	v_mov_b64_e32 v[86:87], 0
	v_mov_b64_e32 v[88:89], 0
	v_mov_b64_e32 v[90:91], 0
	v_mov_b64_e32 v[92:93], 0
	v_mov_b64_e32 v[94:95], 0
	v_mov_b64_e32 v[96:97], 0
	v_mov_b64_e32 v[98:99], 0
	v_mov_b64_e32 v[100:101], 0
	v_mov_b64_e32 v[102:103], 0
	v_mov_b64_e32 v[104:105], 0
	v_mov_b64_e32 v[106:107], 0
	v_mov_b64_e32 v[108:109], 0
	v_mov_b64_e32 v[110:111], 0
	v_mov_b64_e32 v[112:113], 0
	v_mov_b64_e32 v[114:115], 0
	v_mov_b64_e32 v[116:117], 0
	v_mov_b64_e32 v[118:119], 0
	v_mov_b64_e32 v[120:121], 0
	v_mov_b64_e32 v[122:123], 0
	v_mov_b64_e32 v[124:125], 0
	v_mov_b64_e32 v[126:127], 0
	v_mov_b64_e32 v[128:129], 0
	v_mov_b64_e32 v[130:131], 0
.LBB0_863:
	s_add_u32 s22, s20, 0x100
	s_addc_u32 s23, s21, 0
	s_add_i32 s54, 0, 0x10000
	s_cmpk_eq_i32 s53, 0x54
	s_cselect_b32 s27, s17, s23
	s_cselect_b32 s26, s16, s22
	s_cselect_b32 s25, s19, s37
	s_cselect_b32 s24, s18, s36
	s_add_i32 s55, 0, 0x14000
	v_add_u32_e32 v144, s54, v184
	v_add_u32_e32 v182, s55, v184
	ds_read_b128 v[132:135], v144
	ds_read_b128 v[136:139], v144 offset:1024
	ds_read_b128 v[140:143], v144 offset:2048
	ds_read_b128 v[144:147], v144 offset:3072
	ds_read_b128 v[148:151], v182
	ds_read_b128 v[160:163], v182 offset:1024
	ds_read_b128 v[164:167], v182 offset:2048
	ds_read_b128 v[188:191], v182 offset:3072
	v_lshl_add_u64 v[182:183], s[20:21], 0, v[158:159]
	s_add_i32 m0, s41, 0xc000
	ds_read_b128 v[192:195], v186
	ds_read_b128 v[196:199], v186 offset:1024
	ds_read_b128 v[212:215], v186 offset:2048
	ds_read_b128 v[216:219], v186 offset:3072
	ds_read_b128 v[220:223], v186 offset:4096
	ds_read_b128 v[224:227], v186 offset:5120
	ds_read_b128 v[228:231], v186 offset:6144
	ds_read_b128 v[232:235], v186 offset:7168
	global_load_lds_dwordx4 v[182:183], off
	v_lshl_add_u64 v[182:183], s[20:21], 0, v[156:157]
	s_add_i32 m0, s41, 0xe000
	s_nop 0
	global_load_lds_dwordx4 v[182:183], off
	s_waitcnt vmcnt(8)
	s_waitcnt lgkmcnt(0)
	s_barrier
	s_setprio 1
	s_waitcnt lgkmcnt(0)
	v_mfma_f32_16x16x32_bf16 v[128:131], v[132:135], v[192:195], v[128:131]
	v_mfma_f32_16x16x32_bf16 v[124:127], v[140:143], v[192:195], v[124:127]
	v_mfma_f32_16x16x32_bf16 v[120:123], v[132:135], v[212:215], v[120:123]
	v_mfma_f32_16x16x32_bf16 v[116:119], v[140:143], v[212:215], v[116:119]
	v_mfma_f32_16x16x32_bf16 v[96:99], v[132:135], v[220:223], v[96:99]
	v_mfma_f32_16x16x32_bf16 v[92:95], v[140:143], v[220:223], v[92:95]
	v_mfma_f32_16x16x32_bf16 v[80:83], v[132:135], v[228:231], v[80:83]
	v_mfma_f32_16x16x32_bf16 v[76:79], v[140:143], v[228:231], v[76:79]
	v_mfma_f32_16x16x32_bf16 v[128:131], v[136:139], v[196:199], v[128:131]
	v_mfma_f32_16x16x32_bf16 v[124:127], v[144:147], v[196:199], v[124:127]
	v_mfma_f32_16x16x32_bf16 v[120:123], v[136:139], v[216:219], v[120:123]
	v_mfma_f32_16x16x32_bf16 v[116:119], v[144:147], v[216:219], v[116:119]
	v_mfma_f32_16x16x32_bf16 v[96:99], v[136:139], v[224:227], v[96:99]
	v_mfma_f32_16x16x32_bf16 v[92:95], v[144:147], v[224:227], v[92:95]
	v_mfma_f32_16x16x32_bf16 v[80:83], v[136:139], v[232:235], v[80:83]
	v_mfma_f32_16x16x32_bf16 v[76:79], v[144:147], v[232:235], v[76:79]
	s_setprio 0
	s_setprio 1
	v_mfma_f32_16x16x32_bf16 v[112:115], v[148:151], v[192:195], v[112:115]
	v_mfma_f32_16x16x32_bf16 v[108:111], v[164:167], v[192:195], v[108:111]
	v_mfma_f32_16x16x32_bf16 v[104:107], v[148:151], v[212:215], v[104:107]
	v_mfma_f32_16x16x32_bf16 v[100:103], v[164:167], v[212:215], v[100:103]
	v_mfma_f32_16x16x32_bf16 v[88:91], v[148:151], v[220:223], v[88:91]
	v_mfma_f32_16x16x32_bf16 v[84:87], v[164:167], v[220:223], v[84:87]
	v_mfma_f32_16x16x32_bf16 v[72:75], v[148:151], v[228:231], v[72:75]
	v_mfma_f32_16x16x32_bf16 v[68:71], v[164:167], v[228:231], v[68:71]
	v_mfma_f32_16x16x32_bf16 v[112:115], v[160:163], v[196:199], v[112:115]
	v_mfma_f32_16x16x32_bf16 v[108:111], v[188:191], v[196:199], v[108:111]
	v_mfma_f32_16x16x32_bf16 v[104:107], v[160:163], v[216:219], v[104:107]
	v_mfma_f32_16x16x32_bf16 v[100:103], v[188:191], v[216:219], v[100:103]
	v_mfma_f32_16x16x32_bf16 v[88:91], v[160:163], v[224:227], v[88:91]
	v_mfma_f32_16x16x32_bf16 v[84:87], v[188:191], v[224:227], v[84:87]
	v_mfma_f32_16x16x32_bf16 v[72:75], v[160:163], v[232:235], v[72:75]
	v_mfma_f32_16x16x32_bf16 v[68:71], v[188:191], v[232:235], v[68:71]
	s_setprio 0
	s_barrier
; #define PG8_STAGE(bufoff, gbase, voff) do { _Pragma("unroll") for (int _i = 0; _i < 2; ++_i) \
;         __builtin_amdgcn_global_load_lds((const unsigned*)((const char*)(gbase) + (voff)[_i]), (PG8_LAS unsigned*)(lds + (bufoff) + ldsw + _i * 8192), 16, 0, 0); } while (0)
; #define PG8_LDA(dst, b, h) do { _Pragma("unroll") for (int m = 0; m < 4; ++m) _Pragma("unroll") for (int k = 0; k < 2; ++k) dst[m][k] = *(const PG8_LAS bf16x8*)(lds + PG8_SA(b, h) + aoff + m * 2048 + k * 1024); } while (0)
; #define PG8_LDB(dst, b, h) do { _Pragma("unroll") for (int n = 0; n < 2; ++n) _Pragma("unroll") for (int k = 0; k < 2; ++k) dst[n][k] = *(const PG8_LAS bf16x8*)(lds + PG8_SB(b, h) + boff + n * 2048 + k * 1024); } while (0)
; #define PG8_MMA(ai, bj, At, Bt) do { __builtin_amdgcn_s_setprio(1); _Pragma("unroll") for (int m = 0; m < 4; ++m) _Pragma("unroll") for (int n = 0; n < 2; ++n) _Pragma("unroll") for (int k = 0; k < 2; ++k) \
;         acc[ai][bj][m][n] = __builtin_amdgcn_mfma_f32_16x16x32_bf16(Bt[n][k], At[m][k], acc[ai][bj][m][n], 0, 0, 0); __builtin_amdgcn_s_setprio(0); } while (0)
; #define PG8_WAIT_V(n) asm volatile("s_waitcnt vmcnt(" #n ")" ::: "memory")
; #define PG8_WAIT_L(n) asm volatile("s_waitcnt lgkmcnt(" #n ")" ::: "memory")
; #define PG8_BAR __builtin_amdgcn_s_barrier()
; #define PG8_SCHED __builtin_amdgcn_sched_barrier(0)
; template <class Epi, class Sched, bool ALIGN_EPI = false, bool SP2 = false>
; __device__ __forceinline__ void gemm_phase(PG8_LAS unsigned char* lds, const Gemm g, const Sched& S, const Epi& E, int wave_s) {
;     ...
;             PG8_LDA(At, 0, 1); PG8_STAGE(PG8_SB(0, 0), b2, voffB); PG8_STAGE(PG8_SB(0, 1), b2 + hstepB, voffB); PG8_STAGE(PG8_SA(0, 0), a2, voffA);
;             PG8_WAIT_V(8); PG8_WAIT_L(0); PG8_BAR; PG8_MMA(1, 0, At, B0); PG8_MMA(1, 1, At, B1); PG8_BAR; PG8_SCHED;
;             PG8_LDB(B0, 1, 0); PG8_LDB(B1, 1, 1); PG8_SCHED; PG8_LDA(At, 1, 0); PG8_STAGE(PG8_SA(0, 1), a2 + hstepA, voffA);
;             PG8_WAIT_V(8); PG8_WAIT_L(0); PG8_BAR; PG8_MMA(0, 0, At, B0); PG8_MMA(0, 1, At, B1); PG8_BAR; PG8_SCHED;
	s_add_i32 s20, s54, s40
	s_add_u32 s98, s24, s60
	s_addc_u32 s99, s25, s61
	s_mov_b32 m0, s20
	ds_read_b128 v[192:195], v186 offset:16384
	ds_read_b128 v[196:199], v186 offset:17408
	ds_read_b128 v[212:215], v186 offset:18432
	ds_read_b128 v[216:219], v186 offset:19456
	ds_read_b128 v[220:223], v186 offset:20480
	ds_read_b128 v[224:227], v186 offset:21504
	ds_read_b128 v[228:231], v186 offset:22528
	ds_read_b128 v[232:235], v186 offset:23552
	global_load_lds_dwordx4 v2, s[24:25]
	s_add_i32 m0, s20, 0x2000
	s_add_u32 s20, s24, 0x160000
	s_addc_u32 s21, s25, 0
	s_add_i32 s54, s55, s40
	global_load_lds_dwordx4 v0, s[24:25]
	s_mov_b32 m0, s54
	s_add_u32 s100, s26, s60
	s_addc_u32 s101, s27, s61
	s_nop 0
	global_load_lds_dwordx4 v2, s[20:21]
	s_add_i32 m0, s54, 0x2000
	s_nop 0
	global_load_lds_dwordx4 v0, s[20:21]
	s_mov_b32 m0, s41
	s_nop 0
	global_load_lds_dwordx4 v154, s[26:27]
	s_mov_b32 m0, s42
	s_nop 0
	global_load_lds_dwordx4 v152, s[26:27]
	s_waitcnt vmcnt(8)
	s_waitcnt lgkmcnt(0)
	s_barrier
	s_setprio 1
	s_waitcnt lgkmcnt(0)
	v_mfma_f32_16x16x32_bf16 v[64:67], v[132:135], v[192:195], v[64:67]
	v_mfma_f32_16x16x32_bf16 v[60:63], v[140:143], v[192:195], v[60:63]
	v_mfma_f32_16x16x32_bf16 v[48:51], v[132:135], v[212:215], v[48:51]
	v_mfma_f32_16x16x32_bf16 v[44:47], v[140:143], v[212:215], v[44:47]
	v_mfma_f32_16x16x32_bf16 v[32:35], v[132:135], v[220:223], v[32:35]
	v_mfma_f32_16x16x32_bf16 v[28:31], v[140:143], v[220:223], v[28:31]
	v_mfma_f32_16x16x32_bf16 v[16:19], v[132:135], v[228:231], v[16:19]
	v_mfma_f32_16x16x32_bf16 v[12:15], v[140:143], v[228:231], v[12:15]
	v_mfma_f32_16x16x32_bf16 v[64:67], v[136:139], v[196:199], v[64:67]
	v_mfma_f32_16x16x32_bf16 v[60:63], v[144:147], v[196:199], v[60:63]
	v_mfma_f32_16x16x32_bf16 v[48:51], v[136:139], v[216:219], v[48:51]
	v_mfma_f32_16x16x32_bf16 v[44:47], v[144:147], v[216:219], v[44:47]
	v_mfma_f32_16x16x32_bf16 v[32:35], v[136:139], v[224:227], v[32:35]
	v_mfma_f32_16x16x32_bf16 v[28:31], v[144:147], v[224:227], v[28:31]
	v_mfma_f32_16x16x32_bf16 v[16:19], v[136:139], v[232:235], v[16:19]
	v_mfma_f32_16x16x32_bf16 v[12:15], v[144:147], v[232:235], v[12:15]
	s_setprio 0
	s_setprio 1
	v_mfma_f32_16x16x32_bf16 v[56:59], v[148:151], v[192:195], v[56:59]
	v_mfma_f32_16x16x32_bf16 v[52:55], v[164:167], v[192:195], v[52:55]
	v_mfma_f32_16x16x32_bf16 v[40:43], v[148:151], v[212:215], v[40:43]
	v_mfma_f32_16x16x32_bf16 v[36:39], v[164:167], v[212:215], v[36:39]
	v_mfma_f32_16x16x32_bf16 v[24:27], v[148:151], v[220:223], v[24:27]
	v_mfma_f32_16x16x32_bf16 v[20:23], v[164:167], v[220:223], v[20:23]
	v_mfma_f32_16x16x32_bf16 v[8:11], v[148:151], v[228:231], v[8:11]
	v_mfma_f32_16x16x32_bf16 v[4:7], v[164:167], v[228:231], v[4:7]
	v_mfma_f32_16x16x32_bf16 v[56:59], v[160:163], v[196:199], v[56:59]
	v_mfma_f32_16x16x32_bf16 v[52:55], v[188:191], v[196:199], v[52:55]
	v_mfma_f32_16x16x32_bf16 v[40:43], v[160:163], v[216:219], v[40:43]
	v_mfma_f32_16x16x32_bf16 v[36:39], v[188:191], v[216:219], v[36:39]
	v_mfma_f32_16x16x32_bf16 v[24:27], v[160:163], v[224:227], v[24:27]
	v_mfma_f32_16x16x32_bf16 v[20:23], v[188:191], v[224:227], v[20:23]
	v_mfma_f32_16x16x32_bf16 v[8:11], v[160:163], v[232:235], v[8:11]
	v_mfma_f32_16x16x32_bf16 v[4:7], v[188:191], v[232:235], v[4:7]
	s_setprio 0
	s_barrier
	s_nop 0
	s_add_i32 s54, 0, 0x18000
	s_add_i32 s55, 0, 0x1c000
	v_add_u32_e32 v144, s54, v184
	v_add_u32_e32 v187, s55, v184
	ds_read_b128 v[132:135], v144
	ds_read_b128 v[136:139], v144 offset:1024
	ds_read_b128 v[140:143], v144 offset:2048
	ds_read_b128 v[144:147], v144 offset:3072
	ds_read_b128 v[148:151], v187
	ds_read_b128 v[160:163], v187 offset:1024
	ds_read_b128 v[164:167], v187 offset:2048
	ds_read_b128 v[188:191], v187 offset:3072
	s_add_u32 s20, s26, 0x160000
	s_addc_u32 s21, s27, 0
	s_mov_b32 m0, s43
	ds_read_b128 v[192:195], v186 offset:32768
	ds_read_b128 v[196:199], v186 offset:33792
	ds_read_b128 v[212:215], v186 offset:34816
	ds_read_b128 v[216:219], v186 offset:35840
	ds_read_b128 v[220:223], v186 offset:36864
	ds_read_b128 v[224:227], v186 offset:37888
	ds_read_b128 v[228:231], v186 offset:38912
	ds_read_b128 v[232:235], v186 offset:39936
	global_load_lds_dwordx4 v154, s[20:21]
	s_mov_b32 m0, s44
	s_nop 0
	global_load_lds_dwordx4 v152, s[20:21]
	s_waitcnt vmcnt(8)
	s_waitcnt lgkmcnt(0)
	s_barrier
; #define PG8_STAGE(bufoff, gbase, voff) do { _Pragma("unroll") for (int _i = 0; _i < 2; ++_i) \
;         __builtin_amdgcn_global_load_lds((const unsigned*)((const char*)(gbase) + (voff)[_i]), (PG8_LAS unsigned*)(lds + (bufoff) + ldsw + _i * 8192), 16, 0, 0); } while (0)
; #define PG8_LDA(dst, b, h) do { _Pragma("unroll") for (int m = 0; m < 4; ++m) _Pragma("unroll") for (int k = 0; k < 2; ++k) dst[m][k] = *(const PG8_LAS bf16x8*)(lds + PG8_SA(b, h) + aoff + m * 2048 + k * 1024); } while (0)
; #define PG8_WAIT_V(n) asm volatile("s_waitcnt vmcnt(" #n ")" ::: "memory")
; #define PG8_WAIT_L(n) asm volatile("s_waitcnt lgkmcnt(" #n ")" ::: "memory")
; #define PG8_BAR __builtin_amdgcn_s_barrier()
; template <class Epi, class Sched, bool ALIGN_EPI = false, bool SP2 = false>
; __device__ __forceinline__ void gemm_phase(PG8_LAS unsigned char* lds, const Gemm g, const Sched& S, const Epi& E, int wave_s) {
;     ...
;         for (int t = 0; t < nt; t += 2) {
;             const bool last = (t == nt - 2);
;             const char* a1 = cA + (size_t)(t + 1) * kstep;
;             const char* a2 = last ? nA : cA + (size_t)(t + 2) * kstep; const char* b2 = last ? nB : cB + (size_t)(t + 2) * kstep;
;             const char* a3 = a2 + kstep; const char* b3 = b2 + kstep;
;             if (last && has_next) S.a_ready(nxt);
;             if constexpr (SP2) {
;             PG8_LDB(B0, 0, 0); PG8_LDB(B1, 0, 1); PG8_SCHED; PG8_LDA(At, 0, 0); PG8_STAGE(PG8_SA(1, 1), a1 + hstepA, voffA);
;             PG8_WAIT_V(8); PG8_WAIT_L(0); PG8_BAR; PG8_MMA(0, 0, At, B0); PG8_MMA(0, 1, At, B1); PG8_BAR; PG8_SCHED;
;             PG8_LDA(At, 0, 1); PG8_STAGE(PG8_SB(0, 0), b2, voffB); PG8_STAGE(PG8_SB(0, 1), b2 + hstepB, voffB); PG8_STAGE(PG8_SA(0, 0), a2, voffA);
;             PG8_WAIT_V(8); PG8_WAIT_L(0); PG8_BAR; PG8_MMA(1, 0, At, B0); PG8_MMA(1, 1, At, B1); PG8_BAR; PG8_SCHED;
;             PG8_LDB(B0, 1, 0); PG8_LDB(B1, 1, 1); PG8_SCHED; PG8_LDA(At, 1, 0); PG8_STAGE(PG8_SA(0, 1), a2 + hstepA, voffA);
;             PG8_WAIT_V(8); PG8_WAIT_L(0); PG8_BAR; PG8_MMA(0, 0, At, B0); PG8_MMA(0, 1, At, B1); PG8_BAR; PG8_SCHED;
;             PG8_LDA(At, 1, 1); PG8_STAGE(PG8_SB(1, 0), b3, voffB); PG8_STAGE(PG8_SB(1, 1), b3 + hstepB, voffB); PG8_STAGE(PG8_SA(1, 0), a3, voffA);
;             PG8_WAIT_V(8); PG8_WAIT_L(0); PG8_BAR; PG8_MMA(1, 0, At, B0); PG8_MMA(1, 1, At, B1); PG8_BAR; PG8_SCHED;
	s_setprio 1
	s_waitcnt lgkmcnt(0)
	v_mfma_f32_16x16x32_bf16 v[128:131], v[132:135], v[192:195], v[128:131]
	v_mfma_f32_16x16x32_bf16 v[124:127], v[140:143], v[192:195], v[124:127]
	v_mfma_f32_16x16x32_bf16 v[120:123], v[132:135], v[212:215], v[120:123]
	v_mfma_f32_16x16x32_bf16 v[116:119], v[140:143], v[212:215], v[116:119]
	v_mfma_f32_16x16x32_bf16 v[96:99], v[132:135], v[220:223], v[96:99]
	v_mfma_f32_16x16x32_bf16 v[92:95], v[140:143], v[220:223], v[92:95]
	v_mfma_f32_16x16x32_bf16 v[80:83], v[132:135], v[228:231], v[80:83]
	v_mfma_f32_16x16x32_bf16 v[76:79], v[140:143], v[228:231], v[76:79]
	v_mfma_f32_16x16x32_bf16 v[128:131], v[136:139], v[196:199], v[128:131]
	v_mfma_f32_16x16x32_bf16 v[124:127], v[144:147], v[196:199], v[124:127]
	v_mfma_f32_16x16x32_bf16 v[120:123], v[136:139], v[216:219], v[120:123]
	v_mfma_f32_16x16x32_bf16 v[116:119], v[144:147], v[216:219], v[116:119]
	v_mfma_f32_16x16x32_bf16 v[96:99], v[136:139], v[224:227], v[96:99]
	v_mfma_f32_16x16x32_bf16 v[92:95], v[144:147], v[224:227], v[92:95]
	v_mfma_f32_16x16x32_bf16 v[80:83], v[136:139], v[232:235], v[80:83]
	v_mfma_f32_16x16x32_bf16 v[76:79], v[144:147], v[232:235], v[76:79]
	s_setprio 0
	s_setprio 1
	v_mfma_f32_16x16x32_bf16 v[112:115], v[148:151], v[192:195], v[112:115]
	v_mfma_f32_16x16x32_bf16 v[108:111], v[164:167], v[192:195], v[108:111]
	v_mfma_f32_16x16x32_bf16 v[104:107], v[148:151], v[212:215], v[104:107]
	v_mfma_f32_16x16x32_bf16 v[100:103], v[164:167], v[212:215], v[100:103]
	v_mfma_f32_16x16x32_bf16 v[88:91], v[148:151], v[220:223], v[88:91]
	v_mfma_f32_16x16x32_bf16 v[84:87], v[164:167], v[220:223], v[84:87]
	v_mfma_f32_16x16x32_bf16 v[72:75], v[148:151], v[228:231], v[72:75]
	v_mfma_f32_16x16x32_bf16 v[68:71], v[164:167], v[228:231], v[68:71]
	v_mfma_f32_16x16x32_bf16 v[112:115], v[160:163], v[196:199], v[112:115]
	v_mfma_f32_16x16x32_bf16 v[108:111], v[188:191], v[196:199], v[108:111]
	v_mfma_f32_16x16x32_bf16 v[104:107], v[160:163], v[216:219], v[104:107]
	v_mfma_f32_16x16x32_bf16 v[100:103], v[188:191], v[216:219], v[100:103]
	v_mfma_f32_16x16x32_bf16 v[88:91], v[160:163], v[224:227], v[88:91]
	v_mfma_f32_16x16x32_bf16 v[84:87], v[188:191], v[224:227], v[84:87]
	v_mfma_f32_16x16x32_bf16 v[72:75], v[160:163], v[232:235], v[72:75]
	v_mfma_f32_16x16x32_bf16 v[68:71], v[188:191], v[232:235], v[68:71]
	s_setprio 0
	s_barrier
	s_add_i32 s20, s54, s40
	s_mov_b32 m0, s20
	ds_read_b128 v[192:195], v186 offset:49152
	ds_read_b128 v[196:199], v186 offset:50176
	ds_read_b128 v[212:215], v186 offset:51200
	ds_read_b128 v[216:219], v186 offset:52224
	ds_read_b128 v[220:223], v186 offset:53248
	ds_read_b128 v[224:227], v186 offset:54272
	ds_read_b128 v[228:231], v186 offset:55296
	ds_read_b128 v[232:235], v186 offset:56320
	global_load_lds_dwordx4 v2, s[98:99]
	s_add_i32 m0, s20, 0x2000
	s_add_u32 s20, s24, 0x160080
	s_addc_u32 s21, s25, 0
	s_add_i32 s24, s55, s40
	global_load_lds_dwordx4 v0, s[98:99]
	s_mov_b32 m0, s24
	s_nop 0
	global_load_lds_dwordx4 v2, s[20:21]
	s_add_i32 m0, s24, 0x2000
	s_nop 0
	global_load_lds_dwordx4 v0, s[20:21]
	s_mov_b32 m0, s47
	s_nop 0
	global_load_lds_dwordx4 v154, s[100:101]
	s_mov_b32 m0, s48
	s_nop 0
	global_load_lds_dwordx4 v152, s[100:101]
	s_waitcnt vmcnt(8)
	s_waitcnt lgkmcnt(0)
	s_barrier
	s_setprio 1
	s_waitcnt lgkmcnt(0)
	v_mfma_f32_16x16x32_bf16 v[64:67], v[132:135], v[192:195], v[64:67]
	v_mfma_f32_16x16x32_bf16 v[60:63], v[140:143], v[192:195], v[60:63]
	v_mfma_f32_16x16x32_bf16 v[48:51], v[132:135], v[212:215], v[48:51]
	v_mfma_f32_16x16x32_bf16 v[44:47], v[140:143], v[212:215], v[44:47]
	v_mfma_f32_16x16x32_bf16 v[32:35], v[132:135], v[220:223], v[32:35]
	v_mfma_f32_16x16x32_bf16 v[28:31], v[140:143], v[220:223], v[28:31]
	v_mfma_f32_16x16x32_bf16 v[16:19], v[132:135], v[228:231], v[16:19]
	v_mfma_f32_16x16x32_bf16 v[12:15], v[140:143], v[228:231], v[12:15]
	v_mfma_f32_16x16x32_bf16 v[64:67], v[136:139], v[196:199], v[64:67]
	v_mfma_f32_16x16x32_bf16 v[60:63], v[144:147], v[196:199], v[60:63]
	v_mfma_f32_16x16x32_bf16 v[48:51], v[136:139], v[216:219], v[48:51]
	v_mfma_f32_16x16x32_bf16 v[44:47], v[144:147], v[216:219], v[44:47]
	v_mfma_f32_16x16x32_bf16 v[32:35], v[136:139], v[224:227], v[32:35]
	v_mfma_f32_16x16x32_bf16 v[28:31], v[144:147], v[224:227], v[28:31]
	v_mfma_f32_16x16x32_bf16 v[16:19], v[136:139], v[232:235], v[16:19]
	v_mfma_f32_16x16x32_bf16 v[12:15], v[144:147], v[232:235], v[12:15]
	s_setprio 0
	s_setprio 1
	v_mfma_f32_16x16x32_bf16 v[56:59], v[148:151], v[192:195], v[56:59]
	v_mfma_f32_16x16x32_bf16 v[52:55], v[164:167], v[192:195], v[52:55]
	v_mfma_f32_16x16x32_bf16 v[40:43], v[148:151], v[212:215], v[40:43]
	v_mfma_f32_16x16x32_bf16 v[36:39], v[164:167], v[212:215], v[36:39]
	v_mfma_f32_16x16x32_bf16 v[24:27], v[148:151], v[220:223], v[24:27]
	v_mfma_f32_16x16x32_bf16 v[20:23], v[164:167], v[220:223], v[20:23]
	v_mfma_f32_16x16x32_bf16 v[8:11], v[148:151], v[228:231], v[8:11]
	v_mfma_f32_16x16x32_bf16 v[4:7], v[164:167], v[228:231], v[4:7]
	v_mfma_f32_16x16x32_bf16 v[56:59], v[160:163], v[196:199], v[56:59]
	v_mfma_f32_16x16x32_bf16 v[52:55], v[188:191], v[196:199], v[52:55]
	v_mfma_f32_16x16x32_bf16 v[40:43], v[160:163], v[216:219], v[40:43]
	v_mfma_f32_16x16x32_bf16 v[36:39], v[188:191], v[216:219], v[36:39]
	v_mfma_f32_16x16x32_bf16 v[24:27], v[160:163], v[224:227], v[24:27]
	v_mfma_f32_16x16x32_bf16 v[20:23], v[188:191], v[224:227], v[20:23]
	v_mfma_f32_16x16x32_bf16 v[8:11], v[160:163], v[232:235], v[8:11]
	v_mfma_f32_16x16x32_bf16 v[4:7], v[188:191], v[232:235], v[4:7]
	s_setprio 0
	s_barrier
	s_add_i32 s53, s53, 2
	s_add_u32 s36, s36, 0x100
	s_addc_u32 s37, s37, 0
	s_cmpk_gt_u32 s53, 0x55
	s_mov_b64 s[20:21], s[22:23]
	s_cbranch_scc0 .LBB0_863
	s_and_b64 vcc, exec, s[6:7]
	s_cbranch_vccz .LBB0_866
	s_barrier
